# GEMM K-loops: back-edge rotation (7.11) - loop counter / pointer SALU moved in front of the iteration's last barrier in 12 of 18 loops
# speedup vs baseline: 1.0044x; 1.0002x over previous
.LBB0_236:
	ds_read_b128 v[152:155], v149
	ds_read_b128 v[156:159], v149 offset:1024
	ds_read_b128 v[160:163], v149 offset:2048
	ds_read_b128 v[164:167], v149 offset:3072
	ds_read_b128 v[168:171], v150
	ds_read_b128 v[172:175], v150 offset:1024
	ds_read_b128 v[176:179], v150 offset:2048
	ds_read_b128 v[180:183], v150 offset:3072
	s_add_u32 s26, s24, 0xfffc0080
	s_addc_u32 s27, s25, -1
	s_cmp_eq_u32 s53, 12
	s_cselect_b32 s29, s17, s27
	s_cselect_b32 s28, s49, s26
	s_cselect_b32 s27, s15, s52
	s_cselect_b32 s26, s50, s51
	v_lshl_add_u64 v[144:145], s[24:25], 0, v[138:139]
	s_add_i32 m0, s36, 0xc000
	ds_read_b128 v[184:187], v151
	ds_read_b128 v[188:191], v151 offset:1024
	ds_read_b128 v[192:195], v151 offset:2048
	ds_read_b128 v[196:199], v151 offset:3072
	ds_read_b128 v[200:203], v151 offset:4096
	ds_read_b128 v[204:207], v151 offset:5120
	ds_read_b128 v[208:211], v151 offset:6144
	ds_read_b128 v[212:215], v151 offset:7168
	global_load_lds_dwordx4 v[144:145], off
	v_lshl_add_u64 v[144:145], s[24:25], 0, v[136:137]
	s_add_i32 m0, s36, 0xe000
	s_nop 0
	global_load_lds_dwordx4 v[144:145], off
	s_waitcnt vmcnt(8)
	s_waitcnt lgkmcnt(0)
	s_barrier
	s_setprio 1
	s_waitcnt lgkmcnt(0)
	v_mfma_f32_16x16x32_bf16 v[124:127], v[152:155], v[184:187], v[124:127]
	v_mfma_f32_16x16x32_bf16 v[120:123], v[160:163], v[184:187], v[120:123]
	v_mfma_f32_16x16x32_bf16 v[116:119], v[152:155], v[192:195], v[116:119]
	v_mfma_f32_16x16x32_bf16 v[112:115], v[160:163], v[192:195], v[112:115]
	v_mfma_f32_16x16x32_bf16 v[108:111], v[152:155], v[200:203], v[108:111]
	v_mfma_f32_16x16x32_bf16 v[104:107], v[160:163], v[200:203], v[104:107]
	v_mfma_f32_16x16x32_bf16 v[100:103], v[152:155], v[208:211], v[100:103]
	v_mfma_f32_16x16x32_bf16 v[96:99], v[160:163], v[208:211], v[96:99]
	v_mfma_f32_16x16x32_bf16 v[124:127], v[156:159], v[188:191], v[124:127]
	v_mfma_f32_16x16x32_bf16 v[120:123], v[164:167], v[188:191], v[120:123]
	v_mfma_f32_16x16x32_bf16 v[116:119], v[156:159], v[196:199], v[116:119]
	v_mfma_f32_16x16x32_bf16 v[112:115], v[164:167], v[196:199], v[112:115]
	v_mfma_f32_16x16x32_bf16 v[108:111], v[156:159], v[204:207], v[108:111]
	v_mfma_f32_16x16x32_bf16 v[104:107], v[164:167], v[204:207], v[104:107]
	v_mfma_f32_16x16x32_bf16 v[100:103], v[156:159], v[212:215], v[100:103]
	v_mfma_f32_16x16x32_bf16 v[96:99], v[164:167], v[212:215], v[96:99]
	s_setprio 0
	s_setprio 1
	v_mfma_f32_16x16x32_bf16 v[80:83], v[168:171], v[184:187], v[80:83]
	v_mfma_f32_16x16x32_bf16 v[72:75], v[176:179], v[184:187], v[72:75]
	v_mfma_f32_16x16x32_bf16 v[60:63], v[168:171], v[192:195], v[60:63]
	v_mfma_f32_16x16x32_bf16 v[56:59], v[176:179], v[192:195], v[56:59]
	v_mfma_f32_16x16x32_bf16 v[44:47], v[168:171], v[200:203], v[44:47]
	v_mfma_f32_16x16x32_bf16 v[40:43], v[176:179], v[200:203], v[40:43]
	v_mfma_f32_16x16x32_bf16 v[36:39], v[168:171], v[208:211], v[36:39]
	v_mfma_f32_16x16x32_bf16 v[32:35], v[176:179], v[208:211], v[32:35]
	v_mfma_f32_16x16x32_bf16 v[80:83], v[172:175], v[188:191], v[80:83]
	v_mfma_f32_16x16x32_bf16 v[72:75], v[180:183], v[188:191], v[72:75]
	v_mfma_f32_16x16x32_bf16 v[60:63], v[172:175], v[196:199], v[60:63]
	v_mfma_f32_16x16x32_bf16 v[56:59], v[180:183], v[196:199], v[56:59]
	v_mfma_f32_16x16x32_bf16 v[44:47], v[172:175], v[204:207], v[44:47]
	v_mfma_f32_16x16x32_bf16 v[40:43], v[180:183], v[204:207], v[40:43]
	v_mfma_f32_16x16x32_bf16 v[36:39], v[172:175], v[212:215], v[36:39]
	v_mfma_f32_16x16x32_bf16 v[32:35], v[180:183], v[212:215], v[32:35]
	s_setprio 0
	s_barrier
	s_add_i32 s54, s45, s31
	v_lshl_add_u64 v[144:145], s[26:27], 0, v[132:133]
	s_mov_b32 m0, s54
	ds_read_b128 v[184:187], v151 offset:16384
	ds_read_b128 v[188:191], v151 offset:17408
	ds_read_b128 v[192:195], v151 offset:18432
	ds_read_b128 v[196:199], v151 offset:19456
	ds_read_b128 v[200:203], v151 offset:20480
	ds_read_b128 v[204:207], v151 offset:21504
	ds_read_b128 v[208:211], v151 offset:22528
	ds_read_b128 v[212:215], v151 offset:23552
	global_load_lds_dwordx4 v[144:145], off
	s_add_i32 m0, s54, 0x2000
	s_add_u32 s54, s26, 0x40000
	v_lshl_add_u64 v[216:217], s[26:27], 0, v[128:129]
	s_addc_u32 s55, s27, 0
	s_add_i32 s56, s46, s31
	global_load_lds_dwordx4 v[216:217], off
	v_lshl_add_u64 v[218:219], s[54:55], 0, v[132:133]
	s_mov_b32 m0, s56
	v_lshl_add_u64 v[220:221], s[28:29], 0, v[130:131]
	global_load_lds_dwordx4 v[218:219], off
	v_lshl_add_u64 v[218:219], s[54:55], 0, v[128:129]
	s_add_i32 m0, s56, 0x2000
	s_nop 0
	global_load_lds_dwordx4 v[218:219], off
	v_lshl_add_u64 v[218:219], s[28:29], 0, v[134:135]
	s_mov_b32 m0, s36
	s_nop 0
	global_load_lds_dwordx4 v[218:219], off
	s_mov_b32 m0, s37
	s_nop 0
	global_load_lds_dwordx4 v[220:221], off
	s_waitcnt vmcnt(8)
	s_waitcnt lgkmcnt(0)
	s_barrier
	s_setprio 1
	s_waitcnt lgkmcnt(0)
	v_mfma_f32_16x16x32_bf16 v[92:95], v[152:155], v[184:187], v[92:95]
	v_mfma_f32_16x16x32_bf16 v[88:91], v[160:163], v[184:187], v[88:91]
	v_mfma_f32_16x16x32_bf16 v[84:87], v[152:155], v[192:195], v[84:87]
	v_mfma_f32_16x16x32_bf16 v[76:79], v[160:163], v[192:195], v[76:79]
	v_mfma_f32_16x16x32_bf16 v[68:71], v[152:155], v[200:203], v[68:71]
	v_mfma_f32_16x16x32_bf16 v[64:67], v[160:163], v[200:203], v[64:67]
	v_mfma_f32_16x16x32_bf16 v[52:55], v[152:155], v[208:211], v[52:55]
	v_mfma_f32_16x16x32_bf16 v[48:51], v[160:163], v[208:211], v[48:51]
	v_mfma_f32_16x16x32_bf16 v[92:95], v[156:159], v[188:191], v[92:95]
	v_mfma_f32_16x16x32_bf16 v[88:91], v[164:167], v[188:191], v[88:91]
	v_mfma_f32_16x16x32_bf16 v[84:87], v[156:159], v[196:199], v[84:87]
	v_mfma_f32_16x16x32_bf16 v[76:79], v[164:167], v[196:199], v[76:79]
	v_mfma_f32_16x16x32_bf16 v[68:71], v[156:159], v[204:207], v[68:71]
	v_mfma_f32_16x16x32_bf16 v[64:67], v[164:167], v[204:207], v[64:67]
	v_mfma_f32_16x16x32_bf16 v[52:55], v[156:159], v[212:215], v[52:55]
	v_mfma_f32_16x16x32_bf16 v[48:51], v[164:167], v[212:215], v[48:51]
	s_setprio 0
	s_setprio 1
	v_mfma_f32_16x16x32_bf16 v[28:31], v[168:171], v[184:187], v[28:31]
	v_mfma_f32_16x16x32_bf16 v[24:27], v[176:179], v[184:187], v[24:27]
	v_mfma_f32_16x16x32_bf16 v[20:23], v[168:171], v[192:195], v[20:23]
	v_mfma_f32_16x16x32_bf16 v[16:19], v[176:179], v[192:195], v[16:19]
	v_mfma_f32_16x16x32_bf16 v[12:15], v[168:171], v[200:203], v[12:15]
	v_mfma_f32_16x16x32_bf16 v[8:11], v[176:179], v[200:203], v[8:11]
	v_mfma_f32_16x16x32_bf16 v[4:7], v[168:171], v[208:211], v[4:7]
	v_mfma_f32_16x16x32_bf16 v[0:3], v[176:179], v[208:211], v[0:3]
	v_mfma_f32_16x16x32_bf16 v[28:31], v[172:175], v[188:191], v[28:31]
	v_mfma_f32_16x16x32_bf16 v[24:27], v[180:183], v[188:191], v[24:27]
	v_mfma_f32_16x16x32_bf16 v[20:23], v[172:175], v[196:199], v[20:23]
	v_mfma_f32_16x16x32_bf16 v[16:19], v[180:183], v[196:199], v[16:19]
	v_mfma_f32_16x16x32_bf16 v[12:15], v[172:175], v[204:207], v[12:15]
	v_mfma_f32_16x16x32_bf16 v[8:11], v[180:183], v[204:207], v[8:11]
	v_mfma_f32_16x16x32_bf16 v[4:7], v[172:175], v[212:215], v[4:7]
	v_mfma_f32_16x16x32_bf16 v[0:3], v[180:183], v[212:215], v[0:3]
	s_setprio 0
	s_barrier
	s_add_i32 s54, 0, 0x18000
	s_add_i32 s55, 0, 0x1c000
	v_add_u32_e32 v164, s54, v147
	v_add_u32_e32 v180, s55, v147
	ds_read_b128 v[152:155], v164
	ds_read_b128 v[156:159], v164 offset:1024
	ds_read_b128 v[160:163], v164 offset:2048
	ds_read_b128 v[164:167], v164 offset:3072
	ds_read_b128 v[168:171], v180
	ds_read_b128 v[172:175], v180 offset:1024
	ds_read_b128 v[176:179], v180 offset:2048
	ds_read_b128 v[180:183], v180 offset:3072
	s_add_u32 s28, s28, 0x40000
	s_addc_u32 s29, s29, 0
	s_mov_b32 m0, s38
	v_lshl_add_u64 v[222:223], s[28:29], 0, v[134:135]
	ds_read_b128 v[184:187], v151 offset:32768
	ds_read_b128 v[188:191], v151 offset:33792
	ds_read_b128 v[192:195], v151 offset:34816
	ds_read_b128 v[196:199], v151 offset:35840
	ds_read_b128 v[200:203], v151 offset:36864
	ds_read_b128 v[204:207], v151 offset:37888
	ds_read_b128 v[208:211], v151 offset:38912
	ds_read_b128 v[212:215], v151 offset:39936
	global_load_lds_dwordx4 v[222:223], off
	v_lshl_add_u64 v[222:223], s[28:29], 0, v[130:131]
	s_mov_b32 m0, s39
	s_nop 0
	global_load_lds_dwordx4 v[222:223], off
	s_waitcnt vmcnt(8)
	s_waitcnt lgkmcnt(0)
	s_barrier
	s_setprio 1
	s_waitcnt lgkmcnt(0)
	v_mfma_f32_16x16x32_bf16 v[124:127], v[152:155], v[184:187], v[124:127]
	v_mfma_f32_16x16x32_bf16 v[120:123], v[160:163], v[184:187], v[120:123]
	v_mfma_f32_16x16x32_bf16 v[116:119], v[152:155], v[192:195], v[116:119]
	v_mfma_f32_16x16x32_bf16 v[112:115], v[160:163], v[192:195], v[112:115]
	v_mfma_f32_16x16x32_bf16 v[108:111], v[152:155], v[200:203], v[108:111]
	v_mfma_f32_16x16x32_bf16 v[104:107], v[160:163], v[200:203], v[104:107]
	v_mfma_f32_16x16x32_bf16 v[100:103], v[152:155], v[208:211], v[100:103]
	v_mfma_f32_16x16x32_bf16 v[96:99], v[160:163], v[208:211], v[96:99]
	v_mfma_f32_16x16x32_bf16 v[124:127], v[156:159], v[188:191], v[124:127]
	v_mfma_f32_16x16x32_bf16 v[120:123], v[164:167], v[188:191], v[120:123]
	v_mfma_f32_16x16x32_bf16 v[116:119], v[156:159], v[196:199], v[116:119]
	v_mfma_f32_16x16x32_bf16 v[112:115], v[164:167], v[196:199], v[112:115]
	v_mfma_f32_16x16x32_bf16 v[108:111], v[156:159], v[204:207], v[108:111]
	v_mfma_f32_16x16x32_bf16 v[104:107], v[164:167], v[204:207], v[104:107]
	v_mfma_f32_16x16x32_bf16 v[100:103], v[156:159], v[212:215], v[100:103]
	v_mfma_f32_16x16x32_bf16 v[96:99], v[164:167], v[212:215], v[96:99]
	s_setprio 0
	s_setprio 1
	v_mfma_f32_16x16x32_bf16 v[80:83], v[168:171], v[184:187], v[80:83]
	v_mfma_f32_16x16x32_bf16 v[72:75], v[176:179], v[184:187], v[72:75]
	v_mfma_f32_16x16x32_bf16 v[60:63], v[168:171], v[192:195], v[60:63]
	v_mfma_f32_16x16x32_bf16 v[56:59], v[176:179], v[192:195], v[56:59]
	v_mfma_f32_16x16x32_bf16 v[44:47], v[168:171], v[200:203], v[44:47]
	v_mfma_f32_16x16x32_bf16 v[40:43], v[176:179], v[200:203], v[40:43]
	v_mfma_f32_16x16x32_bf16 v[36:39], v[168:171], v[208:211], v[36:39]
	v_mfma_f32_16x16x32_bf16 v[32:35], v[176:179], v[208:211], v[32:35]
	v_mfma_f32_16x16x32_bf16 v[80:83], v[172:175], v[188:191], v[80:83]
	v_mfma_f32_16x16x32_bf16 v[72:75], v[180:183], v[188:191], v[72:75]
	v_mfma_f32_16x16x32_bf16 v[60:63], v[172:175], v[196:199], v[60:63]
	v_mfma_f32_16x16x32_bf16 v[56:59], v[180:183], v[196:199], v[56:59]
	v_mfma_f32_16x16x32_bf16 v[44:47], v[172:175], v[204:207], v[44:47]
	v_mfma_f32_16x16x32_bf16 v[40:43], v[180:183], v[204:207], v[40:43]
	v_mfma_f32_16x16x32_bf16 v[36:39], v[172:175], v[212:215], v[36:39]
	v_mfma_f32_16x16x32_bf16 v[32:35], v[180:183], v[212:215], v[32:35]
	s_setprio 0
	s_barrier
	s_add_i32 s28, s54, s31
	v_lshl_add_u64 v[144:145], v[144:145], 0, s[10:11]
	s_mov_b32 m0, s28
	ds_read_b128 v[184:187], v151 offset:49152
	ds_read_b128 v[188:191], v151 offset:50176
	ds_read_b128 v[192:195], v151 offset:51200
	ds_read_b128 v[196:199], v151 offset:52224
	ds_read_b128 v[200:203], v151 offset:53248
	ds_read_b128 v[204:207], v151 offset:54272
	ds_read_b128 v[208:211], v151 offset:55296
	ds_read_b128 v[212:215], v151 offset:56320
	global_load_lds_dwordx4 v[144:145], off
	s_add_i32 m0, s28, 0x2000
	s_add_u32 s26, s26, 0x40080
	v_lshl_add_u64 v[144:145], v[216:217], 0, s[10:11]
	s_addc_u32 s27, s27, 0
	s_add_i32 s28, s55, s31
	global_load_lds_dwordx4 v[144:145], off
	v_lshl_add_u64 v[144:145], s[26:27], 0, v[132:133]
	s_mov_b32 m0, s28
	s_nop 0
	global_load_lds_dwordx4 v[144:145], off
	v_lshl_add_u64 v[144:145], s[26:27], 0, v[128:129]
	s_add_i32 m0, s28, 0x2000
	s_nop 0
	global_load_lds_dwordx4 v[144:145], off
	v_lshl_add_u64 v[144:145], v[218:219], 0, s[10:11]
	s_mov_b32 m0, s41
	s_nop 0
	global_load_lds_dwordx4 v[144:145], off
	v_lshl_add_u64 v[144:145], v[220:221], 0, s[10:11]
	s_mov_b32 m0, s42
	s_nop 0
	global_load_lds_dwordx4 v[144:145], off
	s_waitcnt vmcnt(8)
	s_waitcnt lgkmcnt(0)
	s_barrier
	s_setprio 1
	s_waitcnt lgkmcnt(0)
	v_mfma_f32_16x16x32_bf16 v[92:95], v[152:155], v[184:187], v[92:95]
	v_mfma_f32_16x16x32_bf16 v[88:91], v[160:163], v[184:187], v[88:91]
	v_mfma_f32_16x16x32_bf16 v[84:87], v[152:155], v[192:195], v[84:87]
	v_mfma_f32_16x16x32_bf16 v[76:79], v[160:163], v[192:195], v[76:79]
	v_mfma_f32_16x16x32_bf16 v[68:71], v[152:155], v[200:203], v[68:71]
	v_mfma_f32_16x16x32_bf16 v[64:67], v[160:163], v[200:203], v[64:67]
	v_mfma_f32_16x16x32_bf16 v[52:55], v[152:155], v[208:211], v[52:55]
	v_mfma_f32_16x16x32_bf16 v[48:51], v[160:163], v[208:211], v[48:51]
	v_mfma_f32_16x16x32_bf16 v[92:95], v[156:159], v[188:191], v[92:95]
	v_mfma_f32_16x16x32_bf16 v[88:91], v[164:167], v[188:191], v[88:91]
	v_mfma_f32_16x16x32_bf16 v[84:87], v[156:159], v[196:199], v[84:87]
	v_mfma_f32_16x16x32_bf16 v[76:79], v[164:167], v[196:199], v[76:79]
	v_mfma_f32_16x16x32_bf16 v[68:71], v[156:159], v[204:207], v[68:71]
	v_mfma_f32_16x16x32_bf16 v[64:67], v[164:167], v[204:207], v[64:67]
	v_mfma_f32_16x16x32_bf16 v[52:55], v[156:159], v[212:215], v[52:55]
	v_mfma_f32_16x16x32_bf16 v[48:51], v[164:167], v[212:215], v[48:51]
	s_setprio 0
	s_setprio 1
	v_mfma_f32_16x16x32_bf16 v[28:31], v[168:171], v[184:187], v[28:31]
	v_mfma_f32_16x16x32_bf16 v[24:27], v[176:179], v[184:187], v[24:27]
	v_mfma_f32_16x16x32_bf16 v[20:23], v[168:171], v[192:195], v[20:23]
	v_mfma_f32_16x16x32_bf16 v[16:19], v[176:179], v[192:195], v[16:19]
	v_mfma_f32_16x16x32_bf16 v[12:15], v[168:171], v[200:203], v[12:15]
	v_mfma_f32_16x16x32_bf16 v[8:11], v[176:179], v[200:203], v[8:11]
	v_mfma_f32_16x16x32_bf16 v[4:7], v[168:171], v[208:211], v[4:7]
	v_mfma_f32_16x16x32_bf16 v[0:3], v[176:179], v[208:211], v[0:3]
	v_mfma_f32_16x16x32_bf16 v[28:31], v[172:175], v[188:191], v[28:31]
	v_mfma_f32_16x16x32_bf16 v[24:27], v[180:183], v[188:191], v[24:27]
	v_mfma_f32_16x16x32_bf16 v[20:23], v[172:175], v[196:199], v[20:23]
	v_mfma_f32_16x16x32_bf16 v[16:19], v[180:183], v[196:199], v[16:19]
	v_mfma_f32_16x16x32_bf16 v[12:15], v[172:175], v[204:207], v[12:15]
	v_mfma_f32_16x16x32_bf16 v[8:11], v[180:183], v[204:207], v[8:11]
	v_mfma_f32_16x16x32_bf16 v[4:7], v[172:175], v[212:215], v[4:7]
	v_mfma_f32_16x16x32_bf16 v[0:3], v[180:183], v[212:215], v[0:3]
	s_setprio 0
	s_add_i32 s53, s53, 2
	s_add_u32 s51, s51, 0x100
	s_addc_u32 s52, s52, 0
	s_add_u32 s24, s24, 0x100
	s_addc_u32 s25, s25, 0
	s_cmp_gt_u32 s53, 13
	s_barrier
	s_cbranch_scc0 .LBB0_236
	s_and_b64 vcc, exec, s[12:13]
	s_cbranch_vccz .LBB0_239
	s_barrier

.LBB0_1116:
	ds_read_b128 v[144:147], v157
	ds_read_b128 v[148:151], v157 offset:1024
	ds_read_b128 v[160:163], v157 offset:2048
	ds_read_b128 v[164:167], v157 offset:3072
	ds_read_b128 v[168:171], v158
	ds_read_b128 v[172:175], v158 offset:1024
	ds_read_b128 v[176:179], v158 offset:2048
	ds_read_b128 v[180:183], v158 offset:3072
	s_add_u32 s28, s24, 0xfffc0080
	s_addc_u32 s29, s25, -1
	s_cmp_eq_u32 s54, 12
	s_cselect_b32 s31, s17, s29
	s_cselect_b32 s30, s50, s28
	s_cselect_b32 s29, s15, s53
	s_cselect_b32 s28, s51, s52
	v_lshl_add_u64 v[152:153], s[24:25], 0, v[138:139]
	s_add_i32 m0, s35, 0xc000
	ds_read_b128 v[184:187], v159
	ds_read_b128 v[188:191], v159 offset:1024
	ds_read_b128 v[192:195], v159 offset:2048
	ds_read_b128 v[196:199], v159 offset:3072
	ds_read_b128 v[200:203], v159 offset:4096
	ds_read_b128 v[204:207], v159 offset:5120
	ds_read_b128 v[208:211], v159 offset:6144
	ds_read_b128 v[212:215], v159 offset:7168
	global_load_lds_dwordx4 v[152:153], off
	v_lshl_add_u64 v[152:153], s[24:25], 0, v[136:137]
	s_add_i32 m0, s35, 0xe000
	s_nop 0
	global_load_lds_dwordx4 v[152:153], off
	s_waitcnt vmcnt(8)
	s_waitcnt lgkmcnt(0)
	s_barrier
	s_setprio 1
	s_waitcnt lgkmcnt(0)
	v_mfma_f32_16x16x32_bf16 v[124:127], v[144:147], v[184:187], v[124:127]
	v_mfma_f32_16x16x32_bf16 v[120:123], v[160:163], v[184:187], v[120:123]
	v_mfma_f32_16x16x32_bf16 v[116:119], v[144:147], v[192:195], v[116:119]
	v_mfma_f32_16x16x32_bf16 v[112:115], v[160:163], v[192:195], v[112:115]
	v_mfma_f32_16x16x32_bf16 v[108:111], v[144:147], v[200:203], v[108:111]
	v_mfma_f32_16x16x32_bf16 v[104:107], v[160:163], v[200:203], v[104:107]
	v_mfma_f32_16x16x32_bf16 v[100:103], v[144:147], v[208:211], v[100:103]
	v_mfma_f32_16x16x32_bf16 v[96:99], v[160:163], v[208:211], v[96:99]
	v_mfma_f32_16x16x32_bf16 v[124:127], v[148:151], v[188:191], v[124:127]
	v_mfma_f32_16x16x32_bf16 v[120:123], v[164:167], v[188:191], v[120:123]
	v_mfma_f32_16x16x32_bf16 v[116:119], v[148:151], v[196:199], v[116:119]
	v_mfma_f32_16x16x32_bf16 v[112:115], v[164:167], v[196:199], v[112:115]
	v_mfma_f32_16x16x32_bf16 v[108:111], v[148:151], v[204:207], v[108:111]
	v_mfma_f32_16x16x32_bf16 v[104:107], v[164:167], v[204:207], v[104:107]
	v_mfma_f32_16x16x32_bf16 v[100:103], v[148:151], v[212:215], v[100:103]
	v_mfma_f32_16x16x32_bf16 v[96:99], v[164:167], v[212:215], v[96:99]
	s_setprio 0
	s_setprio 1
	v_mfma_f32_16x16x32_bf16 v[76:79], v[168:171], v[184:187], v[76:79]
	v_mfma_f32_16x16x32_bf16 v[72:75], v[176:179], v[184:187], v[72:75]
	v_mfma_f32_16x16x32_bf16 v[60:63], v[168:171], v[192:195], v[60:63]
	v_mfma_f32_16x16x32_bf16 v[52:55], v[176:179], v[192:195], v[52:55]
	v_mfma_f32_16x16x32_bf16 v[44:47], v[168:171], v[200:203], v[44:47]
	v_mfma_f32_16x16x32_bf16 v[40:43], v[176:179], v[200:203], v[40:43]
	v_mfma_f32_16x16x32_bf16 v[36:39], v[168:171], v[208:211], v[36:39]
	v_mfma_f32_16x16x32_bf16 v[32:35], v[176:179], v[208:211], v[32:35]
	v_mfma_f32_16x16x32_bf16 v[76:79], v[172:175], v[188:191], v[76:79]
	v_mfma_f32_16x16x32_bf16 v[72:75], v[180:183], v[188:191], v[72:75]
	v_mfma_f32_16x16x32_bf16 v[60:63], v[172:175], v[196:199], v[60:63]
	v_mfma_f32_16x16x32_bf16 v[52:55], v[180:183], v[196:199], v[52:55]
	v_mfma_f32_16x16x32_bf16 v[44:47], v[172:175], v[204:207], v[44:47]
	v_mfma_f32_16x16x32_bf16 v[40:43], v[180:183], v[204:207], v[40:43]
	v_mfma_f32_16x16x32_bf16 v[36:39], v[172:175], v[212:215], v[36:39]
	v_mfma_f32_16x16x32_bf16 v[32:35], v[180:183], v[212:215], v[32:35]
	s_setprio 0
	s_barrier
	s_add_i32 s55, s45, s33
	v_lshl_add_u64 v[152:153], s[28:29], 0, v[130:131]
	s_mov_b32 m0, s55
	ds_read_b128 v[184:187], v159 offset:16384
	ds_read_b128 v[188:191], v159 offset:17408
	ds_read_b128 v[192:195], v159 offset:18432
	ds_read_b128 v[196:199], v159 offset:19456
	ds_read_b128 v[200:203], v159 offset:20480
	ds_read_b128 v[204:207], v159 offset:21504
	ds_read_b128 v[208:211], v159 offset:22528
	ds_read_b128 v[212:215], v159 offset:23552
	global_load_lds_dwordx4 v[152:153], off
	s_add_i32 m0, s55, 0x2000
	s_add_u32 s56, s28, 0x40000
	v_lshl_add_u64 v[216:217], s[28:29], 0, v[134:135]
	s_addc_u32 s57, s29, 0
	s_add_i32 s55, s46, s33
	global_load_lds_dwordx4 v[216:217], off
	v_lshl_add_u64 v[218:219], s[56:57], 0, v[130:131]
	s_mov_b32 m0, s55
	v_lshl_add_u64 v[220:221], s[30:31], 0, v[132:133]
	global_load_lds_dwordx4 v[218:219], off
	v_lshl_add_u64 v[218:219], s[56:57], 0, v[134:135]
	s_add_i32 m0, s55, 0x2000
	s_nop 0
	global_load_lds_dwordx4 v[218:219], off
	v_lshl_add_u64 v[218:219], s[30:31], 0, v[128:129]
	s_mov_b32 m0, s35
	s_nop 0
	global_load_lds_dwordx4 v[218:219], off
	s_mov_b32 m0, s36
	s_nop 0
	global_load_lds_dwordx4 v[220:221], off
	s_waitcnt vmcnt(8)
	s_waitcnt lgkmcnt(0)
	s_barrier
	s_setprio 1
	s_waitcnt lgkmcnt(0)
	v_mfma_f32_16x16x32_bf16 v[92:95], v[144:147], v[184:187], v[92:95]
	v_mfma_f32_16x16x32_bf16 v[88:91], v[160:163], v[184:187], v[88:91]
	v_mfma_f32_16x16x32_bf16 v[84:87], v[144:147], v[192:195], v[84:87]
	v_mfma_f32_16x16x32_bf16 v[80:83], v[160:163], v[192:195], v[80:83]
	v_mfma_f32_16x16x32_bf16 v[68:71], v[144:147], v[200:203], v[68:71]
	v_mfma_f32_16x16x32_bf16 v[64:67], v[160:163], v[200:203], v[64:67]
	v_mfma_f32_16x16x32_bf16 v[56:59], v[144:147], v[208:211], v[56:59]
	v_mfma_f32_16x16x32_bf16 v[48:51], v[160:163], v[208:211], v[48:51]
	v_mfma_f32_16x16x32_bf16 v[92:95], v[148:151], v[188:191], v[92:95]
	v_mfma_f32_16x16x32_bf16 v[88:91], v[164:167], v[188:191], v[88:91]
	v_mfma_f32_16x16x32_bf16 v[84:87], v[148:151], v[196:199], v[84:87]
	v_mfma_f32_16x16x32_bf16 v[80:83], v[164:167], v[196:199], v[80:83]
	v_mfma_f32_16x16x32_bf16 v[68:71], v[148:151], v[204:207], v[68:71]
	v_mfma_f32_16x16x32_bf16 v[64:67], v[164:167], v[204:207], v[64:67]
	v_mfma_f32_16x16x32_bf16 v[56:59], v[148:151], v[212:215], v[56:59]
	v_mfma_f32_16x16x32_bf16 v[48:51], v[164:167], v[212:215], v[48:51]
	s_setprio 0
	s_setprio 1
	v_mfma_f32_16x16x32_bf16 v[28:31], v[168:171], v[184:187], v[28:31]
	v_mfma_f32_16x16x32_bf16 v[24:27], v[176:179], v[184:187], v[24:27]
	v_mfma_f32_16x16x32_bf16 v[20:23], v[168:171], v[192:195], v[20:23]
	v_mfma_f32_16x16x32_bf16 v[16:19], v[176:179], v[192:195], v[16:19]
	v_mfma_f32_16x16x32_bf16 v[12:15], v[168:171], v[200:203], v[12:15]
	v_mfma_f32_16x16x32_bf16 v[8:11], v[176:179], v[200:203], v[8:11]
	v_mfma_f32_16x16x32_bf16 v[4:7], v[168:171], v[208:211], v[4:7]
	v_mfma_f32_16x16x32_bf16 v[0:3], v[176:179], v[208:211], v[0:3]
	v_mfma_f32_16x16x32_bf16 v[28:31], v[172:175], v[188:191], v[28:31]
	v_mfma_f32_16x16x32_bf16 v[24:27], v[180:183], v[188:191], v[24:27]
	v_mfma_f32_16x16x32_bf16 v[20:23], v[172:175], v[196:199], v[20:23]
	v_mfma_f32_16x16x32_bf16 v[16:19], v[180:183], v[196:199], v[16:19]
	v_mfma_f32_16x16x32_bf16 v[12:15], v[172:175], v[204:207], v[12:15]
	v_mfma_f32_16x16x32_bf16 v[8:11], v[180:183], v[204:207], v[8:11]
	v_mfma_f32_16x16x32_bf16 v[4:7], v[172:175], v[212:215], v[4:7]
	v_mfma_f32_16x16x32_bf16 v[0:3], v[180:183], v[212:215], v[0:3]
	s_setprio 0
	s_barrier
	s_add_i32 s55, 0, 0x18000
	s_add_i32 s56, 0, 0x1c000
	v_add_u32_e32 v164, s55, v155
	v_add_u32_e32 v180, s56, v155
	ds_read_b128 v[144:147], v164
	ds_read_b128 v[148:151], v164 offset:1024
	ds_read_b128 v[160:163], v164 offset:2048
	ds_read_b128 v[164:167], v164 offset:3072
	ds_read_b128 v[168:171], v180
	ds_read_b128 v[172:175], v180 offset:1024
	ds_read_b128 v[176:179], v180 offset:2048
	ds_read_b128 v[180:183], v180 offset:3072
	s_add_u32 s30, s30, 0x40000
	s_addc_u32 s31, s31, 0
	s_mov_b32 m0, s37
	v_lshl_add_u64 v[222:223], s[30:31], 0, v[128:129]
	ds_read_b128 v[184:187], v159 offset:32768
	ds_read_b128 v[188:191], v159 offset:33792
	ds_read_b128 v[192:195], v159 offset:34816
	ds_read_b128 v[196:199], v159 offset:35840
	ds_read_b128 v[200:203], v159 offset:36864
	ds_read_b128 v[204:207], v159 offset:37888
	ds_read_b128 v[208:211], v159 offset:38912
	ds_read_b128 v[212:215], v159 offset:39936
	global_load_lds_dwordx4 v[222:223], off
	v_lshl_add_u64 v[222:223], s[30:31], 0, v[132:133]
	s_mov_b32 m0, s38
	s_nop 0
	global_load_lds_dwordx4 v[222:223], off
	s_waitcnt vmcnt(8)
	s_waitcnt lgkmcnt(0)
	s_barrier
	s_setprio 1
	s_waitcnt lgkmcnt(0)
	v_mfma_f32_16x16x32_bf16 v[124:127], v[144:147], v[184:187], v[124:127]
	v_mfma_f32_16x16x32_bf16 v[120:123], v[160:163], v[184:187], v[120:123]
	v_mfma_f32_16x16x32_bf16 v[116:119], v[144:147], v[192:195], v[116:119]
	v_mfma_f32_16x16x32_bf16 v[112:115], v[160:163], v[192:195], v[112:115]
	v_mfma_f32_16x16x32_bf16 v[108:111], v[144:147], v[200:203], v[108:111]
	v_mfma_f32_16x16x32_bf16 v[104:107], v[160:163], v[200:203], v[104:107]
	v_mfma_f32_16x16x32_bf16 v[100:103], v[144:147], v[208:211], v[100:103]
	v_mfma_f32_16x16x32_bf16 v[96:99], v[160:163], v[208:211], v[96:99]
	v_mfma_f32_16x16x32_bf16 v[124:127], v[148:151], v[188:191], v[124:127]
	v_mfma_f32_16x16x32_bf16 v[120:123], v[164:167], v[188:191], v[120:123]
	v_mfma_f32_16x16x32_bf16 v[116:119], v[148:151], v[196:199], v[116:119]
	v_mfma_f32_16x16x32_bf16 v[112:115], v[164:167], v[196:199], v[112:115]
	v_mfma_f32_16x16x32_bf16 v[108:111], v[148:151], v[204:207], v[108:111]
	v_mfma_f32_16x16x32_bf16 v[104:107], v[164:167], v[204:207], v[104:107]
	v_mfma_f32_16x16x32_bf16 v[100:103], v[148:151], v[212:215], v[100:103]
	v_mfma_f32_16x16x32_bf16 v[96:99], v[164:167], v[212:215], v[96:99]
	s_setprio 0
	s_setprio 1
	v_mfma_f32_16x16x32_bf16 v[76:79], v[168:171], v[184:187], v[76:79]
	v_mfma_f32_16x16x32_bf16 v[72:75], v[176:179], v[184:187], v[72:75]
	v_mfma_f32_16x16x32_bf16 v[60:63], v[168:171], v[192:195], v[60:63]
	v_mfma_f32_16x16x32_bf16 v[52:55], v[176:179], v[192:195], v[52:55]
	v_mfma_f32_16x16x32_bf16 v[44:47], v[168:171], v[200:203], v[44:47]
	v_mfma_f32_16x16x32_bf16 v[40:43], v[176:179], v[200:203], v[40:43]
	v_mfma_f32_16x16x32_bf16 v[36:39], v[168:171], v[208:211], v[36:39]
	v_mfma_f32_16x16x32_bf16 v[32:35], v[176:179], v[208:211], v[32:35]
	v_mfma_f32_16x16x32_bf16 v[76:79], v[172:175], v[188:191], v[76:79]
	v_mfma_f32_16x16x32_bf16 v[72:75], v[180:183], v[188:191], v[72:75]
	v_mfma_f32_16x16x32_bf16 v[60:63], v[172:175], v[196:199], v[60:63]
	v_mfma_f32_16x16x32_bf16 v[52:55], v[180:183], v[196:199], v[52:55]
	v_mfma_f32_16x16x32_bf16 v[44:47], v[172:175], v[204:207], v[44:47]
	v_mfma_f32_16x16x32_bf16 v[40:43], v[180:183], v[204:207], v[40:43]
	v_mfma_f32_16x16x32_bf16 v[36:39], v[172:175], v[212:215], v[36:39]
	v_mfma_f32_16x16x32_bf16 v[32:35], v[180:183], v[212:215], v[32:35]
	s_setprio 0
	s_barrier
	s_add_i32 s30, s55, s33
	v_lshl_add_u64 v[152:153], v[152:153], 0, s[10:11]
	s_mov_b32 m0, s30
	ds_read_b128 v[184:187], v159 offset:49152
	ds_read_b128 v[188:191], v159 offset:50176
	ds_read_b128 v[192:195], v159 offset:51200
	ds_read_b128 v[196:199], v159 offset:52224
	ds_read_b128 v[200:203], v159 offset:53248
	ds_read_b128 v[204:207], v159 offset:54272
	ds_read_b128 v[208:211], v159 offset:55296
	ds_read_b128 v[212:215], v159 offset:56320
	global_load_lds_dwordx4 v[152:153], off
	s_add_i32 m0, s30, 0x2000
	s_add_u32 s28, s28, 0x40080
	v_lshl_add_u64 v[152:153], v[216:217], 0, s[10:11]
	s_addc_u32 s29, s29, 0
	s_add_i32 s30, s56, s33
	global_load_lds_dwordx4 v[152:153], off
	v_lshl_add_u64 v[152:153], s[28:29], 0, v[130:131]
	s_mov_b32 m0, s30
	s_nop 0
	global_load_lds_dwordx4 v[152:153], off
	v_lshl_add_u64 v[152:153], s[28:29], 0, v[134:135]
	s_add_i32 m0, s30, 0x2000
	s_nop 0
	global_load_lds_dwordx4 v[152:153], off
	v_lshl_add_u64 v[152:153], v[218:219], 0, s[10:11]
	s_mov_b32 m0, s41
	s_nop 0
	global_load_lds_dwordx4 v[152:153], off
	v_lshl_add_u64 v[152:153], v[220:221], 0, s[10:11]
	s_mov_b32 m0, s42
	s_nop 0
	global_load_lds_dwordx4 v[152:153], off
	s_waitcnt vmcnt(8)
	s_waitcnt lgkmcnt(0)
	s_barrier
	s_setprio 1
	s_waitcnt lgkmcnt(0)
	v_mfma_f32_16x16x32_bf16 v[92:95], v[144:147], v[184:187], v[92:95]
	v_mfma_f32_16x16x32_bf16 v[88:91], v[160:163], v[184:187], v[88:91]
	v_mfma_f32_16x16x32_bf16 v[84:87], v[144:147], v[192:195], v[84:87]
	v_mfma_f32_16x16x32_bf16 v[80:83], v[160:163], v[192:195], v[80:83]
	v_mfma_f32_16x16x32_bf16 v[68:71], v[144:147], v[200:203], v[68:71]
	v_mfma_f32_16x16x32_bf16 v[64:67], v[160:163], v[200:203], v[64:67]
	v_mfma_f32_16x16x32_bf16 v[56:59], v[144:147], v[208:211], v[56:59]
	v_mfma_f32_16x16x32_bf16 v[48:51], v[160:163], v[208:211], v[48:51]
	v_mfma_f32_16x16x32_bf16 v[92:95], v[148:151], v[188:191], v[92:95]
	v_mfma_f32_16x16x32_bf16 v[88:91], v[164:167], v[188:191], v[88:91]
	v_mfma_f32_16x16x32_bf16 v[84:87], v[148:151], v[196:199], v[84:87]
	v_mfma_f32_16x16x32_bf16 v[80:83], v[164:167], v[196:199], v[80:83]
	v_mfma_f32_16x16x32_bf16 v[68:71], v[148:151], v[204:207], v[68:71]
	v_mfma_f32_16x16x32_bf16 v[64:67], v[164:167], v[204:207], v[64:67]
	v_mfma_f32_16x16x32_bf16 v[56:59], v[148:151], v[212:215], v[56:59]
	v_mfma_f32_16x16x32_bf16 v[48:51], v[164:167], v[212:215], v[48:51]
	s_setprio 0
	s_setprio 1
	v_mfma_f32_16x16x32_bf16 v[28:31], v[168:171], v[184:187], v[28:31]
	v_mfma_f32_16x16x32_bf16 v[24:27], v[176:179], v[184:187], v[24:27]
	v_mfma_f32_16x16x32_bf16 v[20:23], v[168:171], v[192:195], v[20:23]
	v_mfma_f32_16x16x32_bf16 v[16:19], v[176:179], v[192:195], v[16:19]
	v_mfma_f32_16x16x32_bf16 v[12:15], v[168:171], v[200:203], v[12:15]
	v_mfma_f32_16x16x32_bf16 v[8:11], v[176:179], v[200:203], v[8:11]
	v_mfma_f32_16x16x32_bf16 v[4:7], v[168:171], v[208:211], v[4:7]
	v_mfma_f32_16x16x32_bf16 v[0:3], v[176:179], v[208:211], v[0:3]
	v_mfma_f32_16x16x32_bf16 v[28:31], v[172:175], v[188:191], v[28:31]
	v_mfma_f32_16x16x32_bf16 v[24:27], v[180:183], v[188:191], v[24:27]
	v_mfma_f32_16x16x32_bf16 v[20:23], v[172:175], v[196:199], v[20:23]
	v_mfma_f32_16x16x32_bf16 v[16:19], v[180:183], v[196:199], v[16:19]
	v_mfma_f32_16x16x32_bf16 v[12:15], v[172:175], v[204:207], v[12:15]
	v_mfma_f32_16x16x32_bf16 v[8:11], v[180:183], v[204:207], v[8:11]
	v_mfma_f32_16x16x32_bf16 v[4:7], v[172:175], v[212:215], v[4:7]
	v_mfma_f32_16x16x32_bf16 v[0:3], v[180:183], v[212:215], v[0:3]
	s_setprio 0
	s_add_i32 s54, s54, 2
	s_add_u32 s52, s52, 0x100
	s_addc_u32 s53, s53, 0
	s_add_u32 s24, s24, 0x100
	s_addc_u32 s25, s25, 0
	s_cmp_gt_u32 s54, 13
	s_barrier
	s_cbranch_scc0 .LBB0_1116
	s_and_b64 vcc, exec, s[12:13]
	s_cbranch_vccz .LBB0_1119
	s_barrier

.LBB0_1249:
	ds_read_b128 v[104:107], v238
	ds_read_b128 v[108:111], v238 offset:1024
	ds_read_b128 v[112:115], v238 offset:2048
	ds_read_b128 v[116:119], v238 offset:3072
	ds_read_b128 v[120:123], v239
	ds_read_b128 v[124:127], v239 offset:1024
	ds_read_b128 v[128:131], v239 offset:2048
	ds_read_b128 v[132:135], v239 offset:3072
	s_add_u32 s74, s24, 0xfffc0080
	s_addc_u32 s75, s25, -1
	s_cmp_eq_u32 s80, 12
	s_cselect_b32 s77, s69, s75
	s_cselect_b32 s76, s68, s74
	s_cselect_b32 s75, s67, s79
	s_cselect_b32 s74, s73, s78
	v_lshl_add_u64 v[208:209], s[24:25], 0, v[186:187]
	s_add_i32 m0, s42, 0xc000
	ds_read_b128 v[160:163], v240
	ds_read_b128 v[164:167], v240 offset:1024
	ds_read_b128 v[168:171], v240 offset:2048
	ds_read_b128 v[172:175], v240 offset:3072
	ds_read_b128 v[192:195], v240 offset:4096
	ds_read_b128 v[196:199], v240 offset:5120
	ds_read_b128 v[200:203], v240 offset:6144
	ds_read_b128 v[204:207], v240 offset:7168
	global_load_lds_dwordx4 v[208:209], off
	v_lshl_add_u64 v[208:209], s[24:25], 0, v[184:185]
	s_add_i32 m0, s42, 0xe000
	s_nop 0
	global_load_lds_dwordx4 v[208:209], off
	s_waitcnt vmcnt(8)
	s_waitcnt lgkmcnt(0)
	s_barrier
	s_setprio 1
	s_waitcnt lgkmcnt(0)
	v_mfma_f32_16x16x32_bf16 v[156:159], v[104:107], v[160:163], v[156:159]
	v_mfma_f32_16x16x32_bf16 v[60:63], v[112:115], v[160:163], v[60:63]
	v_mfma_f32_16x16x32_bf16 v[148:151], v[104:107], v[168:171], v[148:151]
	v_mfma_f32_16x16x32_bf16 v[52:55], v[112:115], v[168:171], v[52:55]
	v_mfma_f32_16x16x32_bf16 v[140:143], v[104:107], v[192:195], v[140:143]
	v_mfma_f32_16x16x32_bf16 v[44:47], v[112:115], v[192:195], v[44:47]
	v_mfma_f32_16x16x32_bf16 v[100:103], v[104:107], v[200:203], v[100:103]
	v_mfma_f32_16x16x32_bf16 v[36:39], v[112:115], v[200:203], v[36:39]
	v_mfma_f32_16x16x32_bf16 v[156:159], v[108:111], v[164:167], v[156:159]
	v_mfma_f32_16x16x32_bf16 v[60:63], v[116:119], v[164:167], v[60:63]
	v_mfma_f32_16x16x32_bf16 v[148:151], v[108:111], v[172:175], v[148:151]
	v_mfma_f32_16x16x32_bf16 v[52:55], v[116:119], v[172:175], v[52:55]
	v_mfma_f32_16x16x32_bf16 v[140:143], v[108:111], v[196:199], v[140:143]
	v_mfma_f32_16x16x32_bf16 v[44:47], v[116:119], v[196:199], v[44:47]
	v_mfma_f32_16x16x32_bf16 v[100:103], v[108:111], v[204:207], v[100:103]
	v_mfma_f32_16x16x32_bf16 v[36:39], v[116:119], v[204:207], v[36:39]
	s_setprio 0
	s_setprio 1
	v_mfma_f32_16x16x32_bf16 v[152:155], v[120:123], v[160:163], v[152:155]
	v_mfma_f32_16x16x32_bf16 v[56:59], v[128:131], v[160:163], v[56:59]
	v_mfma_f32_16x16x32_bf16 v[144:147], v[120:123], v[168:171], v[144:147]
	v_mfma_f32_16x16x32_bf16 v[48:51], v[128:131], v[168:171], v[48:51]
	v_mfma_f32_16x16x32_bf16 v[136:139], v[120:123], v[192:195], v[136:139]
	v_mfma_f32_16x16x32_bf16 v[40:43], v[128:131], v[192:195], v[40:43]
	v_mfma_f32_16x16x32_bf16 v[96:99], v[120:123], v[200:203], v[96:99]
	v_mfma_f32_16x16x32_bf16 v[32:35], v[128:131], v[200:203], v[32:35]
	v_mfma_f32_16x16x32_bf16 v[152:155], v[124:127], v[164:167], v[152:155]
	v_mfma_f32_16x16x32_bf16 v[56:59], v[132:135], v[164:167], v[56:59]
	v_mfma_f32_16x16x32_bf16 v[144:147], v[124:127], v[172:175], v[144:147]
	v_mfma_f32_16x16x32_bf16 v[48:51], v[132:135], v[172:175], v[48:51]
	v_mfma_f32_16x16x32_bf16 v[136:139], v[124:127], v[196:199], v[136:139]
	v_mfma_f32_16x16x32_bf16 v[40:43], v[132:135], v[196:199], v[40:43]
	v_mfma_f32_16x16x32_bf16 v[96:99], v[124:127], v[204:207], v[96:99]
	v_mfma_f32_16x16x32_bf16 v[32:35], v[132:135], v[204:207], v[32:35]
	s_setprio 0
	s_barrier
	s_add_i32 s81, s33, s41
	v_lshl_add_u64 v[208:209], s[74:75], 0, v[178:179]
	s_mov_b32 m0, s81
	ds_read_b128 v[160:163], v240 offset:16384
	ds_read_b128 v[164:167], v240 offset:17408
	ds_read_b128 v[168:171], v240 offset:18432
	ds_read_b128 v[172:175], v240 offset:19456
	ds_read_b128 v[192:195], v240 offset:20480
	ds_read_b128 v[196:199], v240 offset:21504
	ds_read_b128 v[200:203], v240 offset:22528
	ds_read_b128 v[204:207], v240 offset:23552
	global_load_lds_dwordx4 v[208:209], off
	s_add_i32 m0, s81, 0x2000
	s_add_u32 s82, s74, 0x40000
	v_lshl_add_u64 v[210:211], s[74:75], 0, v[182:183]
	s_addc_u32 s83, s75, 0
	s_add_i32 s81, s0, s41
	global_load_lds_dwordx4 v[210:211], off
	v_lshl_add_u64 v[212:213], s[82:83], 0, v[178:179]
	s_mov_b32 m0, s81
	v_lshl_add_u64 v[214:215], s[76:77], 0, v[180:181]
	global_load_lds_dwordx4 v[212:213], off
	v_lshl_add_u64 v[212:213], s[82:83], 0, v[182:183]
	s_add_i32 m0, s81, 0x2000
	s_nop 0
	global_load_lds_dwordx4 v[212:213], off
	v_lshl_add_u64 v[212:213], s[76:77], 0, v[176:177]
	s_mov_b32 m0, s42
	s_nop 0
	global_load_lds_dwordx4 v[212:213], off
	s_mov_b32 m0, s43
	s_nop 0
	global_load_lds_dwordx4 v[214:215], off
	s_waitcnt vmcnt(8)
	s_waitcnt lgkmcnt(0)
	s_barrier
	s_setprio 1
	s_waitcnt lgkmcnt(0)
	v_mfma_f32_16x16x32_bf16 v[92:95], v[104:107], v[160:163], v[92:95]
	v_mfma_f32_16x16x32_bf16 v[28:31], v[112:115], v[160:163], v[28:31]
	v_mfma_f32_16x16x32_bf16 v[84:87], v[104:107], v[168:171], v[84:87]
	v_mfma_f32_16x16x32_bf16 v[20:23], v[112:115], v[168:171], v[20:23]
	v_mfma_f32_16x16x32_bf16 v[76:79], v[104:107], v[192:195], v[76:79]
	v_mfma_f32_16x16x32_bf16 v[12:15], v[112:115], v[192:195], v[12:15]
	v_mfma_f32_16x16x32_bf16 v[68:71], v[104:107], v[200:203], v[68:71]
	v_mfma_f32_16x16x32_bf16 v[4:7], v[112:115], v[200:203], v[4:7]
	v_mfma_f32_16x16x32_bf16 v[92:95], v[108:111], v[164:167], v[92:95]
	v_mfma_f32_16x16x32_bf16 v[28:31], v[116:119], v[164:167], v[28:31]
	v_mfma_f32_16x16x32_bf16 v[84:87], v[108:111], v[172:175], v[84:87]
	v_mfma_f32_16x16x32_bf16 v[20:23], v[116:119], v[172:175], v[20:23]
	v_mfma_f32_16x16x32_bf16 v[76:79], v[108:111], v[196:199], v[76:79]
	v_mfma_f32_16x16x32_bf16 v[12:15], v[116:119], v[196:199], v[12:15]
	v_mfma_f32_16x16x32_bf16 v[68:71], v[108:111], v[204:207], v[68:71]
	v_mfma_f32_16x16x32_bf16 v[4:7], v[116:119], v[204:207], v[4:7]
	s_setprio 0
	s_setprio 1
	v_mfma_f32_16x16x32_bf16 v[88:91], v[120:123], v[160:163], v[88:91]
	v_mfma_f32_16x16x32_bf16 v[24:27], v[128:131], v[160:163], v[24:27]
	v_mfma_f32_16x16x32_bf16 v[80:83], v[120:123], v[168:171], v[80:83]
	v_mfma_f32_16x16x32_bf16 v[16:19], v[128:131], v[168:171], v[16:19]
	v_mfma_f32_16x16x32_bf16 v[72:75], v[120:123], v[192:195], v[72:75]
	v_mfma_f32_16x16x32_bf16 v[8:11], v[128:131], v[192:195], v[8:11]
	v_mfma_f32_16x16x32_bf16 v[64:67], v[120:123], v[200:203], v[64:67]
	v_mfma_f32_16x16x32_bf16 v[0:3], v[128:131], v[200:203], v[0:3]
	v_mfma_f32_16x16x32_bf16 v[88:91], v[124:127], v[164:167], v[88:91]
	v_mfma_f32_16x16x32_bf16 v[24:27], v[132:135], v[164:167], v[24:27]
	v_mfma_f32_16x16x32_bf16 v[80:83], v[124:127], v[172:175], v[80:83]
	v_mfma_f32_16x16x32_bf16 v[16:19], v[132:135], v[172:175], v[16:19]
	v_mfma_f32_16x16x32_bf16 v[72:75], v[124:127], v[196:199], v[72:75]
	v_mfma_f32_16x16x32_bf16 v[8:11], v[132:135], v[196:199], v[8:11]
	v_mfma_f32_16x16x32_bf16 v[64:67], v[124:127], v[204:207], v[64:67]
	v_mfma_f32_16x16x32_bf16 v[0:3], v[132:135], v[204:207], v[0:3]
	s_setprio 0
	s_barrier
	s_add_i32 s81, 0, 0x18000
	s_add_i32 s82, 0, 0x1c000
	v_add_u32_e32 v116, s81, v225
	v_add_u32_e32 v132, s82, v225
	ds_read_b128 v[104:107], v116
	ds_read_b128 v[108:111], v116 offset:1024
	ds_read_b128 v[112:115], v116 offset:2048
	ds_read_b128 v[116:119], v116 offset:3072
	ds_read_b128 v[120:123], v132
	ds_read_b128 v[124:127], v132 offset:1024
	ds_read_b128 v[128:131], v132 offset:2048
	ds_read_b128 v[132:135], v132 offset:3072
	s_add_u32 s76, s76, 0x40000
	s_addc_u32 s77, s77, 0
	s_mov_b32 m0, s96
	v_lshl_add_u64 v[216:217], s[76:77], 0, v[176:177]
	ds_read_b128 v[160:163], v240 offset:32768
	ds_read_b128 v[164:167], v240 offset:33792
	ds_read_b128 v[168:171], v240 offset:34816
	ds_read_b128 v[172:175], v240 offset:35840
	ds_read_b128 v[192:195], v240 offset:36864
	ds_read_b128 v[196:199], v240 offset:37888
	ds_read_b128 v[200:203], v240 offset:38912
	ds_read_b128 v[204:207], v240 offset:39936
	global_load_lds_dwordx4 v[216:217], off
	v_lshl_add_u64 v[216:217], s[76:77], 0, v[180:181]
	s_mov_b32 m0, s97
	s_nop 0
	global_load_lds_dwordx4 v[216:217], off
	s_waitcnt vmcnt(8)
	s_waitcnt lgkmcnt(0)
	s_barrier
	s_setprio 1
	s_waitcnt lgkmcnt(0)
	v_mfma_f32_16x16x32_bf16 v[156:159], v[104:107], v[160:163], v[156:159]
	v_mfma_f32_16x16x32_bf16 v[60:63], v[112:115], v[160:163], v[60:63]
	v_mfma_f32_16x16x32_bf16 v[148:151], v[104:107], v[168:171], v[148:151]
	v_mfma_f32_16x16x32_bf16 v[52:55], v[112:115], v[168:171], v[52:55]
	v_mfma_f32_16x16x32_bf16 v[140:143], v[104:107], v[192:195], v[140:143]
	v_mfma_f32_16x16x32_bf16 v[44:47], v[112:115], v[192:195], v[44:47]
	v_mfma_f32_16x16x32_bf16 v[100:103], v[104:107], v[200:203], v[100:103]
	v_mfma_f32_16x16x32_bf16 v[36:39], v[112:115], v[200:203], v[36:39]
	v_mfma_f32_16x16x32_bf16 v[156:159], v[108:111], v[164:167], v[156:159]
	v_mfma_f32_16x16x32_bf16 v[60:63], v[116:119], v[164:167], v[60:63]
	v_mfma_f32_16x16x32_bf16 v[148:151], v[108:111], v[172:175], v[148:151]
	v_mfma_f32_16x16x32_bf16 v[52:55], v[116:119], v[172:175], v[52:55]
	v_mfma_f32_16x16x32_bf16 v[140:143], v[108:111], v[196:199], v[140:143]
	v_mfma_f32_16x16x32_bf16 v[44:47], v[116:119], v[196:199], v[44:47]
	v_mfma_f32_16x16x32_bf16 v[100:103], v[108:111], v[204:207], v[100:103]
	v_mfma_f32_16x16x32_bf16 v[36:39], v[116:119], v[204:207], v[36:39]
	s_setprio 0
	s_setprio 1
	v_mfma_f32_16x16x32_bf16 v[152:155], v[120:123], v[160:163], v[152:155]
	v_mfma_f32_16x16x32_bf16 v[56:59], v[128:131], v[160:163], v[56:59]
	v_mfma_f32_16x16x32_bf16 v[144:147], v[120:123], v[168:171], v[144:147]
	v_mfma_f32_16x16x32_bf16 v[48:51], v[128:131], v[168:171], v[48:51]
	v_mfma_f32_16x16x32_bf16 v[136:139], v[120:123], v[192:195], v[136:139]
	v_mfma_f32_16x16x32_bf16 v[40:43], v[128:131], v[192:195], v[40:43]
	v_mfma_f32_16x16x32_bf16 v[96:99], v[120:123], v[200:203], v[96:99]
	v_mfma_f32_16x16x32_bf16 v[32:35], v[128:131], v[200:203], v[32:35]
	v_mfma_f32_16x16x32_bf16 v[152:155], v[124:127], v[164:167], v[152:155]
	v_mfma_f32_16x16x32_bf16 v[56:59], v[132:135], v[164:167], v[56:59]
	v_mfma_f32_16x16x32_bf16 v[144:147], v[124:127], v[172:175], v[144:147]
	v_mfma_f32_16x16x32_bf16 v[48:51], v[132:135], v[172:175], v[48:51]
	v_mfma_f32_16x16x32_bf16 v[136:139], v[124:127], v[196:199], v[136:139]
	v_mfma_f32_16x16x32_bf16 v[40:43], v[132:135], v[196:199], v[40:43]
	v_mfma_f32_16x16x32_bf16 v[96:99], v[124:127], v[204:207], v[96:99]
	v_mfma_f32_16x16x32_bf16 v[32:35], v[132:135], v[204:207], v[32:35]
	s_setprio 0
	s_barrier
	s_add_i32 s76, s81, s41
	v_lshl_add_u64 v[208:209], v[208:209], 0, s[46:47]
	s_mov_b32 m0, s76
	ds_read_b128 v[160:163], v240 offset:49152
	ds_read_b128 v[164:167], v240 offset:50176
	ds_read_b128 v[168:171], v240 offset:51200
	ds_read_b128 v[172:175], v240 offset:52224
	ds_read_b128 v[192:195], v240 offset:53248
	ds_read_b128 v[196:199], v240 offset:54272
	ds_read_b128 v[200:203], v240 offset:55296
	ds_read_b128 v[204:207], v240 offset:56320
	global_load_lds_dwordx4 v[208:209], off
	s_add_i32 m0, s76, 0x2000
	s_add_u32 s74, s74, 0x40080
	v_lshl_add_u64 v[208:209], v[210:211], 0, s[46:47]
	s_addc_u32 s75, s75, 0
	s_add_i32 s76, s82, s41
	global_load_lds_dwordx4 v[208:209], off
	v_lshl_add_u64 v[208:209], s[74:75], 0, v[178:179]
	s_mov_b32 m0, s76
	s_nop 0
	global_load_lds_dwordx4 v[208:209], off
	v_lshl_add_u64 v[208:209], s[74:75], 0, v[182:183]
	s_add_i32 m0, s76, 0x2000
	s_nop 0
	global_load_lds_dwordx4 v[208:209], off
	v_lshl_add_u64 v[208:209], v[212:213], 0, s[46:47]
	s_mov_b32 m0, s7
	s_nop 0
	global_load_lds_dwordx4 v[208:209], off
	v_lshl_add_u64 v[208:209], v[214:215], 0, s[46:47]
	s_mov_b32 m0, s36
	s_nop 0
	global_load_lds_dwordx4 v[208:209], off
	s_waitcnt vmcnt(8)
	s_waitcnt lgkmcnt(0)
	s_barrier
	s_setprio 1
	s_waitcnt lgkmcnt(0)
	v_mfma_f32_16x16x32_bf16 v[92:95], v[104:107], v[160:163], v[92:95]
	v_mfma_f32_16x16x32_bf16 v[28:31], v[112:115], v[160:163], v[28:31]
	v_mfma_f32_16x16x32_bf16 v[84:87], v[104:107], v[168:171], v[84:87]
	v_mfma_f32_16x16x32_bf16 v[20:23], v[112:115], v[168:171], v[20:23]
	v_mfma_f32_16x16x32_bf16 v[76:79], v[104:107], v[192:195], v[76:79]
	v_mfma_f32_16x16x32_bf16 v[12:15], v[112:115], v[192:195], v[12:15]
	v_mfma_f32_16x16x32_bf16 v[68:71], v[104:107], v[200:203], v[68:71]
	v_mfma_f32_16x16x32_bf16 v[4:7], v[112:115], v[200:203], v[4:7]
	v_mfma_f32_16x16x32_bf16 v[92:95], v[108:111], v[164:167], v[92:95]
	v_mfma_f32_16x16x32_bf16 v[28:31], v[116:119], v[164:167], v[28:31]
	v_mfma_f32_16x16x32_bf16 v[84:87], v[108:111], v[172:175], v[84:87]
	v_mfma_f32_16x16x32_bf16 v[20:23], v[116:119], v[172:175], v[20:23]
	v_mfma_f32_16x16x32_bf16 v[76:79], v[108:111], v[196:199], v[76:79]
	v_mfma_f32_16x16x32_bf16 v[12:15], v[116:119], v[196:199], v[12:15]
	v_mfma_f32_16x16x32_bf16 v[68:71], v[108:111], v[204:207], v[68:71]
	v_mfma_f32_16x16x32_bf16 v[4:7], v[116:119], v[204:207], v[4:7]
	s_setprio 0
	s_setprio 1
	v_mfma_f32_16x16x32_bf16 v[88:91], v[120:123], v[160:163], v[88:91]
	v_mfma_f32_16x16x32_bf16 v[24:27], v[128:131], v[160:163], v[24:27]
	v_mfma_f32_16x16x32_bf16 v[80:83], v[120:123], v[168:171], v[80:83]
	v_mfma_f32_16x16x32_bf16 v[16:19], v[128:131], v[168:171], v[16:19]
	v_mfma_f32_16x16x32_bf16 v[72:75], v[120:123], v[192:195], v[72:75]
	v_mfma_f32_16x16x32_bf16 v[8:11], v[128:131], v[192:195], v[8:11]
	v_mfma_f32_16x16x32_bf16 v[64:67], v[120:123], v[200:203], v[64:67]
	v_mfma_f32_16x16x32_bf16 v[0:3], v[128:131], v[200:203], v[0:3]
	v_mfma_f32_16x16x32_bf16 v[88:91], v[124:127], v[164:167], v[88:91]
	v_mfma_f32_16x16x32_bf16 v[24:27], v[132:135], v[164:167], v[24:27]
	v_mfma_f32_16x16x32_bf16 v[80:83], v[124:127], v[172:175], v[80:83]
	v_mfma_f32_16x16x32_bf16 v[16:19], v[132:135], v[172:175], v[16:19]
	v_mfma_f32_16x16x32_bf16 v[72:75], v[124:127], v[196:199], v[72:75]
	v_mfma_f32_16x16x32_bf16 v[8:11], v[132:135], v[196:199], v[8:11]
	v_mfma_f32_16x16x32_bf16 v[64:67], v[124:127], v[204:207], v[64:67]
	v_mfma_f32_16x16x32_bf16 v[0:3], v[132:135], v[204:207], v[0:3]
	s_setprio 0
	s_add_i32 s80, s80, 2
	s_add_u32 s78, s78, 0x100
	s_addc_u32 s79, s79, 0
	s_add_u32 s24, s24, 0x100
	s_addc_u32 s25, s25, 0
	s_cmp_gt_u32 s80, 13
	s_barrier
	s_cbranch_scc0 .LBB0_1249
	s_and_b64 vcc, exec, s[48:49]
	s_cbranch_vccz .LBB0_1252
	s_barrier

.LBB0_1584:
	ds_read_b128 v[146:149], v153
	ds_read_b128 v[156:159], v153 offset:1024
	ds_read_b128 v[160:163], v153 offset:2048
	ds_read_b128 v[164:167], v153 offset:3072
	ds_read_b128 v[168:171], v154
	ds_read_b128 v[172:175], v154 offset:1024
	ds_read_b128 v[176:179], v154 offset:2048
	ds_read_b128 v[180:183], v154 offset:3072
	s_add_u32 s46, s44, 0xfffc0080
	s_addc_u32 s47, s45, -1
	s_cmp_eq_u32 s56, 12
	s_cselect_b32 s49, s25, s47
	s_cselect_b32 s48, s31, s46
	s_cselect_b32 s47, s23, s55
	s_cselect_b32 s46, s39, s54
	v_lshl_add_u64 v[216:217], s[44:45], 0, v[140:141]
	s_add_i32 m0, s6, 0xc000
	ds_read_b128 v[184:187], v155
	ds_read_b128 v[188:191], v155 offset:1024
	ds_read_b128 v[192:195], v155 offset:2048
	ds_read_b128 v[196:199], v155 offset:3072
	ds_read_b128 v[200:203], v155 offset:4096
	ds_read_b128 v[204:207], v155 offset:5120
	ds_read_b128 v[208:211], v155 offset:6144
	ds_read_b128 v[212:215], v155 offset:7168
	global_load_lds_dwordx4 v[216:217], off
	v_lshl_add_u64 v[216:217], s[44:45], 0, v[138:139]
	s_add_i32 m0, s6, 0xe000
	s_nop 0
	global_load_lds_dwordx4 v[216:217], off
	s_waitcnt vmcnt(8)
	s_waitcnt lgkmcnt(0)
	s_barrier
	s_setprio 1
	s_waitcnt lgkmcnt(0)
	v_mfma_f32_16x16x32_bf16 v[124:127], v[146:149], v[184:187], v[124:127]
	v_mfma_f32_16x16x32_bf16 v[120:123], v[160:163], v[184:187], v[120:123]
	v_mfma_f32_16x16x32_bf16 v[116:119], v[146:149], v[192:195], v[116:119]
	v_mfma_f32_16x16x32_bf16 v[112:115], v[160:163], v[192:195], v[112:115]
	v_mfma_f32_16x16x32_bf16 v[108:111], v[146:149], v[200:203], v[108:111]
	v_mfma_f32_16x16x32_bf16 v[104:107], v[160:163], v[200:203], v[104:107]
	v_mfma_f32_16x16x32_bf16 v[100:103], v[146:149], v[208:211], v[100:103]
	v_mfma_f32_16x16x32_bf16 v[96:99], v[160:163], v[208:211], v[96:99]
	v_mfma_f32_16x16x32_bf16 v[124:127], v[156:159], v[188:191], v[124:127]
	v_mfma_f32_16x16x32_bf16 v[120:123], v[164:167], v[188:191], v[120:123]
	v_mfma_f32_16x16x32_bf16 v[116:119], v[156:159], v[196:199], v[116:119]
	v_mfma_f32_16x16x32_bf16 v[112:115], v[164:167], v[196:199], v[112:115]
	v_mfma_f32_16x16x32_bf16 v[108:111], v[156:159], v[204:207], v[108:111]
	v_mfma_f32_16x16x32_bf16 v[104:107], v[164:167], v[204:207], v[104:107]
	v_mfma_f32_16x16x32_bf16 v[100:103], v[156:159], v[212:215], v[100:103]
	v_mfma_f32_16x16x32_bf16 v[96:99], v[164:167], v[212:215], v[96:99]
	s_setprio 0
	s_setprio 1
	v_mfma_f32_16x16x32_bf16 v[60:63], v[168:171], v[184:187], v[60:63]
	v_mfma_f32_16x16x32_bf16 v[56:59], v[176:179], v[184:187], v[56:59]
	v_mfma_f32_16x16x32_bf16 v[52:55], v[168:171], v[192:195], v[52:55]
	v_mfma_f32_16x16x32_bf16 v[48:51], v[176:179], v[192:195], v[48:51]
	v_mfma_f32_16x16x32_bf16 v[44:47], v[168:171], v[200:203], v[44:47]
	v_mfma_f32_16x16x32_bf16 v[40:43], v[176:179], v[200:203], v[40:43]
	v_mfma_f32_16x16x32_bf16 v[36:39], v[168:171], v[208:211], v[36:39]
	v_mfma_f32_16x16x32_bf16 v[32:35], v[176:179], v[208:211], v[32:35]
	v_mfma_f32_16x16x32_bf16 v[60:63], v[172:175], v[188:191], v[60:63]
	v_mfma_f32_16x16x32_bf16 v[56:59], v[180:183], v[188:191], v[56:59]
	v_mfma_f32_16x16x32_bf16 v[52:55], v[172:175], v[196:199], v[52:55]
	v_mfma_f32_16x16x32_bf16 v[48:51], v[180:183], v[196:199], v[48:51]
	v_mfma_f32_16x16x32_bf16 v[44:47], v[172:175], v[204:207], v[44:47]
	v_mfma_f32_16x16x32_bf16 v[40:43], v[180:183], v[204:207], v[40:43]
	v_mfma_f32_16x16x32_bf16 v[36:39], v[172:175], v[212:215], v[36:39]
	v_mfma_f32_16x16x32_bf16 v[32:35], v[180:183], v[212:215], v[32:35]
	s_setprio 0
	s_barrier
	s_add_i32 s57, s43, s5
	v_lshl_add_u64 v[216:217], s[46:47], 0, v[130:131]
	s_mov_b32 m0, s57
	ds_read_b128 v[184:187], v155 offset:16384
	ds_read_b128 v[188:191], v155 offset:17408
	ds_read_b128 v[192:195], v155 offset:18432
	ds_read_b128 v[196:199], v155 offset:19456
	ds_read_b128 v[200:203], v155 offset:20480
	ds_read_b128 v[204:207], v155 offset:21504
	ds_read_b128 v[208:211], v155 offset:22528
	ds_read_b128 v[212:215], v155 offset:23552
	global_load_lds_dwordx4 v[216:217], off
	s_add_i32 m0, s57, 0x2000
	s_add_u32 s58, s46, 0x40000
	v_lshl_add_u64 v[218:219], s[46:47], 0, v[134:135]
	s_addc_u32 s59, s47, 0
	s_add_i32 s57, s50, s5
	global_load_lds_dwordx4 v[218:219], off
	v_lshl_add_u64 v[220:221], s[58:59], 0, v[130:131]
	s_mov_b32 m0, s57
	v_lshl_add_u64 v[222:223], s[48:49], 0, v[132:133]
	global_load_lds_dwordx4 v[220:221], off
	v_lshl_add_u64 v[220:221], s[58:59], 0, v[134:135]
	s_add_i32 m0, s57, 0x2000
	s_nop 0
	global_load_lds_dwordx4 v[220:221], off
	v_lshl_add_u64 v[220:221], s[48:49], 0, v[128:129]
	s_mov_b32 m0, s6
	s_nop 0
	global_load_lds_dwordx4 v[220:221], off
	s_mov_b32 m0, s7
	s_nop 0
	global_load_lds_dwordx4 v[222:223], off
	s_waitcnt vmcnt(8)
	s_waitcnt lgkmcnt(0)
	s_barrier
	s_setprio 1
	s_waitcnt lgkmcnt(0)
	v_mfma_f32_16x16x32_bf16 v[92:95], v[146:149], v[184:187], v[92:95]
	v_mfma_f32_16x16x32_bf16 v[88:91], v[160:163], v[184:187], v[88:91]
	v_mfma_f32_16x16x32_bf16 v[84:87], v[146:149], v[192:195], v[84:87]
	v_mfma_f32_16x16x32_bf16 v[80:83], v[160:163], v[192:195], v[80:83]
	v_mfma_f32_16x16x32_bf16 v[76:79], v[146:149], v[200:203], v[76:79]
	v_mfma_f32_16x16x32_bf16 v[72:75], v[160:163], v[200:203], v[72:75]
	v_mfma_f32_16x16x32_bf16 v[68:71], v[146:149], v[208:211], v[68:71]
	v_mfma_f32_16x16x32_bf16 v[64:67], v[160:163], v[208:211], v[64:67]
	v_mfma_f32_16x16x32_bf16 v[92:95], v[156:159], v[188:191], v[92:95]
	v_mfma_f32_16x16x32_bf16 v[88:91], v[164:167], v[188:191], v[88:91]
	v_mfma_f32_16x16x32_bf16 v[84:87], v[156:159], v[196:199], v[84:87]
	v_mfma_f32_16x16x32_bf16 v[80:83], v[164:167], v[196:199], v[80:83]
	v_mfma_f32_16x16x32_bf16 v[76:79], v[156:159], v[204:207], v[76:79]
	v_mfma_f32_16x16x32_bf16 v[72:75], v[164:167], v[204:207], v[72:75]
	v_mfma_f32_16x16x32_bf16 v[68:71], v[156:159], v[212:215], v[68:71]
	v_mfma_f32_16x16x32_bf16 v[64:67], v[164:167], v[212:215], v[64:67]
	s_setprio 0
	s_setprio 1
	v_mfma_f32_16x16x32_bf16 v[28:31], v[168:171], v[184:187], v[28:31]
	v_mfma_f32_16x16x32_bf16 v[24:27], v[176:179], v[184:187], v[24:27]
	v_mfma_f32_16x16x32_bf16 v[20:23], v[168:171], v[192:195], v[20:23]
	v_mfma_f32_16x16x32_bf16 v[16:19], v[176:179], v[192:195], v[16:19]
	v_mfma_f32_16x16x32_bf16 v[12:15], v[168:171], v[200:203], v[12:15]
	v_mfma_f32_16x16x32_bf16 v[8:11], v[176:179], v[200:203], v[8:11]
	v_mfma_f32_16x16x32_bf16 v[4:7], v[168:171], v[208:211], v[4:7]
	v_mfma_f32_16x16x32_bf16 v[0:3], v[176:179], v[208:211], v[0:3]
	v_mfma_f32_16x16x32_bf16 v[28:31], v[172:175], v[188:191], v[28:31]
	v_mfma_f32_16x16x32_bf16 v[24:27], v[180:183], v[188:191], v[24:27]
	v_mfma_f32_16x16x32_bf16 v[20:23], v[172:175], v[196:199], v[20:23]
	v_mfma_f32_16x16x32_bf16 v[16:19], v[180:183], v[196:199], v[16:19]
	v_mfma_f32_16x16x32_bf16 v[12:15], v[172:175], v[204:207], v[12:15]
	v_mfma_f32_16x16x32_bf16 v[8:11], v[180:183], v[204:207], v[8:11]
	v_mfma_f32_16x16x32_bf16 v[4:7], v[172:175], v[212:215], v[4:7]
	v_mfma_f32_16x16x32_bf16 v[0:3], v[180:183], v[212:215], v[0:3]
	s_setprio 0
	s_barrier
	s_add_i32 s57, 0, 0x18000
	s_add_i32 s58, 0, 0x1c000
	v_add_u32_e32 v164, s57, v151
	v_add_u32_e32 v180, s58, v151
	ds_read_b128 v[146:149], v164
	ds_read_b128 v[156:159], v164 offset:1024
	ds_read_b128 v[160:163], v164 offset:2048
	ds_read_b128 v[164:167], v164 offset:3072
	ds_read_b128 v[168:171], v180
	ds_read_b128 v[172:175], v180 offset:1024
	ds_read_b128 v[176:179], v180 offset:2048
	ds_read_b128 v[180:183], v180 offset:3072
	s_add_u32 s48, s48, 0x40000
	s_addc_u32 s49, s49, 0
	s_mov_b32 m0, s8
	v_lshl_add_u64 v[224:225], s[48:49], 0, v[128:129]
	ds_read_b128 v[184:187], v155 offset:32768
	ds_read_b128 v[188:191], v155 offset:33792
	ds_read_b128 v[192:195], v155 offset:34816
	ds_read_b128 v[196:199], v155 offset:35840
	ds_read_b128 v[200:203], v155 offset:36864
	ds_read_b128 v[204:207], v155 offset:37888
	ds_read_b128 v[208:211], v155 offset:38912
	ds_read_b128 v[212:215], v155 offset:39936
	global_load_lds_dwordx4 v[224:225], off
	v_lshl_add_u64 v[224:225], s[48:49], 0, v[132:133]
	s_mov_b32 m0, s9
	s_nop 0
	global_load_lds_dwordx4 v[224:225], off
	s_waitcnt vmcnt(8)
	s_waitcnt lgkmcnt(0)
	s_barrier
	s_setprio 1
	s_waitcnt lgkmcnt(0)
	v_mfma_f32_16x16x32_bf16 v[124:127], v[146:149], v[184:187], v[124:127]
	v_mfma_f32_16x16x32_bf16 v[120:123], v[160:163], v[184:187], v[120:123]
	v_mfma_f32_16x16x32_bf16 v[116:119], v[146:149], v[192:195], v[116:119]
	v_mfma_f32_16x16x32_bf16 v[112:115], v[160:163], v[192:195], v[112:115]
	v_mfma_f32_16x16x32_bf16 v[108:111], v[146:149], v[200:203], v[108:111]
	v_mfma_f32_16x16x32_bf16 v[104:107], v[160:163], v[200:203], v[104:107]
	v_mfma_f32_16x16x32_bf16 v[100:103], v[146:149], v[208:211], v[100:103]
	v_mfma_f32_16x16x32_bf16 v[96:99], v[160:163], v[208:211], v[96:99]
	v_mfma_f32_16x16x32_bf16 v[124:127], v[156:159], v[188:191], v[124:127]
	v_mfma_f32_16x16x32_bf16 v[120:123], v[164:167], v[188:191], v[120:123]
	v_mfma_f32_16x16x32_bf16 v[116:119], v[156:159], v[196:199], v[116:119]
	v_mfma_f32_16x16x32_bf16 v[112:115], v[164:167], v[196:199], v[112:115]
	v_mfma_f32_16x16x32_bf16 v[108:111], v[156:159], v[204:207], v[108:111]
	v_mfma_f32_16x16x32_bf16 v[104:107], v[164:167], v[204:207], v[104:107]
	v_mfma_f32_16x16x32_bf16 v[100:103], v[156:159], v[212:215], v[100:103]
	v_mfma_f32_16x16x32_bf16 v[96:99], v[164:167], v[212:215], v[96:99]
	s_setprio 0
	s_setprio 1
	v_mfma_f32_16x16x32_bf16 v[60:63], v[168:171], v[184:187], v[60:63]
	v_mfma_f32_16x16x32_bf16 v[56:59], v[176:179], v[184:187], v[56:59]
	v_mfma_f32_16x16x32_bf16 v[52:55], v[168:171], v[192:195], v[52:55]
	v_mfma_f32_16x16x32_bf16 v[48:51], v[176:179], v[192:195], v[48:51]
	v_mfma_f32_16x16x32_bf16 v[44:47], v[168:171], v[200:203], v[44:47]
	v_mfma_f32_16x16x32_bf16 v[40:43], v[176:179], v[200:203], v[40:43]
	v_mfma_f32_16x16x32_bf16 v[36:39], v[168:171], v[208:211], v[36:39]
	v_mfma_f32_16x16x32_bf16 v[32:35], v[176:179], v[208:211], v[32:35]
	v_mfma_f32_16x16x32_bf16 v[60:63], v[172:175], v[188:191], v[60:63]
	v_mfma_f32_16x16x32_bf16 v[56:59], v[180:183], v[188:191], v[56:59]
	v_mfma_f32_16x16x32_bf16 v[52:55], v[172:175], v[196:199], v[52:55]
	v_mfma_f32_16x16x32_bf16 v[48:51], v[180:183], v[196:199], v[48:51]
	v_mfma_f32_16x16x32_bf16 v[44:47], v[172:175], v[204:207], v[44:47]
	v_mfma_f32_16x16x32_bf16 v[40:43], v[180:183], v[204:207], v[40:43]
	v_mfma_f32_16x16x32_bf16 v[36:39], v[172:175], v[212:215], v[36:39]
	v_mfma_f32_16x16x32_bf16 v[32:35], v[180:183], v[212:215], v[32:35]
	s_setprio 0
	s_barrier
	s_add_i32 s48, s57, s5
	v_lshl_add_u64 v[216:217], v[216:217], 0, s[18:19]
	s_mov_b32 m0, s48
	ds_read_b128 v[184:187], v155 offset:49152
	ds_read_b128 v[188:191], v155 offset:50176
	ds_read_b128 v[192:195], v155 offset:51200
	ds_read_b128 v[196:199], v155 offset:52224
	ds_read_b128 v[200:203], v155 offset:53248
	ds_read_b128 v[204:207], v155 offset:54272
	ds_read_b128 v[208:211], v155 offset:55296
	ds_read_b128 v[212:215], v155 offset:56320
	global_load_lds_dwordx4 v[216:217], off
	s_add_i32 m0, s48, 0x2000
	s_add_u32 s46, s46, 0x40080
	v_lshl_add_u64 v[216:217], v[218:219], 0, s[18:19]
	s_addc_u32 s47, s47, 0
	s_add_i32 s48, s58, s5
	global_load_lds_dwordx4 v[216:217], off
	v_lshl_add_u64 v[216:217], s[46:47], 0, v[130:131]
	s_mov_b32 m0, s48
	s_nop 0
	global_load_lds_dwordx4 v[216:217], off
	v_lshl_add_u64 v[216:217], s[46:47], 0, v[134:135]
	s_add_i32 m0, s48, 0x2000
	s_nop 0
	global_load_lds_dwordx4 v[216:217], off
	v_lshl_add_u64 v[216:217], v[220:221], 0, s[18:19]
	s_mov_b32 m0, s35
	s_nop 0
	global_load_lds_dwordx4 v[216:217], off
	v_lshl_add_u64 v[216:217], v[222:223], 0, s[18:19]
	s_mov_b32 m0, s36
	s_nop 0
	global_load_lds_dwordx4 v[216:217], off
	s_waitcnt vmcnt(8)
	s_waitcnt lgkmcnt(0)
	s_barrier
	s_setprio 1
	s_waitcnt lgkmcnt(0)
	v_mfma_f32_16x16x32_bf16 v[92:95], v[146:149], v[184:187], v[92:95]
	v_mfma_f32_16x16x32_bf16 v[88:91], v[160:163], v[184:187], v[88:91]
	v_mfma_f32_16x16x32_bf16 v[84:87], v[146:149], v[192:195], v[84:87]
	v_mfma_f32_16x16x32_bf16 v[80:83], v[160:163], v[192:195], v[80:83]
	v_mfma_f32_16x16x32_bf16 v[76:79], v[146:149], v[200:203], v[76:79]
	v_mfma_f32_16x16x32_bf16 v[72:75], v[160:163], v[200:203], v[72:75]
	v_mfma_f32_16x16x32_bf16 v[68:71], v[146:149], v[208:211], v[68:71]
	v_mfma_f32_16x16x32_bf16 v[64:67], v[160:163], v[208:211], v[64:67]
	v_mfma_f32_16x16x32_bf16 v[92:95], v[156:159], v[188:191], v[92:95]
	v_mfma_f32_16x16x32_bf16 v[88:91], v[164:167], v[188:191], v[88:91]
	v_mfma_f32_16x16x32_bf16 v[84:87], v[156:159], v[196:199], v[84:87]
	v_mfma_f32_16x16x32_bf16 v[80:83], v[164:167], v[196:199], v[80:83]
	v_mfma_f32_16x16x32_bf16 v[76:79], v[156:159], v[204:207], v[76:79]
	v_mfma_f32_16x16x32_bf16 v[72:75], v[164:167], v[204:207], v[72:75]
	v_mfma_f32_16x16x32_bf16 v[68:71], v[156:159], v[212:215], v[68:71]
	v_mfma_f32_16x16x32_bf16 v[64:67], v[164:167], v[212:215], v[64:67]
	s_setprio 0
	s_setprio 1
	v_mfma_f32_16x16x32_bf16 v[28:31], v[168:171], v[184:187], v[28:31]
	v_mfma_f32_16x16x32_bf16 v[24:27], v[176:179], v[184:187], v[24:27]
	v_mfma_f32_16x16x32_bf16 v[20:23], v[168:171], v[192:195], v[20:23]
	v_mfma_f32_16x16x32_bf16 v[16:19], v[176:179], v[192:195], v[16:19]
	v_mfma_f32_16x16x32_bf16 v[12:15], v[168:171], v[200:203], v[12:15]
	v_mfma_f32_16x16x32_bf16 v[8:11], v[176:179], v[200:203], v[8:11]
	v_mfma_f32_16x16x32_bf16 v[4:7], v[168:171], v[208:211], v[4:7]
	v_mfma_f32_16x16x32_bf16 v[0:3], v[176:179], v[208:211], v[0:3]
	v_mfma_f32_16x16x32_bf16 v[28:31], v[172:175], v[188:191], v[28:31]
	v_mfma_f32_16x16x32_bf16 v[24:27], v[180:183], v[188:191], v[24:27]
	v_mfma_f32_16x16x32_bf16 v[20:23], v[172:175], v[196:199], v[20:23]
	v_mfma_f32_16x16x32_bf16 v[16:19], v[180:183], v[196:199], v[16:19]
	v_mfma_f32_16x16x32_bf16 v[12:15], v[172:175], v[204:207], v[12:15]
	v_mfma_f32_16x16x32_bf16 v[8:11], v[180:183], v[204:207], v[8:11]
	v_mfma_f32_16x16x32_bf16 v[4:7], v[172:175], v[212:215], v[4:7]
	v_mfma_f32_16x16x32_bf16 v[0:3], v[180:183], v[212:215], v[0:3]
	s_setprio 0
	s_add_i32 s56, s56, 2
	s_add_u32 s54, s54, 0x100
	s_addc_u32 s55, s55, 0
	s_add_u32 s44, s44, 0x100
	s_addc_u32 s45, s45, 0
	s_cmp_gt_u32 s56, 13
	s_barrier
	s_cbranch_scc0 .LBB0_1584
	s_and_b64 vcc, exec, s[20:21]
	s_cbranch_vccz .LBB0_1587
	s_barrier

.LBB0_1805:
	ds_read_b128 v[144:147], v157
	ds_read_b128 v[148:151], v157 offset:1024
	ds_read_b128 v[160:163], v157 offset:2048
	ds_read_b128 v[164:167], v157 offset:3072
	ds_read_b128 v[168:171], v158
	ds_read_b128 v[172:175], v158 offset:1024
	ds_read_b128 v[176:179], v158 offset:2048
	ds_read_b128 v[180:183], v158 offset:3072
	s_add_u32 s44, s30, 0xfffc0080
	s_addc_u32 s45, s31, -1
	s_cmp_eq_u32 s54, 12
	s_cselect_b32 s47, s23, s45
	s_cselect_b32 s46, s50, s44
	s_cselect_b32 s45, s21, s53
	s_cselect_b32 s44, s51, s52
	v_lshl_add_u64 v[152:153], s[30:31], 0, v[138:139]
	s_add_i32 m0, s7, 0xc000
	ds_read_b128 v[184:187], v159
	ds_read_b128 v[188:191], v159 offset:1024
	ds_read_b128 v[192:195], v159 offset:2048
	ds_read_b128 v[196:199], v159 offset:3072
	ds_read_b128 v[200:203], v159 offset:4096
	ds_read_b128 v[204:207], v159 offset:5120
	ds_read_b128 v[208:211], v159 offset:6144
	ds_read_b128 v[212:215], v159 offset:7168
	global_load_lds_dwordx4 v[152:153], off
	v_lshl_add_u64 v[152:153], s[30:31], 0, v[136:137]
	s_add_i32 m0, s7, 0xe000
	s_nop 0
	global_load_lds_dwordx4 v[152:153], off
	s_waitcnt vmcnt(8)
	s_waitcnt lgkmcnt(0)
	s_barrier
	s_setprio 1
	s_waitcnt lgkmcnt(0)
	v_mfma_f32_16x16x32_bf16 v[124:127], v[144:147], v[184:187], v[124:127]
	v_mfma_f32_16x16x32_bf16 v[120:123], v[160:163], v[184:187], v[120:123]
	v_mfma_f32_16x16x32_bf16 v[116:119], v[144:147], v[192:195], v[116:119]
	v_mfma_f32_16x16x32_bf16 v[112:115], v[160:163], v[192:195], v[112:115]
	v_mfma_f32_16x16x32_bf16 v[108:111], v[144:147], v[200:203], v[108:111]
	v_mfma_f32_16x16x32_bf16 v[104:107], v[160:163], v[200:203], v[104:107]
	v_mfma_f32_16x16x32_bf16 v[100:103], v[144:147], v[208:211], v[100:103]
	v_mfma_f32_16x16x32_bf16 v[96:99], v[160:163], v[208:211], v[96:99]
	v_mfma_f32_16x16x32_bf16 v[124:127], v[148:151], v[188:191], v[124:127]
	v_mfma_f32_16x16x32_bf16 v[120:123], v[164:167], v[188:191], v[120:123]
	v_mfma_f32_16x16x32_bf16 v[116:119], v[148:151], v[196:199], v[116:119]
	v_mfma_f32_16x16x32_bf16 v[112:115], v[164:167], v[196:199], v[112:115]
	v_mfma_f32_16x16x32_bf16 v[108:111], v[148:151], v[204:207], v[108:111]
	v_mfma_f32_16x16x32_bf16 v[104:107], v[164:167], v[204:207], v[104:107]
	v_mfma_f32_16x16x32_bf16 v[100:103], v[148:151], v[212:215], v[100:103]
	v_mfma_f32_16x16x32_bf16 v[96:99], v[164:167], v[212:215], v[96:99]
	s_setprio 0
	s_setprio 1
	v_mfma_f32_16x16x32_bf16 v[76:79], v[168:171], v[184:187], v[76:79]
	v_mfma_f32_16x16x32_bf16 v[72:75], v[176:179], v[184:187], v[72:75]
	v_mfma_f32_16x16x32_bf16 v[60:63], v[168:171], v[192:195], v[60:63]
	v_mfma_f32_16x16x32_bf16 v[52:55], v[176:179], v[192:195], v[52:55]
	v_mfma_f32_16x16x32_bf16 v[44:47], v[168:171], v[200:203], v[44:47]
	v_mfma_f32_16x16x32_bf16 v[40:43], v[176:179], v[200:203], v[40:43]
	v_mfma_f32_16x16x32_bf16 v[36:39], v[168:171], v[208:211], v[36:39]
	v_mfma_f32_16x16x32_bf16 v[32:35], v[176:179], v[208:211], v[32:35]
	v_mfma_f32_16x16x32_bf16 v[76:79], v[172:175], v[188:191], v[76:79]
	v_mfma_f32_16x16x32_bf16 v[72:75], v[180:183], v[188:191], v[72:75]
	v_mfma_f32_16x16x32_bf16 v[60:63], v[172:175], v[196:199], v[60:63]
	v_mfma_f32_16x16x32_bf16 v[52:55], v[180:183], v[196:199], v[52:55]
	v_mfma_f32_16x16x32_bf16 v[44:47], v[172:175], v[204:207], v[44:47]
	v_mfma_f32_16x16x32_bf16 v[40:43], v[180:183], v[204:207], v[40:43]
	v_mfma_f32_16x16x32_bf16 v[36:39], v[172:175], v[212:215], v[36:39]
	v_mfma_f32_16x16x32_bf16 v[32:35], v[180:183], v[212:215], v[32:35]
	s_setprio 0
	s_barrier
	s_add_i32 s55, s41, s6
	v_lshl_add_u64 v[152:153], s[44:45], 0, v[130:131]
	s_mov_b32 m0, s55
	ds_read_b128 v[184:187], v159 offset:16384
	ds_read_b128 v[188:191], v159 offset:17408
	ds_read_b128 v[192:195], v159 offset:18432
	ds_read_b128 v[196:199], v159 offset:19456
	ds_read_b128 v[200:203], v159 offset:20480
	ds_read_b128 v[204:207], v159 offset:21504
	ds_read_b128 v[208:211], v159 offset:22528
	ds_read_b128 v[212:215], v159 offset:23552
	global_load_lds_dwordx4 v[152:153], off
	s_add_i32 m0, s55, 0x2000
	s_add_u32 s56, s44, 0x40000
	v_lshl_add_u64 v[216:217], s[44:45], 0, v[134:135]
	s_addc_u32 s57, s45, 0
	s_add_i32 s55, s42, s6
	global_load_lds_dwordx4 v[216:217], off
	v_lshl_add_u64 v[218:219], s[56:57], 0, v[130:131]
	s_mov_b32 m0, s55
	v_lshl_add_u64 v[220:221], s[46:47], 0, v[132:133]
	global_load_lds_dwordx4 v[218:219], off
	v_lshl_add_u64 v[218:219], s[56:57], 0, v[134:135]
	s_add_i32 m0, s55, 0x2000
	s_nop 0
	global_load_lds_dwordx4 v[218:219], off
	v_lshl_add_u64 v[218:219], s[46:47], 0, v[128:129]
	s_mov_b32 m0, s7
	s_nop 0
	global_load_lds_dwordx4 v[218:219], off
	s_mov_b32 m0, s8
	s_nop 0
	global_load_lds_dwordx4 v[220:221], off
	s_waitcnt vmcnt(8)
	s_waitcnt lgkmcnt(0)
	s_barrier
	s_setprio 1
	s_waitcnt lgkmcnt(0)
	v_mfma_f32_16x16x32_bf16 v[92:95], v[144:147], v[184:187], v[92:95]
	v_mfma_f32_16x16x32_bf16 v[88:91], v[160:163], v[184:187], v[88:91]
	v_mfma_f32_16x16x32_bf16 v[84:87], v[144:147], v[192:195], v[84:87]
	v_mfma_f32_16x16x32_bf16 v[80:83], v[160:163], v[192:195], v[80:83]
	v_mfma_f32_16x16x32_bf16 v[68:71], v[144:147], v[200:203], v[68:71]
	v_mfma_f32_16x16x32_bf16 v[64:67], v[160:163], v[200:203], v[64:67]
	v_mfma_f32_16x16x32_bf16 v[56:59], v[144:147], v[208:211], v[56:59]
	v_mfma_f32_16x16x32_bf16 v[48:51], v[160:163], v[208:211], v[48:51]
	v_mfma_f32_16x16x32_bf16 v[92:95], v[148:151], v[188:191], v[92:95]
	v_mfma_f32_16x16x32_bf16 v[88:91], v[164:167], v[188:191], v[88:91]
	v_mfma_f32_16x16x32_bf16 v[84:87], v[148:151], v[196:199], v[84:87]
	v_mfma_f32_16x16x32_bf16 v[80:83], v[164:167], v[196:199], v[80:83]
	v_mfma_f32_16x16x32_bf16 v[68:71], v[148:151], v[204:207], v[68:71]
	v_mfma_f32_16x16x32_bf16 v[64:67], v[164:167], v[204:207], v[64:67]
	v_mfma_f32_16x16x32_bf16 v[56:59], v[148:151], v[212:215], v[56:59]
	v_mfma_f32_16x16x32_bf16 v[48:51], v[164:167], v[212:215], v[48:51]
	s_setprio 0
	s_setprio 1
	v_mfma_f32_16x16x32_bf16 v[28:31], v[168:171], v[184:187], v[28:31]
	v_mfma_f32_16x16x32_bf16 v[24:27], v[176:179], v[184:187], v[24:27]
	v_mfma_f32_16x16x32_bf16 v[20:23], v[168:171], v[192:195], v[20:23]
	v_mfma_f32_16x16x32_bf16 v[16:19], v[176:179], v[192:195], v[16:19]
	v_mfma_f32_16x16x32_bf16 v[12:15], v[168:171], v[200:203], v[12:15]
	v_mfma_f32_16x16x32_bf16 v[8:11], v[176:179], v[200:203], v[8:11]
	v_mfma_f32_16x16x32_bf16 v[4:7], v[168:171], v[208:211], v[4:7]
	v_mfma_f32_16x16x32_bf16 v[0:3], v[176:179], v[208:211], v[0:3]
	v_mfma_f32_16x16x32_bf16 v[28:31], v[172:175], v[188:191], v[28:31]
	v_mfma_f32_16x16x32_bf16 v[24:27], v[180:183], v[188:191], v[24:27]
	v_mfma_f32_16x16x32_bf16 v[20:23], v[172:175], v[196:199], v[20:23]
	v_mfma_f32_16x16x32_bf16 v[16:19], v[180:183], v[196:199], v[16:19]
	v_mfma_f32_16x16x32_bf16 v[12:15], v[172:175], v[204:207], v[12:15]
	v_mfma_f32_16x16x32_bf16 v[8:11], v[180:183], v[204:207], v[8:11]
	v_mfma_f32_16x16x32_bf16 v[4:7], v[172:175], v[212:215], v[4:7]
	v_mfma_f32_16x16x32_bf16 v[0:3], v[180:183], v[212:215], v[0:3]
	s_setprio 0
	s_barrier
	s_add_i32 s55, 0, 0x18000
	s_add_i32 s56, 0, 0x1c000
	v_add_u32_e32 v164, s55, v155
	v_add_u32_e32 v180, s56, v155
	ds_read_b128 v[144:147], v164
	ds_read_b128 v[148:151], v164 offset:1024
	ds_read_b128 v[160:163], v164 offset:2048
	ds_read_b128 v[164:167], v164 offset:3072
	ds_read_b128 v[168:171], v180
	ds_read_b128 v[172:175], v180 offset:1024
	ds_read_b128 v[176:179], v180 offset:2048
	ds_read_b128 v[180:183], v180 offset:3072
	s_add_u32 s46, s46, 0x40000
	s_addc_u32 s47, s47, 0
	s_mov_b32 m0, s9
	v_lshl_add_u64 v[222:223], s[46:47], 0, v[128:129]
	ds_read_b128 v[184:187], v159 offset:32768
	ds_read_b128 v[188:191], v159 offset:33792
	ds_read_b128 v[192:195], v159 offset:34816
	ds_read_b128 v[196:199], v159 offset:35840
	ds_read_b128 v[200:203], v159 offset:36864
	ds_read_b128 v[204:207], v159 offset:37888
	ds_read_b128 v[208:211], v159 offset:38912
	ds_read_b128 v[212:215], v159 offset:39936
	global_load_lds_dwordx4 v[222:223], off
	v_lshl_add_u64 v[222:223], s[46:47], 0, v[132:133]
	s_mov_b32 m0, s33
	s_nop 0
	global_load_lds_dwordx4 v[222:223], off
	s_waitcnt vmcnt(8)
	s_waitcnt lgkmcnt(0)
	s_barrier
	s_setprio 1
	s_waitcnt lgkmcnt(0)
	v_mfma_f32_16x16x32_bf16 v[124:127], v[144:147], v[184:187], v[124:127]
	v_mfma_f32_16x16x32_bf16 v[120:123], v[160:163], v[184:187], v[120:123]
	v_mfma_f32_16x16x32_bf16 v[116:119], v[144:147], v[192:195], v[116:119]
	v_mfma_f32_16x16x32_bf16 v[112:115], v[160:163], v[192:195], v[112:115]
	v_mfma_f32_16x16x32_bf16 v[108:111], v[144:147], v[200:203], v[108:111]
	v_mfma_f32_16x16x32_bf16 v[104:107], v[160:163], v[200:203], v[104:107]
	v_mfma_f32_16x16x32_bf16 v[100:103], v[144:147], v[208:211], v[100:103]
	v_mfma_f32_16x16x32_bf16 v[96:99], v[160:163], v[208:211], v[96:99]
	v_mfma_f32_16x16x32_bf16 v[124:127], v[148:151], v[188:191], v[124:127]
	v_mfma_f32_16x16x32_bf16 v[120:123], v[164:167], v[188:191], v[120:123]
	v_mfma_f32_16x16x32_bf16 v[116:119], v[148:151], v[196:199], v[116:119]
	v_mfma_f32_16x16x32_bf16 v[112:115], v[164:167], v[196:199], v[112:115]
	v_mfma_f32_16x16x32_bf16 v[108:111], v[148:151], v[204:207], v[108:111]
	v_mfma_f32_16x16x32_bf16 v[104:107], v[164:167], v[204:207], v[104:107]
	v_mfma_f32_16x16x32_bf16 v[100:103], v[148:151], v[212:215], v[100:103]
	v_mfma_f32_16x16x32_bf16 v[96:99], v[164:167], v[212:215], v[96:99]
	s_setprio 0
	s_setprio 1
	v_mfma_f32_16x16x32_bf16 v[76:79], v[168:171], v[184:187], v[76:79]
	v_mfma_f32_16x16x32_bf16 v[72:75], v[176:179], v[184:187], v[72:75]
	v_mfma_f32_16x16x32_bf16 v[60:63], v[168:171], v[192:195], v[60:63]
	v_mfma_f32_16x16x32_bf16 v[52:55], v[176:179], v[192:195], v[52:55]
	v_mfma_f32_16x16x32_bf16 v[44:47], v[168:171], v[200:203], v[44:47]
	v_mfma_f32_16x16x32_bf16 v[40:43], v[176:179], v[200:203], v[40:43]
	v_mfma_f32_16x16x32_bf16 v[36:39], v[168:171], v[208:211], v[36:39]
	v_mfma_f32_16x16x32_bf16 v[32:35], v[176:179], v[208:211], v[32:35]
	v_mfma_f32_16x16x32_bf16 v[76:79], v[172:175], v[188:191], v[76:79]
	v_mfma_f32_16x16x32_bf16 v[72:75], v[180:183], v[188:191], v[72:75]
	v_mfma_f32_16x16x32_bf16 v[60:63], v[172:175], v[196:199], v[60:63]
	v_mfma_f32_16x16x32_bf16 v[52:55], v[180:183], v[196:199], v[52:55]
	v_mfma_f32_16x16x32_bf16 v[44:47], v[172:175], v[204:207], v[44:47]
	v_mfma_f32_16x16x32_bf16 v[40:43], v[180:183], v[204:207], v[40:43]
	v_mfma_f32_16x16x32_bf16 v[36:39], v[172:175], v[212:215], v[36:39]
	v_mfma_f32_16x16x32_bf16 v[32:35], v[180:183], v[212:215], v[32:35]
	s_setprio 0
	s_barrier
	s_add_i32 s46, s55, s6
	v_lshl_add_u64 v[152:153], v[152:153], 0, s[16:17]
	s_mov_b32 m0, s46
	ds_read_b128 v[184:187], v159 offset:49152
	ds_read_b128 v[188:191], v159 offset:50176
	ds_read_b128 v[192:195], v159 offset:51200
	ds_read_b128 v[196:199], v159 offset:52224
	ds_read_b128 v[200:203], v159 offset:53248
	ds_read_b128 v[204:207], v159 offset:54272
	ds_read_b128 v[208:211], v159 offset:55296
	ds_read_b128 v[212:215], v159 offset:56320
	global_load_lds_dwordx4 v[152:153], off
	s_add_i32 m0, s46, 0x2000
	s_add_u32 s44, s44, 0x40080
	v_lshl_add_u64 v[152:153], v[216:217], 0, s[16:17]
	s_addc_u32 s45, s45, 0
	s_add_i32 s46, s56, s6
	global_load_lds_dwordx4 v[152:153], off
	v_lshl_add_u64 v[152:153], s[44:45], 0, v[130:131]
	s_mov_b32 m0, s46
	s_nop 0
	global_load_lds_dwordx4 v[152:153], off
	v_lshl_add_u64 v[152:153], s[44:45], 0, v[134:135]
	s_add_i32 m0, s46, 0x2000
	s_nop 0
	global_load_lds_dwordx4 v[152:153], off
	v_lshl_add_u64 v[152:153], v[218:219], 0, s[16:17]
	s_mov_b32 m0, s37
	s_nop 0
	global_load_lds_dwordx4 v[152:153], off
	v_lshl_add_u64 v[152:153], v[220:221], 0, s[16:17]
	s_mov_b32 m0, s38
	s_nop 0
	global_load_lds_dwordx4 v[152:153], off
	s_waitcnt vmcnt(8)
	s_waitcnt lgkmcnt(0)
	s_barrier
	s_setprio 1
	s_waitcnt lgkmcnt(0)
	v_mfma_f32_16x16x32_bf16 v[92:95], v[144:147], v[184:187], v[92:95]
	v_mfma_f32_16x16x32_bf16 v[88:91], v[160:163], v[184:187], v[88:91]
	v_mfma_f32_16x16x32_bf16 v[84:87], v[144:147], v[192:195], v[84:87]
	v_mfma_f32_16x16x32_bf16 v[80:83], v[160:163], v[192:195], v[80:83]
	v_mfma_f32_16x16x32_bf16 v[68:71], v[144:147], v[200:203], v[68:71]
	v_mfma_f32_16x16x32_bf16 v[64:67], v[160:163], v[200:203], v[64:67]
	v_mfma_f32_16x16x32_bf16 v[56:59], v[144:147], v[208:211], v[56:59]
	v_mfma_f32_16x16x32_bf16 v[48:51], v[160:163], v[208:211], v[48:51]
	v_mfma_f32_16x16x32_bf16 v[92:95], v[148:151], v[188:191], v[92:95]
	v_mfma_f32_16x16x32_bf16 v[88:91], v[164:167], v[188:191], v[88:91]
	v_mfma_f32_16x16x32_bf16 v[84:87], v[148:151], v[196:199], v[84:87]
	v_mfma_f32_16x16x32_bf16 v[80:83], v[164:167], v[196:199], v[80:83]
	v_mfma_f32_16x16x32_bf16 v[68:71], v[148:151], v[204:207], v[68:71]
	v_mfma_f32_16x16x32_bf16 v[64:67], v[164:167], v[204:207], v[64:67]
	v_mfma_f32_16x16x32_bf16 v[56:59], v[148:151], v[212:215], v[56:59]
	v_mfma_f32_16x16x32_bf16 v[48:51], v[164:167], v[212:215], v[48:51]
	s_setprio 0
	s_setprio 1
	v_mfma_f32_16x16x32_bf16 v[28:31], v[168:171], v[184:187], v[28:31]
	v_mfma_f32_16x16x32_bf16 v[24:27], v[176:179], v[184:187], v[24:27]
	v_mfma_f32_16x16x32_bf16 v[20:23], v[168:171], v[192:195], v[20:23]
	v_mfma_f32_16x16x32_bf16 v[16:19], v[176:179], v[192:195], v[16:19]
	v_mfma_f32_16x16x32_bf16 v[12:15], v[168:171], v[200:203], v[12:15]
	v_mfma_f32_16x16x32_bf16 v[8:11], v[176:179], v[200:203], v[8:11]
	v_mfma_f32_16x16x32_bf16 v[4:7], v[168:171], v[208:211], v[4:7]
	v_mfma_f32_16x16x32_bf16 v[0:3], v[176:179], v[208:211], v[0:3]
	v_mfma_f32_16x16x32_bf16 v[28:31], v[172:175], v[188:191], v[28:31]
	v_mfma_f32_16x16x32_bf16 v[24:27], v[180:183], v[188:191], v[24:27]
	v_mfma_f32_16x16x32_bf16 v[20:23], v[172:175], v[196:199], v[20:23]
	v_mfma_f32_16x16x32_bf16 v[16:19], v[180:183], v[196:199], v[16:19]
	v_mfma_f32_16x16x32_bf16 v[12:15], v[172:175], v[204:207], v[12:15]
	v_mfma_f32_16x16x32_bf16 v[8:11], v[180:183], v[204:207], v[8:11]
	v_mfma_f32_16x16x32_bf16 v[4:7], v[172:175], v[212:215], v[4:7]
	v_mfma_f32_16x16x32_bf16 v[0:3], v[180:183], v[212:215], v[0:3]
	s_setprio 0
	s_add_i32 s54, s54, 2
	s_add_u32 s52, s52, 0x100
	s_addc_u32 s53, s53, 0
	s_add_u32 s30, s30, 0x100
	s_addc_u32 s31, s31, 0
	s_cmp_gt_u32 s54, 13
	s_barrier
	s_cbranch_scc0 .LBB0_1805
	s_and_b64 vcc, exec, s[18:19]
	s_cbranch_vccz .LBB0_1808
	s_barrier

.LBB0_1938:
	ds_read_b128 v[104:107], v233
	ds_read_b128 v[108:111], v233 offset:1024
	ds_read_b128 v[112:115], v233 offset:2048
	ds_read_b128 v[116:119], v233 offset:3072
	ds_read_b128 v[120:123], v234
	ds_read_b128 v[124:127], v234 offset:1024
	ds_read_b128 v[128:131], v234 offset:2048
	ds_read_b128 v[132:135], v234 offset:3072
	s_add_u32 s78, s28, 0xfffc0080
	s_addc_u32 s79, s29, -1
	s_cmp_eq_u32 s84, 12
	s_cselect_b32 s81, s73, s79
	s_cselect_b32 s80, s72, s78
	s_cselect_b32 s79, s71, s83
	s_cselect_b32 s78, s77, s82
	v_lshl_add_u64 v[208:209], s[28:29], 0, v[186:187]
	s_add_i32 m0, s42, 0xc000
	ds_read_b128 v[160:163], v235
	ds_read_b128 v[164:167], v235 offset:1024
	ds_read_b128 v[168:171], v235 offset:2048
	ds_read_b128 v[172:175], v235 offset:3072
	ds_read_b128 v[192:195], v235 offset:4096
	ds_read_b128 v[196:199], v235 offset:5120
	ds_read_b128 v[200:203], v235 offset:6144
	ds_read_b128 v[204:207], v235 offset:7168
	global_load_lds_dwordx4 v[208:209], off
	v_lshl_add_u64 v[208:209], s[28:29], 0, v[184:185]
	s_add_i32 m0, s42, 0xe000
	s_nop 0
	global_load_lds_dwordx4 v[208:209], off
	s_waitcnt vmcnt(8)
	s_waitcnt lgkmcnt(0)
	s_barrier
	s_setprio 1
	s_waitcnt lgkmcnt(0)
	v_mfma_f32_16x16x32_bf16 v[156:159], v[104:107], v[160:163], v[156:159]
	v_mfma_f32_16x16x32_bf16 v[60:63], v[112:115], v[160:163], v[60:63]
	v_mfma_f32_16x16x32_bf16 v[148:151], v[104:107], v[168:171], v[148:151]
	v_mfma_f32_16x16x32_bf16 v[52:55], v[112:115], v[168:171], v[52:55]
	v_mfma_f32_16x16x32_bf16 v[140:143], v[104:107], v[192:195], v[140:143]
	v_mfma_f32_16x16x32_bf16 v[44:47], v[112:115], v[192:195], v[44:47]
	v_mfma_f32_16x16x32_bf16 v[100:103], v[104:107], v[200:203], v[100:103]
	v_mfma_f32_16x16x32_bf16 v[36:39], v[112:115], v[200:203], v[36:39]
	v_mfma_f32_16x16x32_bf16 v[156:159], v[108:111], v[164:167], v[156:159]
	v_mfma_f32_16x16x32_bf16 v[60:63], v[116:119], v[164:167], v[60:63]
	v_mfma_f32_16x16x32_bf16 v[148:151], v[108:111], v[172:175], v[148:151]
	v_mfma_f32_16x16x32_bf16 v[52:55], v[116:119], v[172:175], v[52:55]
	v_mfma_f32_16x16x32_bf16 v[140:143], v[108:111], v[196:199], v[140:143]
	v_mfma_f32_16x16x32_bf16 v[44:47], v[116:119], v[196:199], v[44:47]
	v_mfma_f32_16x16x32_bf16 v[100:103], v[108:111], v[204:207], v[100:103]
	v_mfma_f32_16x16x32_bf16 v[36:39], v[116:119], v[204:207], v[36:39]
	s_setprio 0
	s_setprio 1
	v_mfma_f32_16x16x32_bf16 v[152:155], v[120:123], v[160:163], v[152:155]
	v_mfma_f32_16x16x32_bf16 v[56:59], v[128:131], v[160:163], v[56:59]
	v_mfma_f32_16x16x32_bf16 v[144:147], v[120:123], v[168:171], v[144:147]
	v_mfma_f32_16x16x32_bf16 v[48:51], v[128:131], v[168:171], v[48:51]
	v_mfma_f32_16x16x32_bf16 v[136:139], v[120:123], v[192:195], v[136:139]
	v_mfma_f32_16x16x32_bf16 v[40:43], v[128:131], v[192:195], v[40:43]
	v_mfma_f32_16x16x32_bf16 v[96:99], v[120:123], v[200:203], v[96:99]
	v_mfma_f32_16x16x32_bf16 v[32:35], v[128:131], v[200:203], v[32:35]
	v_mfma_f32_16x16x32_bf16 v[152:155], v[124:127], v[164:167], v[152:155]
	v_mfma_f32_16x16x32_bf16 v[56:59], v[132:135], v[164:167], v[56:59]
	v_mfma_f32_16x16x32_bf16 v[144:147], v[124:127], v[172:175], v[144:147]
	v_mfma_f32_16x16x32_bf16 v[48:51], v[132:135], v[172:175], v[48:51]
	v_mfma_f32_16x16x32_bf16 v[136:139], v[124:127], v[196:199], v[136:139]
	v_mfma_f32_16x16x32_bf16 v[40:43], v[132:135], v[196:199], v[40:43]
	v_mfma_f32_16x16x32_bf16 v[96:99], v[124:127], v[204:207], v[96:99]
	v_mfma_f32_16x16x32_bf16 v[32:35], v[132:135], v[204:207], v[32:35]
	s_setprio 0
	s_barrier
	s_add_i32 s85, s33, s41
	v_lshl_add_u64 v[208:209], s[78:79], 0, v[178:179]
	s_mov_b32 m0, s85
	ds_read_b128 v[160:163], v235 offset:16384
	ds_read_b128 v[164:167], v235 offset:17408
	ds_read_b128 v[168:171], v235 offset:18432
	ds_read_b128 v[172:175], v235 offset:19456
	ds_read_b128 v[192:195], v235 offset:20480
	ds_read_b128 v[196:199], v235 offset:21504
	ds_read_b128 v[200:203], v235 offset:22528
	ds_read_b128 v[204:207], v235 offset:23552
	global_load_lds_dwordx4 v[208:209], off
	s_add_i32 m0, s85, 0x2000
	s_add_u32 s86, s78, 0x40000
	v_lshl_add_u64 v[210:211], s[78:79], 0, v[182:183]
	s_addc_u32 s87, s79, 0
	s_add_i32 s85, s44, s41
	global_load_lds_dwordx4 v[210:211], off
	v_lshl_add_u64 v[212:213], s[86:87], 0, v[178:179]
	s_mov_b32 m0, s85
	v_lshl_add_u64 v[214:215], s[80:81], 0, v[180:181]
	global_load_lds_dwordx4 v[212:213], off
	v_lshl_add_u64 v[212:213], s[86:87], 0, v[182:183]
	s_add_i32 m0, s85, 0x2000
	s_nop 0
	global_load_lds_dwordx4 v[212:213], off
	v_lshl_add_u64 v[212:213], s[80:81], 0, v[176:177]
	s_mov_b32 m0, s42
	s_nop 0
	global_load_lds_dwordx4 v[212:213], off
	s_mov_b32 m0, s43
	s_nop 0
	global_load_lds_dwordx4 v[214:215], off
	s_waitcnt vmcnt(8)
	s_waitcnt lgkmcnt(0)
	s_barrier
	s_setprio 1
	s_waitcnt lgkmcnt(0)
	v_mfma_f32_16x16x32_bf16 v[92:95], v[104:107], v[160:163], v[92:95]
	v_mfma_f32_16x16x32_bf16 v[28:31], v[112:115], v[160:163], v[28:31]
	v_mfma_f32_16x16x32_bf16 v[84:87], v[104:107], v[168:171], v[84:87]
	v_mfma_f32_16x16x32_bf16 v[20:23], v[112:115], v[168:171], v[20:23]
	v_mfma_f32_16x16x32_bf16 v[76:79], v[104:107], v[192:195], v[76:79]
	v_mfma_f32_16x16x32_bf16 v[12:15], v[112:115], v[192:195], v[12:15]
	v_mfma_f32_16x16x32_bf16 v[68:71], v[104:107], v[200:203], v[68:71]
	v_mfma_f32_16x16x32_bf16 v[4:7], v[112:115], v[200:203], v[4:7]
	v_mfma_f32_16x16x32_bf16 v[92:95], v[108:111], v[164:167], v[92:95]
	v_mfma_f32_16x16x32_bf16 v[28:31], v[116:119], v[164:167], v[28:31]
	v_mfma_f32_16x16x32_bf16 v[84:87], v[108:111], v[172:175], v[84:87]
	v_mfma_f32_16x16x32_bf16 v[20:23], v[116:119], v[172:175], v[20:23]
	v_mfma_f32_16x16x32_bf16 v[76:79], v[108:111], v[196:199], v[76:79]
	v_mfma_f32_16x16x32_bf16 v[12:15], v[116:119], v[196:199], v[12:15]
	v_mfma_f32_16x16x32_bf16 v[68:71], v[108:111], v[204:207], v[68:71]
	v_mfma_f32_16x16x32_bf16 v[4:7], v[116:119], v[204:207], v[4:7]
	s_setprio 0
	s_setprio 1
	v_mfma_f32_16x16x32_bf16 v[88:91], v[120:123], v[160:163], v[88:91]
	v_mfma_f32_16x16x32_bf16 v[24:27], v[128:131], v[160:163], v[24:27]
	v_mfma_f32_16x16x32_bf16 v[80:83], v[120:123], v[168:171], v[80:83]
	v_mfma_f32_16x16x32_bf16 v[16:19], v[128:131], v[168:171], v[16:19]
	v_mfma_f32_16x16x32_bf16 v[72:75], v[120:123], v[192:195], v[72:75]
	v_mfma_f32_16x16x32_bf16 v[8:11], v[128:131], v[192:195], v[8:11]
	v_mfma_f32_16x16x32_bf16 v[64:67], v[120:123], v[200:203], v[64:67]
	v_mfma_f32_16x16x32_bf16 v[0:3], v[128:131], v[200:203], v[0:3]
	v_mfma_f32_16x16x32_bf16 v[88:91], v[124:127], v[164:167], v[88:91]
	v_mfma_f32_16x16x32_bf16 v[24:27], v[132:135], v[164:167], v[24:27]
	v_mfma_f32_16x16x32_bf16 v[80:83], v[124:127], v[172:175], v[80:83]
	v_mfma_f32_16x16x32_bf16 v[16:19], v[132:135], v[172:175], v[16:19]
	v_mfma_f32_16x16x32_bf16 v[72:75], v[124:127], v[196:199], v[72:75]
	v_mfma_f32_16x16x32_bf16 v[8:11], v[132:135], v[196:199], v[8:11]
	v_mfma_f32_16x16x32_bf16 v[64:67], v[124:127], v[204:207], v[64:67]
	v_mfma_f32_16x16x32_bf16 v[0:3], v[132:135], v[204:207], v[0:3]
	s_setprio 0
	s_barrier
	s_add_i32 s85, 0, 0x18000
	s_add_i32 s86, 0, 0x1c000
	v_add_u32_e32 v116, s85, v221
	v_add_u32_e32 v132, s86, v221
	ds_read_b128 v[104:107], v116
	ds_read_b128 v[108:111], v116 offset:1024
	ds_read_b128 v[112:115], v116 offset:2048
	ds_read_b128 v[116:119], v116 offset:3072
	ds_read_b128 v[120:123], v132
	ds_read_b128 v[124:127], v132 offset:1024
	ds_read_b128 v[128:131], v132 offset:2048
	ds_read_b128 v[132:135], v132 offset:3072
	s_add_u32 s80, s80, 0x40000
	s_addc_u32 s81, s81, 0
	s_mov_b32 m0, s8
	v_lshl_add_u64 v[216:217], s[80:81], 0, v[176:177]
	ds_read_b128 v[160:163], v235 offset:32768
	ds_read_b128 v[164:167], v235 offset:33792
	ds_read_b128 v[168:171], v235 offset:34816
	ds_read_b128 v[172:175], v235 offset:35840
	ds_read_b128 v[192:195], v235 offset:36864
	ds_read_b128 v[196:199], v235 offset:37888
	ds_read_b128 v[200:203], v235 offset:38912
	ds_read_b128 v[204:207], v235 offset:39936
	global_load_lds_dwordx4 v[216:217], off
	v_lshl_add_u64 v[216:217], s[80:81], 0, v[180:181]
	s_mov_b32 m0, s9
	s_nop 0
	global_load_lds_dwordx4 v[216:217], off
	s_waitcnt vmcnt(8)
	s_waitcnt lgkmcnt(0)
	s_barrier
	s_setprio 1
	s_waitcnt lgkmcnt(0)
	v_mfma_f32_16x16x32_bf16 v[156:159], v[104:107], v[160:163], v[156:159]
	v_mfma_f32_16x16x32_bf16 v[60:63], v[112:115], v[160:163], v[60:63]
	v_mfma_f32_16x16x32_bf16 v[148:151], v[104:107], v[168:171], v[148:151]
	v_mfma_f32_16x16x32_bf16 v[52:55], v[112:115], v[168:171], v[52:55]
	v_mfma_f32_16x16x32_bf16 v[140:143], v[104:107], v[192:195], v[140:143]
	v_mfma_f32_16x16x32_bf16 v[44:47], v[112:115], v[192:195], v[44:47]
	v_mfma_f32_16x16x32_bf16 v[100:103], v[104:107], v[200:203], v[100:103]
	v_mfma_f32_16x16x32_bf16 v[36:39], v[112:115], v[200:203], v[36:39]
	v_mfma_f32_16x16x32_bf16 v[156:159], v[108:111], v[164:167], v[156:159]
	v_mfma_f32_16x16x32_bf16 v[60:63], v[116:119], v[164:167], v[60:63]
	v_mfma_f32_16x16x32_bf16 v[148:151], v[108:111], v[172:175], v[148:151]
	v_mfma_f32_16x16x32_bf16 v[52:55], v[116:119], v[172:175], v[52:55]
	v_mfma_f32_16x16x32_bf16 v[140:143], v[108:111], v[196:199], v[140:143]
	v_mfma_f32_16x16x32_bf16 v[44:47], v[116:119], v[196:199], v[44:47]
	v_mfma_f32_16x16x32_bf16 v[100:103], v[108:111], v[204:207], v[100:103]
	v_mfma_f32_16x16x32_bf16 v[36:39], v[116:119], v[204:207], v[36:39]
	s_setprio 0
	s_setprio 1
	v_mfma_f32_16x16x32_bf16 v[152:155], v[120:123], v[160:163], v[152:155]
	v_mfma_f32_16x16x32_bf16 v[56:59], v[128:131], v[160:163], v[56:59]
	v_mfma_f32_16x16x32_bf16 v[144:147], v[120:123], v[168:171], v[144:147]
	v_mfma_f32_16x16x32_bf16 v[48:51], v[128:131], v[168:171], v[48:51]
	v_mfma_f32_16x16x32_bf16 v[136:139], v[120:123], v[192:195], v[136:139]
	v_mfma_f32_16x16x32_bf16 v[40:43], v[128:131], v[192:195], v[40:43]
	v_mfma_f32_16x16x32_bf16 v[96:99], v[120:123], v[200:203], v[96:99]
	v_mfma_f32_16x16x32_bf16 v[32:35], v[128:131], v[200:203], v[32:35]
	v_mfma_f32_16x16x32_bf16 v[152:155], v[124:127], v[164:167], v[152:155]
	v_mfma_f32_16x16x32_bf16 v[56:59], v[132:135], v[164:167], v[56:59]
	v_mfma_f32_16x16x32_bf16 v[144:147], v[124:127], v[172:175], v[144:147]
	v_mfma_f32_16x16x32_bf16 v[48:51], v[132:135], v[172:175], v[48:51]
	v_mfma_f32_16x16x32_bf16 v[136:139], v[124:127], v[196:199], v[136:139]
	v_mfma_f32_16x16x32_bf16 v[40:43], v[132:135], v[196:199], v[40:43]
	v_mfma_f32_16x16x32_bf16 v[96:99], v[124:127], v[204:207], v[96:99]
	v_mfma_f32_16x16x32_bf16 v[32:35], v[132:135], v[204:207], v[32:35]
	s_setprio 0
	s_barrier
	s_add_i32 s80, s85, s41
	v_lshl_add_u64 v[208:209], v[208:209], 0, s[52:53]
	s_mov_b32 m0, s80
	ds_read_b128 v[160:163], v235 offset:49152
	ds_read_b128 v[164:167], v235 offset:50176
	ds_read_b128 v[168:171], v235 offset:51200
	ds_read_b128 v[172:175], v235 offset:52224
	ds_read_b128 v[192:195], v235 offset:53248
	ds_read_b128 v[196:199], v235 offset:54272
	ds_read_b128 v[200:203], v235 offset:55296
	ds_read_b128 v[204:207], v235 offset:56320
	global_load_lds_dwordx4 v[208:209], off
	s_add_i32 m0, s80, 0x2000
	s_add_u32 s78, s78, 0x40080
	v_lshl_add_u64 v[208:209], v[210:211], 0, s[52:53]
	s_addc_u32 s79, s79, 0
	s_add_i32 s80, s86, s41
	global_load_lds_dwordx4 v[208:209], off
	v_lshl_add_u64 v[208:209], s[78:79], 0, v[178:179]
	s_mov_b32 m0, s80
	s_nop 0
	global_load_lds_dwordx4 v[208:209], off
	v_lshl_add_u64 v[208:209], s[78:79], 0, v[182:183]
	s_add_i32 m0, s80, 0x2000
	s_nop 0
	global_load_lds_dwordx4 v[208:209], off
	v_lshl_add_u64 v[208:209], v[212:213], 0, s[52:53]
	s_mov_b32 m0, s5
	s_nop 0
	global_load_lds_dwordx4 v[208:209], off
	v_lshl_add_u64 v[208:209], v[214:215], 0, s[52:53]
	s_mov_b32 m0, s6
	s_nop 0
	global_load_lds_dwordx4 v[208:209], off
	s_waitcnt vmcnt(8)
	s_waitcnt lgkmcnt(0)
	s_barrier
	s_setprio 1
	s_waitcnt lgkmcnt(0)
	v_mfma_f32_16x16x32_bf16 v[92:95], v[104:107], v[160:163], v[92:95]
	v_mfma_f32_16x16x32_bf16 v[28:31], v[112:115], v[160:163], v[28:31]
	v_mfma_f32_16x16x32_bf16 v[84:87], v[104:107], v[168:171], v[84:87]
	v_mfma_f32_16x16x32_bf16 v[20:23], v[112:115], v[168:171], v[20:23]
	v_mfma_f32_16x16x32_bf16 v[76:79], v[104:107], v[192:195], v[76:79]
	v_mfma_f32_16x16x32_bf16 v[12:15], v[112:115], v[192:195], v[12:15]
	v_mfma_f32_16x16x32_bf16 v[68:71], v[104:107], v[200:203], v[68:71]
	v_mfma_f32_16x16x32_bf16 v[4:7], v[112:115], v[200:203], v[4:7]
	v_mfma_f32_16x16x32_bf16 v[92:95], v[108:111], v[164:167], v[92:95]
	v_mfma_f32_16x16x32_bf16 v[28:31], v[116:119], v[164:167], v[28:31]
	v_mfma_f32_16x16x32_bf16 v[84:87], v[108:111], v[172:175], v[84:87]
	v_mfma_f32_16x16x32_bf16 v[20:23], v[116:119], v[172:175], v[20:23]
	v_mfma_f32_16x16x32_bf16 v[76:79], v[108:111], v[196:199], v[76:79]
	v_mfma_f32_16x16x32_bf16 v[12:15], v[116:119], v[196:199], v[12:15]
	v_mfma_f32_16x16x32_bf16 v[68:71], v[108:111], v[204:207], v[68:71]
	v_mfma_f32_16x16x32_bf16 v[4:7], v[116:119], v[204:207], v[4:7]
	s_setprio 0
	s_setprio 1
	v_mfma_f32_16x16x32_bf16 v[88:91], v[120:123], v[160:163], v[88:91]
	v_mfma_f32_16x16x32_bf16 v[24:27], v[128:131], v[160:163], v[24:27]
	v_mfma_f32_16x16x32_bf16 v[80:83], v[120:123], v[168:171], v[80:83]
	v_mfma_f32_16x16x32_bf16 v[16:19], v[128:131], v[168:171], v[16:19]
	v_mfma_f32_16x16x32_bf16 v[72:75], v[120:123], v[192:195], v[72:75]
	v_mfma_f32_16x16x32_bf16 v[8:11], v[128:131], v[192:195], v[8:11]
	v_mfma_f32_16x16x32_bf16 v[64:67], v[120:123], v[200:203], v[64:67]
	v_mfma_f32_16x16x32_bf16 v[0:3], v[128:131], v[200:203], v[0:3]
	v_mfma_f32_16x16x32_bf16 v[88:91], v[124:127], v[164:167], v[88:91]
	v_mfma_f32_16x16x32_bf16 v[24:27], v[132:135], v[164:167], v[24:27]
	v_mfma_f32_16x16x32_bf16 v[80:83], v[124:127], v[172:175], v[80:83]
	v_mfma_f32_16x16x32_bf16 v[16:19], v[132:135], v[172:175], v[16:19]
	v_mfma_f32_16x16x32_bf16 v[72:75], v[124:127], v[196:199], v[72:75]
	v_mfma_f32_16x16x32_bf16 v[8:11], v[132:135], v[196:199], v[8:11]
	v_mfma_f32_16x16x32_bf16 v[64:67], v[124:127], v[204:207], v[64:67]
	v_mfma_f32_16x16x32_bf16 v[0:3], v[132:135], v[204:207], v[0:3]
	s_setprio 0
	s_add_i32 s84, s84, 2
	s_add_u32 s82, s82, 0x100
	s_addc_u32 s83, s83, 0
	s_add_u32 s28, s28, 0x100
	s_addc_u32 s29, s29, 0
	s_cmp_gt_u32 s84, 13
	s_barrier
	s_cbranch_scc0 .LBB0_1938
	s_and_b64 vcc, exec, s[54:55]
	s_cbranch_vccz .LBB0_1941
	s_barrier

.LBB0_2337:
	ds_read_b128 v[152:155], v149
	ds_read_b128 v[156:159], v149 offset:1024
	ds_read_b128 v[160:163], v149 offset:2048
	ds_read_b128 v[164:167], v149 offset:3072
	ds_read_b128 v[168:171], v150
	ds_read_b128 v[172:175], v150 offset:1024
	ds_read_b128 v[176:179], v150 offset:2048
	ds_read_b128 v[180:183], v150 offset:3072
	s_add_u32 s42, s30, 0xfffc0080
	s_addc_u32 s43, s31, -1
	s_cmp_eq_u32 s53, 12
	s_cselect_b32 s45, s23, s43
	s_cselect_b32 s44, s49, s42
	s_cselect_b32 s43, s21, s52
	s_cselect_b32 s42, s50, s51
	v_lshl_add_u64 v[144:145], s[30:31], 0, v[138:139]
	s_add_i32 m0, s8, 0xc000
	ds_read_b128 v[184:187], v151
	ds_read_b128 v[188:191], v151 offset:1024
	ds_read_b128 v[192:195], v151 offset:2048
	ds_read_b128 v[196:199], v151 offset:3072
	ds_read_b128 v[200:203], v151 offset:4096
	ds_read_b128 v[204:207], v151 offset:5120
	ds_read_b128 v[208:211], v151 offset:6144
	ds_read_b128 v[212:215], v151 offset:7168
	global_load_lds_dwordx4 v[144:145], off
	v_lshl_add_u64 v[144:145], s[30:31], 0, v[136:137]
	s_add_i32 m0, s8, 0xe000
	s_nop 0
	global_load_lds_dwordx4 v[144:145], off
	s_waitcnt vmcnt(8)
	s_waitcnt lgkmcnt(0)
	s_barrier
	s_setprio 1
	s_waitcnt lgkmcnt(0)
	v_mfma_f32_16x16x32_bf16 v[124:127], v[152:155], v[184:187], v[124:127]
	v_mfma_f32_16x16x32_bf16 v[120:123], v[160:163], v[184:187], v[120:123]
	v_mfma_f32_16x16x32_bf16 v[116:119], v[152:155], v[192:195], v[116:119]
	v_mfma_f32_16x16x32_bf16 v[112:115], v[160:163], v[192:195], v[112:115]
	v_mfma_f32_16x16x32_bf16 v[108:111], v[152:155], v[200:203], v[108:111]
	v_mfma_f32_16x16x32_bf16 v[104:107], v[160:163], v[200:203], v[104:107]
	v_mfma_f32_16x16x32_bf16 v[100:103], v[152:155], v[208:211], v[100:103]
	v_mfma_f32_16x16x32_bf16 v[96:99], v[160:163], v[208:211], v[96:99]
	v_mfma_f32_16x16x32_bf16 v[124:127], v[156:159], v[188:191], v[124:127]
	v_mfma_f32_16x16x32_bf16 v[120:123], v[164:167], v[188:191], v[120:123]
	v_mfma_f32_16x16x32_bf16 v[116:119], v[156:159], v[196:199], v[116:119]
	v_mfma_f32_16x16x32_bf16 v[112:115], v[164:167], v[196:199], v[112:115]
	v_mfma_f32_16x16x32_bf16 v[108:111], v[156:159], v[204:207], v[108:111]
	v_mfma_f32_16x16x32_bf16 v[104:107], v[164:167], v[204:207], v[104:107]
	v_mfma_f32_16x16x32_bf16 v[100:103], v[156:159], v[212:215], v[100:103]
	v_mfma_f32_16x16x32_bf16 v[96:99], v[164:167], v[212:215], v[96:99]
	s_setprio 0
	s_setprio 1
	v_mfma_f32_16x16x32_bf16 v[80:83], v[168:171], v[184:187], v[80:83]
	v_mfma_f32_16x16x32_bf16 v[72:75], v[176:179], v[184:187], v[72:75]
	v_mfma_f32_16x16x32_bf16 v[60:63], v[168:171], v[192:195], v[60:63]
	v_mfma_f32_16x16x32_bf16 v[56:59], v[176:179], v[192:195], v[56:59]
	v_mfma_f32_16x16x32_bf16 v[44:47], v[168:171], v[200:203], v[44:47]
	v_mfma_f32_16x16x32_bf16 v[40:43], v[176:179], v[200:203], v[40:43]
	v_mfma_f32_16x16x32_bf16 v[36:39], v[168:171], v[208:211], v[36:39]
	v_mfma_f32_16x16x32_bf16 v[32:35], v[176:179], v[208:211], v[32:35]
	v_mfma_f32_16x16x32_bf16 v[80:83], v[172:175], v[188:191], v[80:83]
	v_mfma_f32_16x16x32_bf16 v[72:75], v[180:183], v[188:191], v[72:75]
	v_mfma_f32_16x16x32_bf16 v[60:63], v[172:175], v[196:199], v[60:63]
	v_mfma_f32_16x16x32_bf16 v[56:59], v[180:183], v[196:199], v[56:59]
	v_mfma_f32_16x16x32_bf16 v[44:47], v[172:175], v[204:207], v[44:47]
	v_mfma_f32_16x16x32_bf16 v[40:43], v[180:183], v[204:207], v[40:43]
	v_mfma_f32_16x16x32_bf16 v[36:39], v[172:175], v[212:215], v[36:39]
	v_mfma_f32_16x16x32_bf16 v[32:35], v[180:183], v[212:215], v[32:35]
	s_setprio 0
	s_barrier
	s_add_i32 s54, s41, s5
	v_lshl_add_u64 v[144:145], s[42:43], 0, v[132:133]
	s_mov_b32 m0, s54
	ds_read_b128 v[184:187], v151 offset:16384
	ds_read_b128 v[188:191], v151 offset:17408
	ds_read_b128 v[192:195], v151 offset:18432
	ds_read_b128 v[196:199], v151 offset:19456
	ds_read_b128 v[200:203], v151 offset:20480
	ds_read_b128 v[204:207], v151 offset:21504
	ds_read_b128 v[208:211], v151 offset:22528
	ds_read_b128 v[212:215], v151 offset:23552
	global_load_lds_dwordx4 v[144:145], off
	s_add_i32 m0, s54, 0x2000
	s_add_u32 s54, s42, 0x40000
	v_lshl_add_u64 v[216:217], s[42:43], 0, v[128:129]
	s_addc_u32 s55, s43, 0
	s_add_i32 s56, s46, s5
	global_load_lds_dwordx4 v[216:217], off
	v_lshl_add_u64 v[218:219], s[54:55], 0, v[132:133]
	s_mov_b32 m0, s56
	v_lshl_add_u64 v[220:221], s[44:45], 0, v[130:131]
	global_load_lds_dwordx4 v[218:219], off
	v_lshl_add_u64 v[218:219], s[54:55], 0, v[128:129]
	s_add_i32 m0, s56, 0x2000
	s_nop 0
	global_load_lds_dwordx4 v[218:219], off
	v_lshl_add_u64 v[218:219], s[44:45], 0, v[134:135]
	s_mov_b32 m0, s8
	s_nop 0
	global_load_lds_dwordx4 v[218:219], off
	s_mov_b32 m0, s9
	s_nop 0
	global_load_lds_dwordx4 v[220:221], off
	s_waitcnt vmcnt(8)
	s_waitcnt lgkmcnt(0)
	s_barrier
	s_setprio 1
	s_waitcnt lgkmcnt(0)
	v_mfma_f32_16x16x32_bf16 v[92:95], v[152:155], v[184:187], v[92:95]
	v_mfma_f32_16x16x32_bf16 v[88:91], v[160:163], v[184:187], v[88:91]
	v_mfma_f32_16x16x32_bf16 v[84:87], v[152:155], v[192:195], v[84:87]
	v_mfma_f32_16x16x32_bf16 v[76:79], v[160:163], v[192:195], v[76:79]
	v_mfma_f32_16x16x32_bf16 v[68:71], v[152:155], v[200:203], v[68:71]
	v_mfma_f32_16x16x32_bf16 v[64:67], v[160:163], v[200:203], v[64:67]
	v_mfma_f32_16x16x32_bf16 v[52:55], v[152:155], v[208:211], v[52:55]
	v_mfma_f32_16x16x32_bf16 v[48:51], v[160:163], v[208:211], v[48:51]
	v_mfma_f32_16x16x32_bf16 v[92:95], v[156:159], v[188:191], v[92:95]
	v_mfma_f32_16x16x32_bf16 v[88:91], v[164:167], v[188:191], v[88:91]
	v_mfma_f32_16x16x32_bf16 v[84:87], v[156:159], v[196:199], v[84:87]
	v_mfma_f32_16x16x32_bf16 v[76:79], v[164:167], v[196:199], v[76:79]
	v_mfma_f32_16x16x32_bf16 v[68:71], v[156:159], v[204:207], v[68:71]
	v_mfma_f32_16x16x32_bf16 v[64:67], v[164:167], v[204:207], v[64:67]
	v_mfma_f32_16x16x32_bf16 v[52:55], v[156:159], v[212:215], v[52:55]
	v_mfma_f32_16x16x32_bf16 v[48:51], v[164:167], v[212:215], v[48:51]
	s_setprio 0
	s_setprio 1
	v_mfma_f32_16x16x32_bf16 v[28:31], v[168:171], v[184:187], v[28:31]
	v_mfma_f32_16x16x32_bf16 v[24:27], v[176:179], v[184:187], v[24:27]
	v_mfma_f32_16x16x32_bf16 v[20:23], v[168:171], v[192:195], v[20:23]
	v_mfma_f32_16x16x32_bf16 v[16:19], v[176:179], v[192:195], v[16:19]
	v_mfma_f32_16x16x32_bf16 v[12:15], v[168:171], v[200:203], v[12:15]
	v_mfma_f32_16x16x32_bf16 v[8:11], v[176:179], v[200:203], v[8:11]
	v_mfma_f32_16x16x32_bf16 v[4:7], v[168:171], v[208:211], v[4:7]
	v_mfma_f32_16x16x32_bf16 v[0:3], v[176:179], v[208:211], v[0:3]
	v_mfma_f32_16x16x32_bf16 v[28:31], v[172:175], v[188:191], v[28:31]
	v_mfma_f32_16x16x32_bf16 v[24:27], v[180:183], v[188:191], v[24:27]
	v_mfma_f32_16x16x32_bf16 v[20:23], v[172:175], v[196:199], v[20:23]
	v_mfma_f32_16x16x32_bf16 v[16:19], v[180:183], v[196:199], v[16:19]
	v_mfma_f32_16x16x32_bf16 v[12:15], v[172:175], v[204:207], v[12:15]
	v_mfma_f32_16x16x32_bf16 v[8:11], v[180:183], v[204:207], v[8:11]
	v_mfma_f32_16x16x32_bf16 v[4:7], v[172:175], v[212:215], v[4:7]
	v_mfma_f32_16x16x32_bf16 v[0:3], v[180:183], v[212:215], v[0:3]
	s_setprio 0
	s_barrier
	s_add_i32 s54, 0, 0x18000
	s_add_i32 s55, 0, 0x1c000
	v_add_u32_e32 v164, s54, v147
	v_add_u32_e32 v180, s55, v147
	ds_read_b128 v[152:155], v164
	ds_read_b128 v[156:159], v164 offset:1024
	ds_read_b128 v[160:163], v164 offset:2048
	ds_read_b128 v[164:167], v164 offset:3072
	ds_read_b128 v[168:171], v180
	ds_read_b128 v[172:175], v180 offset:1024
	ds_read_b128 v[176:179], v180 offset:2048
	ds_read_b128 v[180:183], v180 offset:3072
	s_add_u32 s44, s44, 0x40000
	s_addc_u32 s45, s45, 0
	s_mov_b32 m0, s33
	v_lshl_add_u64 v[222:223], s[44:45], 0, v[134:135]
	ds_read_b128 v[184:187], v151 offset:32768
	ds_read_b128 v[188:191], v151 offset:33792
	ds_read_b128 v[192:195], v151 offset:34816
	ds_read_b128 v[196:199], v151 offset:35840
	ds_read_b128 v[200:203], v151 offset:36864
	ds_read_b128 v[204:207], v151 offset:37888
	ds_read_b128 v[208:211], v151 offset:38912
	ds_read_b128 v[212:215], v151 offset:39936
	global_load_lds_dwordx4 v[222:223], off
	v_lshl_add_u64 v[222:223], s[44:45], 0, v[130:131]
	s_mov_b32 m0, s35
	s_nop 0
	global_load_lds_dwordx4 v[222:223], off
	s_waitcnt vmcnt(8)
	s_waitcnt lgkmcnt(0)
	s_barrier
	s_setprio 1
	s_waitcnt lgkmcnt(0)
	v_mfma_f32_16x16x32_bf16 v[124:127], v[152:155], v[184:187], v[124:127]
	v_mfma_f32_16x16x32_bf16 v[120:123], v[160:163], v[184:187], v[120:123]
	v_mfma_f32_16x16x32_bf16 v[116:119], v[152:155], v[192:195], v[116:119]
	v_mfma_f32_16x16x32_bf16 v[112:115], v[160:163], v[192:195], v[112:115]
	v_mfma_f32_16x16x32_bf16 v[108:111], v[152:155], v[200:203], v[108:111]
	v_mfma_f32_16x16x32_bf16 v[104:107], v[160:163], v[200:203], v[104:107]
	v_mfma_f32_16x16x32_bf16 v[100:103], v[152:155], v[208:211], v[100:103]
	v_mfma_f32_16x16x32_bf16 v[96:99], v[160:163], v[208:211], v[96:99]
	v_mfma_f32_16x16x32_bf16 v[124:127], v[156:159], v[188:191], v[124:127]
	v_mfma_f32_16x16x32_bf16 v[120:123], v[164:167], v[188:191], v[120:123]
	v_mfma_f32_16x16x32_bf16 v[116:119], v[156:159], v[196:199], v[116:119]
	v_mfma_f32_16x16x32_bf16 v[112:115], v[164:167], v[196:199], v[112:115]
	v_mfma_f32_16x16x32_bf16 v[108:111], v[156:159], v[204:207], v[108:111]
	v_mfma_f32_16x16x32_bf16 v[104:107], v[164:167], v[204:207], v[104:107]
	v_mfma_f32_16x16x32_bf16 v[100:103], v[156:159], v[212:215], v[100:103]
	v_mfma_f32_16x16x32_bf16 v[96:99], v[164:167], v[212:215], v[96:99]
	s_setprio 0
	s_setprio 1
	v_mfma_f32_16x16x32_bf16 v[80:83], v[168:171], v[184:187], v[80:83]
	v_mfma_f32_16x16x32_bf16 v[72:75], v[176:179], v[184:187], v[72:75]
	v_mfma_f32_16x16x32_bf16 v[60:63], v[168:171], v[192:195], v[60:63]
	v_mfma_f32_16x16x32_bf16 v[56:59], v[176:179], v[192:195], v[56:59]
	v_mfma_f32_16x16x32_bf16 v[44:47], v[168:171], v[200:203], v[44:47]
	v_mfma_f32_16x16x32_bf16 v[40:43], v[176:179], v[200:203], v[40:43]
	v_mfma_f32_16x16x32_bf16 v[36:39], v[168:171], v[208:211], v[36:39]
	v_mfma_f32_16x16x32_bf16 v[32:35], v[176:179], v[208:211], v[32:35]
	v_mfma_f32_16x16x32_bf16 v[80:83], v[172:175], v[188:191], v[80:83]
	v_mfma_f32_16x16x32_bf16 v[72:75], v[180:183], v[188:191], v[72:75]
	v_mfma_f32_16x16x32_bf16 v[60:63], v[172:175], v[196:199], v[60:63]
	v_mfma_f32_16x16x32_bf16 v[56:59], v[180:183], v[196:199], v[56:59]
	v_mfma_f32_16x16x32_bf16 v[44:47], v[172:175], v[204:207], v[44:47]
	v_mfma_f32_16x16x32_bf16 v[40:43], v[180:183], v[204:207], v[40:43]
	v_mfma_f32_16x16x32_bf16 v[36:39], v[172:175], v[212:215], v[36:39]
	v_mfma_f32_16x16x32_bf16 v[32:35], v[180:183], v[212:215], v[32:35]
	s_setprio 0
	s_barrier
	s_add_i32 s44, s54, s5
	v_lshl_add_u64 v[144:145], v[144:145], 0, s[16:17]
	s_mov_b32 m0, s44
	ds_read_b128 v[184:187], v151 offset:49152
	ds_read_b128 v[188:191], v151 offset:50176
	ds_read_b128 v[192:195], v151 offset:51200
	ds_read_b128 v[196:199], v151 offset:52224
	ds_read_b128 v[200:203], v151 offset:53248
	ds_read_b128 v[204:207], v151 offset:54272
	ds_read_b128 v[208:211], v151 offset:55296
	ds_read_b128 v[212:215], v151 offset:56320
	global_load_lds_dwordx4 v[144:145], off
	s_add_i32 m0, s44, 0x2000
	s_add_u32 s42, s42, 0x40080
	v_lshl_add_u64 v[144:145], v[216:217], 0, s[16:17]
	s_addc_u32 s43, s43, 0
	s_add_i32 s44, s55, s5
	global_load_lds_dwordx4 v[144:145], off
	v_lshl_add_u64 v[144:145], s[42:43], 0, v[132:133]
	s_mov_b32 m0, s44
	s_nop 0
	global_load_lds_dwordx4 v[144:145], off
	v_lshl_add_u64 v[144:145], s[42:43], 0, v[128:129]
	s_add_i32 m0, s44, 0x2000
	s_nop 0
	global_load_lds_dwordx4 v[144:145], off
	v_lshl_add_u64 v[144:145], v[218:219], 0, s[16:17]
	s_mov_b32 m0, s37
	s_nop 0
	global_load_lds_dwordx4 v[144:145], off
	v_lshl_add_u64 v[144:145], v[220:221], 0, s[16:17]
	s_mov_b32 m0, s38
	s_nop 0
	global_load_lds_dwordx4 v[144:145], off
	s_waitcnt vmcnt(8)
	s_waitcnt lgkmcnt(0)
	s_barrier
	s_setprio 1
	s_waitcnt lgkmcnt(0)
	v_mfma_f32_16x16x32_bf16 v[92:95], v[152:155], v[184:187], v[92:95]
	v_mfma_f32_16x16x32_bf16 v[88:91], v[160:163], v[184:187], v[88:91]
	v_mfma_f32_16x16x32_bf16 v[84:87], v[152:155], v[192:195], v[84:87]
	v_mfma_f32_16x16x32_bf16 v[76:79], v[160:163], v[192:195], v[76:79]
	v_mfma_f32_16x16x32_bf16 v[68:71], v[152:155], v[200:203], v[68:71]
	v_mfma_f32_16x16x32_bf16 v[64:67], v[160:163], v[200:203], v[64:67]
	v_mfma_f32_16x16x32_bf16 v[52:55], v[152:155], v[208:211], v[52:55]
	v_mfma_f32_16x16x32_bf16 v[48:51], v[160:163], v[208:211], v[48:51]
	v_mfma_f32_16x16x32_bf16 v[92:95], v[156:159], v[188:191], v[92:95]
	v_mfma_f32_16x16x32_bf16 v[88:91], v[164:167], v[188:191], v[88:91]
	v_mfma_f32_16x16x32_bf16 v[84:87], v[156:159], v[196:199], v[84:87]
	v_mfma_f32_16x16x32_bf16 v[76:79], v[164:167], v[196:199], v[76:79]
	v_mfma_f32_16x16x32_bf16 v[68:71], v[156:159], v[204:207], v[68:71]
	v_mfma_f32_16x16x32_bf16 v[64:67], v[164:167], v[204:207], v[64:67]
	v_mfma_f32_16x16x32_bf16 v[52:55], v[156:159], v[212:215], v[52:55]
	v_mfma_f32_16x16x32_bf16 v[48:51], v[164:167], v[212:215], v[48:51]
	s_setprio 0
	s_setprio 1
	v_mfma_f32_16x16x32_bf16 v[28:31], v[168:171], v[184:187], v[28:31]
	v_mfma_f32_16x16x32_bf16 v[24:27], v[176:179], v[184:187], v[24:27]
	v_mfma_f32_16x16x32_bf16 v[20:23], v[168:171], v[192:195], v[20:23]
	v_mfma_f32_16x16x32_bf16 v[16:19], v[176:179], v[192:195], v[16:19]
	v_mfma_f32_16x16x32_bf16 v[12:15], v[168:171], v[200:203], v[12:15]
	v_mfma_f32_16x16x32_bf16 v[8:11], v[176:179], v[200:203], v[8:11]
	v_mfma_f32_16x16x32_bf16 v[4:7], v[168:171], v[208:211], v[4:7]
	v_mfma_f32_16x16x32_bf16 v[0:3], v[176:179], v[208:211], v[0:3]
	v_mfma_f32_16x16x32_bf16 v[28:31], v[172:175], v[188:191], v[28:31]
	v_mfma_f32_16x16x32_bf16 v[24:27], v[180:183], v[188:191], v[24:27]
	v_mfma_f32_16x16x32_bf16 v[20:23], v[172:175], v[196:199], v[20:23]
	v_mfma_f32_16x16x32_bf16 v[16:19], v[180:183], v[196:199], v[16:19]
	v_mfma_f32_16x16x32_bf16 v[12:15], v[172:175], v[204:207], v[12:15]
	v_mfma_f32_16x16x32_bf16 v[8:11], v[180:183], v[204:207], v[8:11]
	v_mfma_f32_16x16x32_bf16 v[4:7], v[172:175], v[212:215], v[4:7]
	v_mfma_f32_16x16x32_bf16 v[0:3], v[180:183], v[212:215], v[0:3]
	s_setprio 0
	s_add_i32 s53, s53, 2
	s_add_u32 s51, s51, 0x100
	s_addc_u32 s52, s52, 0
	s_add_u32 s30, s30, 0x100
	s_addc_u32 s31, s31, 0
	s_cmp_gt_u32 s53, 13
	s_barrier
	s_cbranch_scc0 .LBB0_2337
	s_and_b64 vcc, exec, s[18:19]
	s_cbranch_vccz .LBB0_2340
	s_barrier

.LBB0_3217:
	ds_read_b128 v[144:147], v157
	ds_read_b128 v[148:151], v157 offset:1024
	ds_read_b128 v[160:163], v157 offset:2048
	ds_read_b128 v[164:167], v157 offset:3072
	ds_read_b128 v[168:171], v158
	ds_read_b128 v[172:175], v158 offset:1024
	ds_read_b128 v[176:179], v158 offset:2048
	ds_read_b128 v[180:183], v158 offset:3072
	s_add_u32 s40, s30, 0xfffc0080
	s_addc_u32 s41, s31, -1
	s_cmp_eq_u32 s54, 12
	s_cselect_b32 s43, s23, s41
	s_cselect_b32 s42, s50, s40
	s_cselect_b32 s41, s21, s53
	s_cselect_b32 s40, s51, s52
	v_lshl_add_u64 v[152:153], s[30:31], 0, v[138:139]
	s_add_i32 m0, s7, 0xc000
	ds_read_b128 v[184:187], v159
	ds_read_b128 v[188:191], v159 offset:1024
	ds_read_b128 v[192:195], v159 offset:2048
	ds_read_b128 v[196:199], v159 offset:3072
	ds_read_b128 v[200:203], v159 offset:4096
	ds_read_b128 v[204:207], v159 offset:5120
	ds_read_b128 v[208:211], v159 offset:6144
	ds_read_b128 v[212:215], v159 offset:7168
	global_load_lds_dwordx4 v[152:153], off
	v_lshl_add_u64 v[152:153], s[30:31], 0, v[136:137]
	s_add_i32 m0, s7, 0xe000
	s_nop 0
	global_load_lds_dwordx4 v[152:153], off
	s_waitcnt vmcnt(8)
	s_waitcnt lgkmcnt(0)
	s_barrier
	s_setprio 1
	s_waitcnt lgkmcnt(0)
	v_mfma_f32_16x16x32_bf16 v[124:127], v[144:147], v[184:187], v[124:127]
	v_mfma_f32_16x16x32_bf16 v[120:123], v[160:163], v[184:187], v[120:123]
	v_mfma_f32_16x16x32_bf16 v[116:119], v[144:147], v[192:195], v[116:119]
	v_mfma_f32_16x16x32_bf16 v[112:115], v[160:163], v[192:195], v[112:115]
	v_mfma_f32_16x16x32_bf16 v[108:111], v[144:147], v[200:203], v[108:111]
	v_mfma_f32_16x16x32_bf16 v[104:107], v[160:163], v[200:203], v[104:107]
	v_mfma_f32_16x16x32_bf16 v[100:103], v[144:147], v[208:211], v[100:103]
	v_mfma_f32_16x16x32_bf16 v[96:99], v[160:163], v[208:211], v[96:99]
	v_mfma_f32_16x16x32_bf16 v[124:127], v[148:151], v[188:191], v[124:127]
	v_mfma_f32_16x16x32_bf16 v[120:123], v[164:167], v[188:191], v[120:123]
	v_mfma_f32_16x16x32_bf16 v[116:119], v[148:151], v[196:199], v[116:119]
	v_mfma_f32_16x16x32_bf16 v[112:115], v[164:167], v[196:199], v[112:115]
	v_mfma_f32_16x16x32_bf16 v[108:111], v[148:151], v[204:207], v[108:111]
	v_mfma_f32_16x16x32_bf16 v[104:107], v[164:167], v[204:207], v[104:107]
	v_mfma_f32_16x16x32_bf16 v[100:103], v[148:151], v[212:215], v[100:103]
	v_mfma_f32_16x16x32_bf16 v[96:99], v[164:167], v[212:215], v[96:99]
	s_setprio 0
	s_setprio 1
	v_mfma_f32_16x16x32_bf16 v[76:79], v[168:171], v[184:187], v[76:79]
	v_mfma_f32_16x16x32_bf16 v[72:75], v[176:179], v[184:187], v[72:75]
	v_mfma_f32_16x16x32_bf16 v[60:63], v[168:171], v[192:195], v[60:63]
	v_mfma_f32_16x16x32_bf16 v[52:55], v[176:179], v[192:195], v[52:55]
	v_mfma_f32_16x16x32_bf16 v[44:47], v[168:171], v[200:203], v[44:47]
	v_mfma_f32_16x16x32_bf16 v[40:43], v[176:179], v[200:203], v[40:43]
	v_mfma_f32_16x16x32_bf16 v[36:39], v[168:171], v[208:211], v[36:39]
	v_mfma_f32_16x16x32_bf16 v[32:35], v[176:179], v[208:211], v[32:35]
	v_mfma_f32_16x16x32_bf16 v[76:79], v[172:175], v[188:191], v[76:79]
	v_mfma_f32_16x16x32_bf16 v[72:75], v[180:183], v[188:191], v[72:75]
	v_mfma_f32_16x16x32_bf16 v[60:63], v[172:175], v[196:199], v[60:63]
	v_mfma_f32_16x16x32_bf16 v[52:55], v[180:183], v[196:199], v[52:55]
	v_mfma_f32_16x16x32_bf16 v[44:47], v[172:175], v[204:207], v[44:47]
	v_mfma_f32_16x16x32_bf16 v[40:43], v[180:183], v[204:207], v[40:43]
	v_mfma_f32_16x16x32_bf16 v[36:39], v[172:175], v[212:215], v[36:39]
	v_mfma_f32_16x16x32_bf16 v[32:35], v[180:183], v[212:215], v[32:35]
	s_setprio 0
	s_barrier
	s_add_i32 s55, s45, s6
	v_lshl_add_u64 v[152:153], s[40:41], 0, v[130:131]
	s_mov_b32 m0, s55
	ds_read_b128 v[184:187], v159 offset:16384
	ds_read_b128 v[188:191], v159 offset:17408
	ds_read_b128 v[192:195], v159 offset:18432
	ds_read_b128 v[196:199], v159 offset:19456
	ds_read_b128 v[200:203], v159 offset:20480
	ds_read_b128 v[204:207], v159 offset:21504
	ds_read_b128 v[208:211], v159 offset:22528
	ds_read_b128 v[212:215], v159 offset:23552
	global_load_lds_dwordx4 v[152:153], off
	s_add_i32 m0, s55, 0x2000
	s_add_u32 s56, s40, 0x40000
	v_lshl_add_u64 v[216:217], s[40:41], 0, v[134:135]
	s_addc_u32 s57, s41, 0
	s_add_i32 s55, s46, s6
	global_load_lds_dwordx4 v[216:217], off
	v_lshl_add_u64 v[218:219], s[56:57], 0, v[130:131]
	s_mov_b32 m0, s55
	v_lshl_add_u64 v[220:221], s[42:43], 0, v[132:133]
	global_load_lds_dwordx4 v[218:219], off
	v_lshl_add_u64 v[218:219], s[56:57], 0, v[134:135]
	s_add_i32 m0, s55, 0x2000
	s_nop 0
	global_load_lds_dwordx4 v[218:219], off
	v_lshl_add_u64 v[218:219], s[42:43], 0, v[128:129]
	s_mov_b32 m0, s7
	s_nop 0
	global_load_lds_dwordx4 v[218:219], off
	s_mov_b32 m0, s8
	s_nop 0
	global_load_lds_dwordx4 v[220:221], off
	s_waitcnt vmcnt(8)
	s_waitcnt lgkmcnt(0)
	s_barrier
	s_setprio 1
	s_waitcnt lgkmcnt(0)
	v_mfma_f32_16x16x32_bf16 v[92:95], v[144:147], v[184:187], v[92:95]
	v_mfma_f32_16x16x32_bf16 v[88:91], v[160:163], v[184:187], v[88:91]
	v_mfma_f32_16x16x32_bf16 v[84:87], v[144:147], v[192:195], v[84:87]
	v_mfma_f32_16x16x32_bf16 v[80:83], v[160:163], v[192:195], v[80:83]
	v_mfma_f32_16x16x32_bf16 v[68:71], v[144:147], v[200:203], v[68:71]
	v_mfma_f32_16x16x32_bf16 v[64:67], v[160:163], v[200:203], v[64:67]
	v_mfma_f32_16x16x32_bf16 v[56:59], v[144:147], v[208:211], v[56:59]
	v_mfma_f32_16x16x32_bf16 v[48:51], v[160:163], v[208:211], v[48:51]
	v_mfma_f32_16x16x32_bf16 v[92:95], v[148:151], v[188:191], v[92:95]
	v_mfma_f32_16x16x32_bf16 v[88:91], v[164:167], v[188:191], v[88:91]
	v_mfma_f32_16x16x32_bf16 v[84:87], v[148:151], v[196:199], v[84:87]
	v_mfma_f32_16x16x32_bf16 v[80:83], v[164:167], v[196:199], v[80:83]
	v_mfma_f32_16x16x32_bf16 v[68:71], v[148:151], v[204:207], v[68:71]
	v_mfma_f32_16x16x32_bf16 v[64:67], v[164:167], v[204:207], v[64:67]
	v_mfma_f32_16x16x32_bf16 v[56:59], v[148:151], v[212:215], v[56:59]
	v_mfma_f32_16x16x32_bf16 v[48:51], v[164:167], v[212:215], v[48:51]
	s_setprio 0
	s_setprio 1
	v_mfma_f32_16x16x32_bf16 v[28:31], v[168:171], v[184:187], v[28:31]
	v_mfma_f32_16x16x32_bf16 v[24:27], v[176:179], v[184:187], v[24:27]
	v_mfma_f32_16x16x32_bf16 v[20:23], v[168:171], v[192:195], v[20:23]
	v_mfma_f32_16x16x32_bf16 v[16:19], v[176:179], v[192:195], v[16:19]
	v_mfma_f32_16x16x32_bf16 v[12:15], v[168:171], v[200:203], v[12:15]
	v_mfma_f32_16x16x32_bf16 v[8:11], v[176:179], v[200:203], v[8:11]
	v_mfma_f32_16x16x32_bf16 v[4:7], v[168:171], v[208:211], v[4:7]
	v_mfma_f32_16x16x32_bf16 v[0:3], v[176:179], v[208:211], v[0:3]
	v_mfma_f32_16x16x32_bf16 v[28:31], v[172:175], v[188:191], v[28:31]
	v_mfma_f32_16x16x32_bf16 v[24:27], v[180:183], v[188:191], v[24:27]
	v_mfma_f32_16x16x32_bf16 v[20:23], v[172:175], v[196:199], v[20:23]
	v_mfma_f32_16x16x32_bf16 v[16:19], v[180:183], v[196:199], v[16:19]
	v_mfma_f32_16x16x32_bf16 v[12:15], v[172:175], v[204:207], v[12:15]
	v_mfma_f32_16x16x32_bf16 v[8:11], v[180:183], v[204:207], v[8:11]
	v_mfma_f32_16x16x32_bf16 v[4:7], v[172:175], v[212:215], v[4:7]
	v_mfma_f32_16x16x32_bf16 v[0:3], v[180:183], v[212:215], v[0:3]
	s_setprio 0
	s_barrier
	s_add_i32 s55, 0, 0x18000
	s_add_i32 s56, 0, 0x1c000
	v_add_u32_e32 v164, s55, v155
	v_add_u32_e32 v180, s56, v155
	ds_read_b128 v[144:147], v164
	ds_read_b128 v[148:151], v164 offset:1024
	ds_read_b128 v[160:163], v164 offset:2048
	ds_read_b128 v[164:167], v164 offset:3072
	ds_read_b128 v[168:171], v180
	ds_read_b128 v[172:175], v180 offset:1024
	ds_read_b128 v[176:179], v180 offset:2048
	ds_read_b128 v[180:183], v180 offset:3072
	s_add_u32 s42, s42, 0x40000
	s_addc_u32 s43, s43, 0
	s_mov_b32 m0, s9
	v_lshl_add_u64 v[222:223], s[42:43], 0, v[128:129]
	ds_read_b128 v[184:187], v159 offset:32768
	ds_read_b128 v[188:191], v159 offset:33792
	ds_read_b128 v[192:195], v159 offset:34816
	ds_read_b128 v[196:199], v159 offset:35840
	ds_read_b128 v[200:203], v159 offset:36864
	ds_read_b128 v[204:207], v159 offset:37888
	ds_read_b128 v[208:211], v159 offset:38912
	ds_read_b128 v[212:215], v159 offset:39936
	global_load_lds_dwordx4 v[222:223], off
	v_lshl_add_u64 v[222:223], s[42:43], 0, v[132:133]
	s_mov_b32 m0, s33
	s_nop 0
	global_load_lds_dwordx4 v[222:223], off
	s_waitcnt vmcnt(8)
	s_waitcnt lgkmcnt(0)
	s_barrier
	s_setprio 1
	s_waitcnt lgkmcnt(0)
	v_mfma_f32_16x16x32_bf16 v[124:127], v[144:147], v[184:187], v[124:127]
	v_mfma_f32_16x16x32_bf16 v[120:123], v[160:163], v[184:187], v[120:123]
	v_mfma_f32_16x16x32_bf16 v[116:119], v[144:147], v[192:195], v[116:119]
	v_mfma_f32_16x16x32_bf16 v[112:115], v[160:163], v[192:195], v[112:115]
	v_mfma_f32_16x16x32_bf16 v[108:111], v[144:147], v[200:203], v[108:111]
	v_mfma_f32_16x16x32_bf16 v[104:107], v[160:163], v[200:203], v[104:107]
	v_mfma_f32_16x16x32_bf16 v[100:103], v[144:147], v[208:211], v[100:103]
	v_mfma_f32_16x16x32_bf16 v[96:99], v[160:163], v[208:211], v[96:99]
	v_mfma_f32_16x16x32_bf16 v[124:127], v[148:151], v[188:191], v[124:127]
	v_mfma_f32_16x16x32_bf16 v[120:123], v[164:167], v[188:191], v[120:123]
	v_mfma_f32_16x16x32_bf16 v[116:119], v[148:151], v[196:199], v[116:119]
	v_mfma_f32_16x16x32_bf16 v[112:115], v[164:167], v[196:199], v[112:115]
	v_mfma_f32_16x16x32_bf16 v[108:111], v[148:151], v[204:207], v[108:111]
	v_mfma_f32_16x16x32_bf16 v[104:107], v[164:167], v[204:207], v[104:107]
	v_mfma_f32_16x16x32_bf16 v[100:103], v[148:151], v[212:215], v[100:103]
	v_mfma_f32_16x16x32_bf16 v[96:99], v[164:167], v[212:215], v[96:99]
	s_setprio 0
	s_setprio 1
	v_mfma_f32_16x16x32_bf16 v[76:79], v[168:171], v[184:187], v[76:79]
	v_mfma_f32_16x16x32_bf16 v[72:75], v[176:179], v[184:187], v[72:75]
	v_mfma_f32_16x16x32_bf16 v[60:63], v[168:171], v[192:195], v[60:63]
	v_mfma_f32_16x16x32_bf16 v[52:55], v[176:179], v[192:195], v[52:55]
	v_mfma_f32_16x16x32_bf16 v[44:47], v[168:171], v[200:203], v[44:47]
	v_mfma_f32_16x16x32_bf16 v[40:43], v[176:179], v[200:203], v[40:43]
	v_mfma_f32_16x16x32_bf16 v[36:39], v[168:171], v[208:211], v[36:39]
	v_mfma_f32_16x16x32_bf16 v[32:35], v[176:179], v[208:211], v[32:35]
	v_mfma_f32_16x16x32_bf16 v[76:79], v[172:175], v[188:191], v[76:79]
	v_mfma_f32_16x16x32_bf16 v[72:75], v[180:183], v[188:191], v[72:75]
	v_mfma_f32_16x16x32_bf16 v[60:63], v[172:175], v[196:199], v[60:63]
	v_mfma_f32_16x16x32_bf16 v[52:55], v[180:183], v[196:199], v[52:55]
	v_mfma_f32_16x16x32_bf16 v[44:47], v[172:175], v[204:207], v[44:47]
	v_mfma_f32_16x16x32_bf16 v[40:43], v[180:183], v[204:207], v[40:43]
	v_mfma_f32_16x16x32_bf16 v[36:39], v[172:175], v[212:215], v[36:39]
	v_mfma_f32_16x16x32_bf16 v[32:35], v[180:183], v[212:215], v[32:35]
	s_setprio 0
	s_barrier
	s_add_i32 s42, s55, s6
	v_lshl_add_u64 v[152:153], v[152:153], 0, s[16:17]
	s_mov_b32 m0, s42
	ds_read_b128 v[184:187], v159 offset:49152
	ds_read_b128 v[188:191], v159 offset:50176
	ds_read_b128 v[192:195], v159 offset:51200
	ds_read_b128 v[196:199], v159 offset:52224
	ds_read_b128 v[200:203], v159 offset:53248
	ds_read_b128 v[204:207], v159 offset:54272
	ds_read_b128 v[208:211], v159 offset:55296
	ds_read_b128 v[212:215], v159 offset:56320
	global_load_lds_dwordx4 v[152:153], off
	s_add_i32 m0, s42, 0x2000
	s_add_u32 s40, s40, 0x40080
	v_lshl_add_u64 v[152:153], v[216:217], 0, s[16:17]
	s_addc_u32 s41, s41, 0
	s_add_i32 s42, s56, s6
	global_load_lds_dwordx4 v[152:153], off
	v_lshl_add_u64 v[152:153], s[40:41], 0, v[130:131]
	s_mov_b32 m0, s42
	s_nop 0
	global_load_lds_dwordx4 v[152:153], off
	v_lshl_add_u64 v[152:153], s[40:41], 0, v[134:135]
	s_add_i32 m0, s42, 0x2000
	s_nop 0
	global_load_lds_dwordx4 v[152:153], off
	v_lshl_add_u64 v[152:153], v[218:219], 0, s[16:17]
	s_mov_b32 m0, s37
	s_nop 0
	global_load_lds_dwordx4 v[152:153], off
	v_lshl_add_u64 v[152:153], v[220:221], 0, s[16:17]
	s_mov_b32 m0, s38
	s_nop 0
	global_load_lds_dwordx4 v[152:153], off
	s_waitcnt vmcnt(8)
	s_waitcnt lgkmcnt(0)
	s_barrier
	s_setprio 1
	s_waitcnt lgkmcnt(0)
	v_mfma_f32_16x16x32_bf16 v[92:95], v[144:147], v[184:187], v[92:95]
	v_mfma_f32_16x16x32_bf16 v[88:91], v[160:163], v[184:187], v[88:91]
	v_mfma_f32_16x16x32_bf16 v[84:87], v[144:147], v[192:195], v[84:87]
	v_mfma_f32_16x16x32_bf16 v[80:83], v[160:163], v[192:195], v[80:83]
	v_mfma_f32_16x16x32_bf16 v[68:71], v[144:147], v[200:203], v[68:71]
	v_mfma_f32_16x16x32_bf16 v[64:67], v[160:163], v[200:203], v[64:67]
	v_mfma_f32_16x16x32_bf16 v[56:59], v[144:147], v[208:211], v[56:59]
	v_mfma_f32_16x16x32_bf16 v[48:51], v[160:163], v[208:211], v[48:51]
	v_mfma_f32_16x16x32_bf16 v[92:95], v[148:151], v[188:191], v[92:95]
	v_mfma_f32_16x16x32_bf16 v[88:91], v[164:167], v[188:191], v[88:91]
	v_mfma_f32_16x16x32_bf16 v[84:87], v[148:151], v[196:199], v[84:87]
	v_mfma_f32_16x16x32_bf16 v[80:83], v[164:167], v[196:199], v[80:83]
	v_mfma_f32_16x16x32_bf16 v[68:71], v[148:151], v[204:207], v[68:71]
	v_mfma_f32_16x16x32_bf16 v[64:67], v[164:167], v[204:207], v[64:67]
	v_mfma_f32_16x16x32_bf16 v[56:59], v[148:151], v[212:215], v[56:59]
	v_mfma_f32_16x16x32_bf16 v[48:51], v[164:167], v[212:215], v[48:51]
	s_setprio 0
	s_setprio 1
	v_mfma_f32_16x16x32_bf16 v[28:31], v[168:171], v[184:187], v[28:31]
	v_mfma_f32_16x16x32_bf16 v[24:27], v[176:179], v[184:187], v[24:27]
	v_mfma_f32_16x16x32_bf16 v[20:23], v[168:171], v[192:195], v[20:23]
	v_mfma_f32_16x16x32_bf16 v[16:19], v[176:179], v[192:195], v[16:19]
	v_mfma_f32_16x16x32_bf16 v[12:15], v[168:171], v[200:203], v[12:15]
	v_mfma_f32_16x16x32_bf16 v[8:11], v[176:179], v[200:203], v[8:11]
	v_mfma_f32_16x16x32_bf16 v[4:7], v[168:171], v[208:211], v[4:7]
	v_mfma_f32_16x16x32_bf16 v[0:3], v[176:179], v[208:211], v[0:3]
	v_mfma_f32_16x16x32_bf16 v[28:31], v[172:175], v[188:191], v[28:31]
	v_mfma_f32_16x16x32_bf16 v[24:27], v[180:183], v[188:191], v[24:27]
	v_mfma_f32_16x16x32_bf16 v[20:23], v[172:175], v[196:199], v[20:23]
	v_mfma_f32_16x16x32_bf16 v[16:19], v[180:183], v[196:199], v[16:19]
	v_mfma_f32_16x16x32_bf16 v[12:15], v[172:175], v[204:207], v[12:15]
	v_mfma_f32_16x16x32_bf16 v[8:11], v[180:183], v[204:207], v[8:11]
	v_mfma_f32_16x16x32_bf16 v[4:7], v[172:175], v[212:215], v[4:7]
	v_mfma_f32_16x16x32_bf16 v[0:3], v[180:183], v[212:215], v[0:3]
	s_setprio 0
	s_add_i32 s54, s54, 2
	s_add_u32 s52, s52, 0x100
	s_addc_u32 s53, s53, 0
	s_add_u32 s30, s30, 0x100
	s_addc_u32 s31, s31, 0
	s_cmp_gt_u32 s54, 13
	s_barrier
	s_cbranch_scc0 .LBB0_3217
	s_and_b64 vcc, exec, s[18:19]
	s_cbranch_vccz .LBB0_3220
	s_barrier

.LBB0_3350:
	ds_read_b128 v[104:107], v233
	ds_read_b128 v[108:111], v233 offset:1024
	ds_read_b128 v[112:115], v233 offset:2048
	ds_read_b128 v[116:119], v233 offset:3072
	ds_read_b128 v[120:123], v234
	ds_read_b128 v[124:127], v234 offset:1024
	ds_read_b128 v[128:131], v234 offset:2048
	ds_read_b128 v[132:135], v234 offset:3072
	s_add_u32 s74, s28, 0xfffc0080
	s_addc_u32 s75, s29, -1
	s_cmp_eq_u32 s80, 12
	s_cselect_b32 s77, s69, s75
	s_cselect_b32 s76, s68, s74
	s_cselect_b32 s75, s67, s79
	s_cselect_b32 s74, s73, s78
	v_lshl_add_u64 v[208:209], s[28:29], 0, v[186:187]
	s_add_i32 m0, s96, 0xc000
	ds_read_b128 v[160:163], v235
	ds_read_b128 v[164:167], v235 offset:1024
	ds_read_b128 v[168:171], v235 offset:2048
	ds_read_b128 v[172:175], v235 offset:3072
	ds_read_b128 v[192:195], v235 offset:4096
	ds_read_b128 v[196:199], v235 offset:5120
	ds_read_b128 v[200:203], v235 offset:6144
	ds_read_b128 v[204:207], v235 offset:7168
	global_load_lds_dwordx4 v[208:209], off
	v_lshl_add_u64 v[208:209], s[28:29], 0, v[184:185]
	s_add_i32 m0, s96, 0xe000
	s_nop 0
	global_load_lds_dwordx4 v[208:209], off
	s_waitcnt vmcnt(8)
	s_waitcnt lgkmcnt(0)
	s_barrier
	s_setprio 1
	s_waitcnt lgkmcnt(0)
	v_mfma_f32_16x16x32_bf16 v[156:159], v[104:107], v[160:163], v[156:159]
	v_mfma_f32_16x16x32_bf16 v[60:63], v[112:115], v[160:163], v[60:63]
	v_mfma_f32_16x16x32_bf16 v[148:151], v[104:107], v[168:171], v[148:151]
	v_mfma_f32_16x16x32_bf16 v[52:55], v[112:115], v[168:171], v[52:55]
	v_mfma_f32_16x16x32_bf16 v[140:143], v[104:107], v[192:195], v[140:143]
	v_mfma_f32_16x16x32_bf16 v[44:47], v[112:115], v[192:195], v[44:47]
	v_mfma_f32_16x16x32_bf16 v[100:103], v[104:107], v[200:203], v[100:103]
	v_mfma_f32_16x16x32_bf16 v[36:39], v[112:115], v[200:203], v[36:39]
	v_mfma_f32_16x16x32_bf16 v[156:159], v[108:111], v[164:167], v[156:159]
	v_mfma_f32_16x16x32_bf16 v[60:63], v[116:119], v[164:167], v[60:63]
	v_mfma_f32_16x16x32_bf16 v[148:151], v[108:111], v[172:175], v[148:151]
	v_mfma_f32_16x16x32_bf16 v[52:55], v[116:119], v[172:175], v[52:55]
	v_mfma_f32_16x16x32_bf16 v[140:143], v[108:111], v[196:199], v[140:143]
	v_mfma_f32_16x16x32_bf16 v[44:47], v[116:119], v[196:199], v[44:47]
	v_mfma_f32_16x16x32_bf16 v[100:103], v[108:111], v[204:207], v[100:103]
	v_mfma_f32_16x16x32_bf16 v[36:39], v[116:119], v[204:207], v[36:39]
	s_setprio 0
	s_setprio 1
	v_mfma_f32_16x16x32_bf16 v[152:155], v[120:123], v[160:163], v[152:155]
	v_mfma_f32_16x16x32_bf16 v[56:59], v[128:131], v[160:163], v[56:59]
	v_mfma_f32_16x16x32_bf16 v[144:147], v[120:123], v[168:171], v[144:147]
	v_mfma_f32_16x16x32_bf16 v[48:51], v[128:131], v[168:171], v[48:51]
	v_mfma_f32_16x16x32_bf16 v[136:139], v[120:123], v[192:195], v[136:139]
	v_mfma_f32_16x16x32_bf16 v[40:43], v[128:131], v[192:195], v[40:43]
	v_mfma_f32_16x16x32_bf16 v[96:99], v[120:123], v[200:203], v[96:99]
	v_mfma_f32_16x16x32_bf16 v[32:35], v[128:131], v[200:203], v[32:35]
	v_mfma_f32_16x16x32_bf16 v[152:155], v[124:127], v[164:167], v[152:155]
	v_mfma_f32_16x16x32_bf16 v[56:59], v[132:135], v[164:167], v[56:59]
	v_mfma_f32_16x16x32_bf16 v[144:147], v[124:127], v[172:175], v[144:147]
	v_mfma_f32_16x16x32_bf16 v[48:51], v[132:135], v[172:175], v[48:51]
	v_mfma_f32_16x16x32_bf16 v[136:139], v[124:127], v[196:199], v[136:139]
	v_mfma_f32_16x16x32_bf16 v[40:43], v[132:135], v[196:199], v[40:43]
	v_mfma_f32_16x16x32_bf16 v[96:99], v[124:127], v[204:207], v[96:99]
	v_mfma_f32_16x16x32_bf16 v[32:35], v[132:135], v[204:207], v[32:35]
	s_setprio 0
	s_barrier
	s_add_i32 s81, s33, s95
	v_lshl_add_u64 v[208:209], s[74:75], 0, v[178:179]
	s_mov_b32 m0, s81
	ds_read_b128 v[160:163], v235 offset:16384
	ds_read_b128 v[164:167], v235 offset:17408
	ds_read_b128 v[168:171], v235 offset:18432
	ds_read_b128 v[172:175], v235 offset:19456
	ds_read_b128 v[192:195], v235 offset:20480
	ds_read_b128 v[196:199], v235 offset:21504
	ds_read_b128 v[200:203], v235 offset:22528
	ds_read_b128 v[204:207], v235 offset:23552
	global_load_lds_dwordx4 v[208:209], off
	s_add_i32 m0, s81, 0x2000
	s_add_u32 s82, s74, 0x40000
	v_lshl_add_u64 v[210:211], s[74:75], 0, v[182:183]
	s_addc_u32 s83, s75, 0
	s_add_i32 s81, s0, s95
	global_load_lds_dwordx4 v[210:211], off
	v_lshl_add_u64 v[212:213], s[82:83], 0, v[178:179]
	s_mov_b32 m0, s81
	v_lshl_add_u64 v[214:215], s[76:77], 0, v[180:181]
	global_load_lds_dwordx4 v[212:213], off
	v_lshl_add_u64 v[212:213], s[82:83], 0, v[182:183]
	s_add_i32 m0, s81, 0x2000
	s_nop 0
	global_load_lds_dwordx4 v[212:213], off
	v_lshl_add_u64 v[212:213], s[76:77], 0, v[176:177]
	s_mov_b32 m0, s96
	s_nop 0
	global_load_lds_dwordx4 v[212:213], off
	s_mov_b32 m0, s97
	s_nop 0
	global_load_lds_dwordx4 v[214:215], off
	s_waitcnt vmcnt(8)
	s_waitcnt lgkmcnt(0)
	s_barrier
	s_setprio 1
	s_waitcnt lgkmcnt(0)
	v_mfma_f32_16x16x32_bf16 v[92:95], v[104:107], v[160:163], v[92:95]
	v_mfma_f32_16x16x32_bf16 v[28:31], v[112:115], v[160:163], v[28:31]
	v_mfma_f32_16x16x32_bf16 v[84:87], v[104:107], v[168:171], v[84:87]
	v_mfma_f32_16x16x32_bf16 v[20:23], v[112:115], v[168:171], v[20:23]
	v_mfma_f32_16x16x32_bf16 v[76:79], v[104:107], v[192:195], v[76:79]
	v_mfma_f32_16x16x32_bf16 v[12:15], v[112:115], v[192:195], v[12:15]
	v_mfma_f32_16x16x32_bf16 v[68:71], v[104:107], v[200:203], v[68:71]
	v_mfma_f32_16x16x32_bf16 v[4:7], v[112:115], v[200:203], v[4:7]
	v_mfma_f32_16x16x32_bf16 v[92:95], v[108:111], v[164:167], v[92:95]
	v_mfma_f32_16x16x32_bf16 v[28:31], v[116:119], v[164:167], v[28:31]
	v_mfma_f32_16x16x32_bf16 v[84:87], v[108:111], v[172:175], v[84:87]
	v_mfma_f32_16x16x32_bf16 v[20:23], v[116:119], v[172:175], v[20:23]
	v_mfma_f32_16x16x32_bf16 v[76:79], v[108:111], v[196:199], v[76:79]
	v_mfma_f32_16x16x32_bf16 v[12:15], v[116:119], v[196:199], v[12:15]
	v_mfma_f32_16x16x32_bf16 v[68:71], v[108:111], v[204:207], v[68:71]
	v_mfma_f32_16x16x32_bf16 v[4:7], v[116:119], v[204:207], v[4:7]
	s_setprio 0
	s_setprio 1
	v_mfma_f32_16x16x32_bf16 v[88:91], v[120:123], v[160:163], v[88:91]
	v_mfma_f32_16x16x32_bf16 v[24:27], v[128:131], v[160:163], v[24:27]
	v_mfma_f32_16x16x32_bf16 v[80:83], v[120:123], v[168:171], v[80:83]
	v_mfma_f32_16x16x32_bf16 v[16:19], v[128:131], v[168:171], v[16:19]
	v_mfma_f32_16x16x32_bf16 v[72:75], v[120:123], v[192:195], v[72:75]
	v_mfma_f32_16x16x32_bf16 v[8:11], v[128:131], v[192:195], v[8:11]
	v_mfma_f32_16x16x32_bf16 v[64:67], v[120:123], v[200:203], v[64:67]
	v_mfma_f32_16x16x32_bf16 v[0:3], v[128:131], v[200:203], v[0:3]
	v_mfma_f32_16x16x32_bf16 v[88:91], v[124:127], v[164:167], v[88:91]
	v_mfma_f32_16x16x32_bf16 v[24:27], v[132:135], v[164:167], v[24:27]
	v_mfma_f32_16x16x32_bf16 v[80:83], v[124:127], v[172:175], v[80:83]
	v_mfma_f32_16x16x32_bf16 v[16:19], v[132:135], v[172:175], v[16:19]
	v_mfma_f32_16x16x32_bf16 v[72:75], v[124:127], v[196:199], v[72:75]
	v_mfma_f32_16x16x32_bf16 v[8:11], v[132:135], v[196:199], v[8:11]
	v_mfma_f32_16x16x32_bf16 v[64:67], v[124:127], v[204:207], v[64:67]
	v_mfma_f32_16x16x32_bf16 v[0:3], v[132:135], v[204:207], v[0:3]
	s_setprio 0
	s_barrier
	s_add_i32 s81, 0, 0x18000
	s_add_i32 s82, 0, 0x1c000
	v_add_u32_e32 v116, s81, v221
	v_add_u32_e32 v132, s82, v221
	ds_read_b128 v[104:107], v116
	ds_read_b128 v[108:111], v116 offset:1024
	ds_read_b128 v[112:115], v116 offset:2048
	ds_read_b128 v[116:119], v116 offset:3072
	ds_read_b128 v[120:123], v132
	ds_read_b128 v[124:127], v132 offset:1024
	ds_read_b128 v[128:131], v132 offset:2048
	ds_read_b128 v[132:135], v132 offset:3072
	s_add_u32 s76, s76, 0x40000
	s_addc_u32 s77, s77, 0
	s_mov_b32 m0, s8
	v_lshl_add_u64 v[216:217], s[76:77], 0, v[176:177]
	ds_read_b128 v[160:163], v235 offset:32768
	ds_read_b128 v[164:167], v235 offset:33792
	ds_read_b128 v[168:171], v235 offset:34816
	ds_read_b128 v[172:175], v235 offset:35840
	ds_read_b128 v[192:195], v235 offset:36864
	ds_read_b128 v[196:199], v235 offset:37888
	ds_read_b128 v[200:203], v235 offset:38912
	ds_read_b128 v[204:207], v235 offset:39936
	global_load_lds_dwordx4 v[216:217], off
	v_lshl_add_u64 v[216:217], s[76:77], 0, v[180:181]
	s_mov_b32 m0, s9
	s_nop 0
	global_load_lds_dwordx4 v[216:217], off
	s_waitcnt vmcnt(8)
	s_waitcnt lgkmcnt(0)
	s_barrier
	s_setprio 1
	s_waitcnt lgkmcnt(0)
	v_mfma_f32_16x16x32_bf16 v[156:159], v[104:107], v[160:163], v[156:159]
	v_mfma_f32_16x16x32_bf16 v[60:63], v[112:115], v[160:163], v[60:63]
	v_mfma_f32_16x16x32_bf16 v[148:151], v[104:107], v[168:171], v[148:151]
	v_mfma_f32_16x16x32_bf16 v[52:55], v[112:115], v[168:171], v[52:55]
	v_mfma_f32_16x16x32_bf16 v[140:143], v[104:107], v[192:195], v[140:143]
	v_mfma_f32_16x16x32_bf16 v[44:47], v[112:115], v[192:195], v[44:47]
	v_mfma_f32_16x16x32_bf16 v[100:103], v[104:107], v[200:203], v[100:103]
	v_mfma_f32_16x16x32_bf16 v[36:39], v[112:115], v[200:203], v[36:39]
	v_mfma_f32_16x16x32_bf16 v[156:159], v[108:111], v[164:167], v[156:159]
	v_mfma_f32_16x16x32_bf16 v[60:63], v[116:119], v[164:167], v[60:63]
	v_mfma_f32_16x16x32_bf16 v[148:151], v[108:111], v[172:175], v[148:151]
	v_mfma_f32_16x16x32_bf16 v[52:55], v[116:119], v[172:175], v[52:55]
	v_mfma_f32_16x16x32_bf16 v[140:143], v[108:111], v[196:199], v[140:143]
	v_mfma_f32_16x16x32_bf16 v[44:47], v[116:119], v[196:199], v[44:47]
	v_mfma_f32_16x16x32_bf16 v[100:103], v[108:111], v[204:207], v[100:103]
	v_mfma_f32_16x16x32_bf16 v[36:39], v[116:119], v[204:207], v[36:39]
	s_setprio 0
	s_setprio 1
	v_mfma_f32_16x16x32_bf16 v[152:155], v[120:123], v[160:163], v[152:155]
	v_mfma_f32_16x16x32_bf16 v[56:59], v[128:131], v[160:163], v[56:59]
	v_mfma_f32_16x16x32_bf16 v[144:147], v[120:123], v[168:171], v[144:147]
	v_mfma_f32_16x16x32_bf16 v[48:51], v[128:131], v[168:171], v[48:51]
	v_mfma_f32_16x16x32_bf16 v[136:139], v[120:123], v[192:195], v[136:139]
	v_mfma_f32_16x16x32_bf16 v[40:43], v[128:131], v[192:195], v[40:43]
	v_mfma_f32_16x16x32_bf16 v[96:99], v[120:123], v[200:203], v[96:99]
	v_mfma_f32_16x16x32_bf16 v[32:35], v[128:131], v[200:203], v[32:35]
	v_mfma_f32_16x16x32_bf16 v[152:155], v[124:127], v[164:167], v[152:155]
	v_mfma_f32_16x16x32_bf16 v[56:59], v[132:135], v[164:167], v[56:59]
	v_mfma_f32_16x16x32_bf16 v[144:147], v[124:127], v[172:175], v[144:147]
	v_mfma_f32_16x16x32_bf16 v[48:51], v[132:135], v[172:175], v[48:51]
	v_mfma_f32_16x16x32_bf16 v[136:139], v[124:127], v[196:199], v[136:139]
	v_mfma_f32_16x16x32_bf16 v[40:43], v[132:135], v[196:199], v[40:43]
	v_mfma_f32_16x16x32_bf16 v[96:99], v[124:127], v[204:207], v[96:99]
	v_mfma_f32_16x16x32_bf16 v[32:35], v[132:135], v[204:207], v[32:35]
	s_setprio 0
	s_barrier
	s_add_i32 s76, s81, s95
	v_lshl_add_u64 v[208:209], v[208:209], 0, s[48:49]
	s_mov_b32 m0, s76
	ds_read_b128 v[160:163], v235 offset:49152
	ds_read_b128 v[164:167], v235 offset:50176
	ds_read_b128 v[168:171], v235 offset:51200
	ds_read_b128 v[172:175], v235 offset:52224
	ds_read_b128 v[192:195], v235 offset:53248
	ds_read_b128 v[196:199], v235 offset:54272
	ds_read_b128 v[200:203], v235 offset:55296
	ds_read_b128 v[204:207], v235 offset:56320
	global_load_lds_dwordx4 v[208:209], off
	s_add_i32 m0, s76, 0x2000
	s_add_u32 s74, s74, 0x40080
	v_lshl_add_u64 v[208:209], v[210:211], 0, s[48:49]
	s_addc_u32 s75, s75, 0
	s_add_i32 s76, s82, s95
	global_load_lds_dwordx4 v[208:209], off
	v_lshl_add_u64 v[208:209], s[74:75], 0, v[178:179]
	s_mov_b32 m0, s76
	s_nop 0
	global_load_lds_dwordx4 v[208:209], off
	v_lshl_add_u64 v[208:209], s[74:75], 0, v[182:183]
	s_add_i32 m0, s76, 0x2000
	s_nop 0
	global_load_lds_dwordx4 v[208:209], off
	v_lshl_add_u64 v[208:209], v[212:213], 0, s[48:49]
	s_mov_b32 m0, s5
	s_nop 0
	global_load_lds_dwordx4 v[208:209], off
	v_lshl_add_u64 v[208:209], v[214:215], 0, s[48:49]
	s_mov_b32 m0, s6
	s_nop 0
	global_load_lds_dwordx4 v[208:209], off
	s_waitcnt vmcnt(8)
	s_waitcnt lgkmcnt(0)
	s_barrier
	s_setprio 1
	s_waitcnt lgkmcnt(0)
	v_mfma_f32_16x16x32_bf16 v[92:95], v[104:107], v[160:163], v[92:95]
	v_mfma_f32_16x16x32_bf16 v[28:31], v[112:115], v[160:163], v[28:31]
	v_mfma_f32_16x16x32_bf16 v[84:87], v[104:107], v[168:171], v[84:87]
	v_mfma_f32_16x16x32_bf16 v[20:23], v[112:115], v[168:171], v[20:23]
	v_mfma_f32_16x16x32_bf16 v[76:79], v[104:107], v[192:195], v[76:79]
	v_mfma_f32_16x16x32_bf16 v[12:15], v[112:115], v[192:195], v[12:15]
	v_mfma_f32_16x16x32_bf16 v[68:71], v[104:107], v[200:203], v[68:71]
	v_mfma_f32_16x16x32_bf16 v[4:7], v[112:115], v[200:203], v[4:7]
	v_mfma_f32_16x16x32_bf16 v[92:95], v[108:111], v[164:167], v[92:95]
	v_mfma_f32_16x16x32_bf16 v[28:31], v[116:119], v[164:167], v[28:31]
	v_mfma_f32_16x16x32_bf16 v[84:87], v[108:111], v[172:175], v[84:87]
	v_mfma_f32_16x16x32_bf16 v[20:23], v[116:119], v[172:175], v[20:23]
	v_mfma_f32_16x16x32_bf16 v[76:79], v[108:111], v[196:199], v[76:79]
	v_mfma_f32_16x16x32_bf16 v[12:15], v[116:119], v[196:199], v[12:15]
	v_mfma_f32_16x16x32_bf16 v[68:71], v[108:111], v[204:207], v[68:71]
	v_mfma_f32_16x16x32_bf16 v[4:7], v[116:119], v[204:207], v[4:7]
	s_setprio 0
	s_setprio 1
	v_mfma_f32_16x16x32_bf16 v[88:91], v[120:123], v[160:163], v[88:91]
	v_mfma_f32_16x16x32_bf16 v[24:27], v[128:131], v[160:163], v[24:27]
	v_mfma_f32_16x16x32_bf16 v[80:83], v[120:123], v[168:171], v[80:83]
	v_mfma_f32_16x16x32_bf16 v[16:19], v[128:131], v[168:171], v[16:19]
	v_mfma_f32_16x16x32_bf16 v[72:75], v[120:123], v[192:195], v[72:75]
	v_mfma_f32_16x16x32_bf16 v[8:11], v[128:131], v[192:195], v[8:11]
	v_mfma_f32_16x16x32_bf16 v[64:67], v[120:123], v[200:203], v[64:67]
	v_mfma_f32_16x16x32_bf16 v[0:3], v[128:131], v[200:203], v[0:3]
	v_mfma_f32_16x16x32_bf16 v[88:91], v[124:127], v[164:167], v[88:91]
	v_mfma_f32_16x16x32_bf16 v[24:27], v[132:135], v[164:167], v[24:27]
	v_mfma_f32_16x16x32_bf16 v[80:83], v[124:127], v[172:175], v[80:83]
	v_mfma_f32_16x16x32_bf16 v[16:19], v[132:135], v[172:175], v[16:19]
	v_mfma_f32_16x16x32_bf16 v[72:75], v[124:127], v[196:199], v[72:75]
	v_mfma_f32_16x16x32_bf16 v[8:11], v[132:135], v[196:199], v[8:11]
	v_mfma_f32_16x16x32_bf16 v[64:67], v[124:127], v[204:207], v[64:67]
	v_mfma_f32_16x16x32_bf16 v[0:3], v[132:135], v[204:207], v[0:3]
	s_setprio 0
	s_add_i32 s80, s80, 2
	s_add_u32 s78, s78, 0x100
	s_addc_u32 s79, s79, 0
	s_add_u32 s28, s28, 0x100
	s_addc_u32 s29, s29, 0
	s_cmp_gt_u32 s80, 13
	s_barrier
	s_cbranch_scc0 .LBB0_3350
	s_and_b64 vcc, exec, s[50:51]
	s_cbranch_vccz .LBB0_3353
	s_barrier

.LBB0_3685:
	ds_read_b128 v[146:149], v153
	ds_read_b128 v[156:159], v153 offset:1024
	ds_read_b128 v[160:163], v153 offset:2048
	ds_read_b128 v[164:167], v153 offset:3072
	ds_read_b128 v[168:171], v154
	ds_read_b128 v[172:175], v154 offset:1024
	ds_read_b128 v[176:179], v154 offset:2048
	ds_read_b128 v[180:183], v154 offset:3072
	s_add_u32 s42, s40, 0xfffc0080
	s_addc_u32 s43, s41, -1
	s_cmp_eq_u32 s56, 12
	s_cselect_b32 s45, s23, s43
	s_cselect_b32 s44, s29, s42
	s_cselect_b32 s43, s21, s55
	s_cselect_b32 s42, s31, s54
	v_lshl_add_u64 v[216:217], s[40:41], 0, v[140:141]
	s_add_i32 m0, s6, 0xc000
	ds_read_b128 v[184:187], v155
	ds_read_b128 v[188:191], v155 offset:1024
	ds_read_b128 v[192:195], v155 offset:2048
	ds_read_b128 v[196:199], v155 offset:3072
	ds_read_b128 v[200:203], v155 offset:4096
	ds_read_b128 v[204:207], v155 offset:5120
	ds_read_b128 v[208:211], v155 offset:6144
	ds_read_b128 v[212:215], v155 offset:7168
	global_load_lds_dwordx4 v[216:217], off
	v_lshl_add_u64 v[216:217], s[40:41], 0, v[138:139]
	s_add_i32 m0, s6, 0xe000
	s_nop 0
	global_load_lds_dwordx4 v[216:217], off
	s_waitcnt vmcnt(8)
	s_waitcnt lgkmcnt(0)
	s_barrier
	s_setprio 1
	s_waitcnt lgkmcnt(0)
	v_mfma_f32_16x16x32_bf16 v[124:127], v[146:149], v[184:187], v[124:127]
	v_mfma_f32_16x16x32_bf16 v[120:123], v[160:163], v[184:187], v[120:123]
	v_mfma_f32_16x16x32_bf16 v[116:119], v[146:149], v[192:195], v[116:119]
	v_mfma_f32_16x16x32_bf16 v[112:115], v[160:163], v[192:195], v[112:115]
	v_mfma_f32_16x16x32_bf16 v[108:111], v[146:149], v[200:203], v[108:111]
	v_mfma_f32_16x16x32_bf16 v[104:107], v[160:163], v[200:203], v[104:107]
	v_mfma_f32_16x16x32_bf16 v[100:103], v[146:149], v[208:211], v[100:103]
	v_mfma_f32_16x16x32_bf16 v[96:99], v[160:163], v[208:211], v[96:99]
	v_mfma_f32_16x16x32_bf16 v[124:127], v[156:159], v[188:191], v[124:127]
	v_mfma_f32_16x16x32_bf16 v[120:123], v[164:167], v[188:191], v[120:123]
	v_mfma_f32_16x16x32_bf16 v[116:119], v[156:159], v[196:199], v[116:119]
	v_mfma_f32_16x16x32_bf16 v[112:115], v[164:167], v[196:199], v[112:115]
	v_mfma_f32_16x16x32_bf16 v[108:111], v[156:159], v[204:207], v[108:111]
	v_mfma_f32_16x16x32_bf16 v[104:107], v[164:167], v[204:207], v[104:107]
	v_mfma_f32_16x16x32_bf16 v[100:103], v[156:159], v[212:215], v[100:103]
	v_mfma_f32_16x16x32_bf16 v[96:99], v[164:167], v[212:215], v[96:99]
	s_setprio 0
	s_setprio 1
	v_mfma_f32_16x16x32_bf16 v[60:63], v[168:171], v[184:187], v[60:63]
	v_mfma_f32_16x16x32_bf16 v[56:59], v[176:179], v[184:187], v[56:59]
	v_mfma_f32_16x16x32_bf16 v[52:55], v[168:171], v[192:195], v[52:55]
	v_mfma_f32_16x16x32_bf16 v[48:51], v[176:179], v[192:195], v[48:51]
	v_mfma_f32_16x16x32_bf16 v[44:47], v[168:171], v[200:203], v[44:47]
	v_mfma_f32_16x16x32_bf16 v[40:43], v[176:179], v[200:203], v[40:43]
	v_mfma_f32_16x16x32_bf16 v[36:39], v[168:171], v[208:211], v[36:39]
	v_mfma_f32_16x16x32_bf16 v[32:35], v[176:179], v[208:211], v[32:35]
	v_mfma_f32_16x16x32_bf16 v[60:63], v[172:175], v[188:191], v[60:63]
	v_mfma_f32_16x16x32_bf16 v[56:59], v[180:183], v[188:191], v[56:59]
	v_mfma_f32_16x16x32_bf16 v[52:55], v[172:175], v[196:199], v[52:55]
	v_mfma_f32_16x16x32_bf16 v[48:51], v[180:183], v[196:199], v[48:51]
	v_mfma_f32_16x16x32_bf16 v[44:47], v[172:175], v[204:207], v[44:47]
	v_mfma_f32_16x16x32_bf16 v[40:43], v[180:183], v[204:207], v[40:43]
	v_mfma_f32_16x16x32_bf16 v[36:39], v[172:175], v[212:215], v[36:39]
	v_mfma_f32_16x16x32_bf16 v[32:35], v[180:183], v[212:215], v[32:35]
	s_setprio 0
	s_barrier
	s_add_i32 s57, s49, s5
	v_lshl_add_u64 v[216:217], s[42:43], 0, v[130:131]
	s_mov_b32 m0, s57
	ds_read_b128 v[184:187], v155 offset:16384
	ds_read_b128 v[188:191], v155 offset:17408
	ds_read_b128 v[192:195], v155 offset:18432
	ds_read_b128 v[196:199], v155 offset:19456
	ds_read_b128 v[200:203], v155 offset:20480
	ds_read_b128 v[204:207], v155 offset:21504
	ds_read_b128 v[208:211], v155 offset:22528
	ds_read_b128 v[212:215], v155 offset:23552
	global_load_lds_dwordx4 v[216:217], off
	s_add_i32 m0, s57, 0x2000
	s_add_u32 s58, s42, 0x40000
	v_lshl_add_u64 v[218:219], s[42:43], 0, v[134:135]
	s_addc_u32 s59, s43, 0
	s_add_i32 s57, s50, s5
	global_load_lds_dwordx4 v[218:219], off
	v_lshl_add_u64 v[220:221], s[58:59], 0, v[130:131]
	s_mov_b32 m0, s57
	v_lshl_add_u64 v[222:223], s[44:45], 0, v[132:133]
	global_load_lds_dwordx4 v[220:221], off
	v_lshl_add_u64 v[220:221], s[58:59], 0, v[134:135]
	s_add_i32 m0, s57, 0x2000
	s_nop 0
	global_load_lds_dwordx4 v[220:221], off
	v_lshl_add_u64 v[220:221], s[44:45], 0, v[128:129]
	s_mov_b32 m0, s6
	s_nop 0
	global_load_lds_dwordx4 v[220:221], off
	s_mov_b32 m0, s7
	s_nop 0
	global_load_lds_dwordx4 v[222:223], off
	s_waitcnt vmcnt(8)
	s_waitcnt lgkmcnt(0)
	s_barrier
	s_setprio 1
	s_waitcnt lgkmcnt(0)
	v_mfma_f32_16x16x32_bf16 v[92:95], v[146:149], v[184:187], v[92:95]
	v_mfma_f32_16x16x32_bf16 v[88:91], v[160:163], v[184:187], v[88:91]
	v_mfma_f32_16x16x32_bf16 v[84:87], v[146:149], v[192:195], v[84:87]
	v_mfma_f32_16x16x32_bf16 v[80:83], v[160:163], v[192:195], v[80:83]
	v_mfma_f32_16x16x32_bf16 v[76:79], v[146:149], v[200:203], v[76:79]
	v_mfma_f32_16x16x32_bf16 v[72:75], v[160:163], v[200:203], v[72:75]
	v_mfma_f32_16x16x32_bf16 v[68:71], v[146:149], v[208:211], v[68:71]
	v_mfma_f32_16x16x32_bf16 v[64:67], v[160:163], v[208:211], v[64:67]
	v_mfma_f32_16x16x32_bf16 v[92:95], v[156:159], v[188:191], v[92:95]
	v_mfma_f32_16x16x32_bf16 v[88:91], v[164:167], v[188:191], v[88:91]
	v_mfma_f32_16x16x32_bf16 v[84:87], v[156:159], v[196:199], v[84:87]
	v_mfma_f32_16x16x32_bf16 v[80:83], v[164:167], v[196:199], v[80:83]
	v_mfma_f32_16x16x32_bf16 v[76:79], v[156:159], v[204:207], v[76:79]
	v_mfma_f32_16x16x32_bf16 v[72:75], v[164:167], v[204:207], v[72:75]
	v_mfma_f32_16x16x32_bf16 v[68:71], v[156:159], v[212:215], v[68:71]
	v_mfma_f32_16x16x32_bf16 v[64:67], v[164:167], v[212:215], v[64:67]
	s_setprio 0
	s_setprio 1
	v_mfma_f32_16x16x32_bf16 v[28:31], v[168:171], v[184:187], v[28:31]
	v_mfma_f32_16x16x32_bf16 v[24:27], v[176:179], v[184:187], v[24:27]
	v_mfma_f32_16x16x32_bf16 v[20:23], v[168:171], v[192:195], v[20:23]
	v_mfma_f32_16x16x32_bf16 v[16:19], v[176:179], v[192:195], v[16:19]
	v_mfma_f32_16x16x32_bf16 v[12:15], v[168:171], v[200:203], v[12:15]
	v_mfma_f32_16x16x32_bf16 v[8:11], v[176:179], v[200:203], v[8:11]
	v_mfma_f32_16x16x32_bf16 v[4:7], v[168:171], v[208:211], v[4:7]
	v_mfma_f32_16x16x32_bf16 v[0:3], v[176:179], v[208:211], v[0:3]
	v_mfma_f32_16x16x32_bf16 v[28:31], v[172:175], v[188:191], v[28:31]
	v_mfma_f32_16x16x32_bf16 v[24:27], v[180:183], v[188:191], v[24:27]
	v_mfma_f32_16x16x32_bf16 v[20:23], v[172:175], v[196:199], v[20:23]
	v_mfma_f32_16x16x32_bf16 v[16:19], v[180:183], v[196:199], v[16:19]
	v_mfma_f32_16x16x32_bf16 v[12:15], v[172:175], v[204:207], v[12:15]
	v_mfma_f32_16x16x32_bf16 v[8:11], v[180:183], v[204:207], v[8:11]
	v_mfma_f32_16x16x32_bf16 v[4:7], v[172:175], v[212:215], v[4:7]
	v_mfma_f32_16x16x32_bf16 v[0:3], v[180:183], v[212:215], v[0:3]
	s_setprio 0
	s_barrier
	s_add_i32 s57, 0, 0x18000
	s_add_i32 s58, 0, 0x1c000
	v_add_u32_e32 v164, s57, v151
	v_add_u32_e32 v180, s58, v151
	ds_read_b128 v[146:149], v164
	ds_read_b128 v[156:159], v164 offset:1024
	ds_read_b128 v[160:163], v164 offset:2048
	ds_read_b128 v[164:167], v164 offset:3072
	ds_read_b128 v[168:171], v180
	ds_read_b128 v[172:175], v180 offset:1024
	ds_read_b128 v[176:179], v180 offset:2048
	ds_read_b128 v[180:183], v180 offset:3072
	s_add_u32 s44, s44, 0x40000
	s_addc_u32 s45, s45, 0
	s_mov_b32 m0, s33
	v_lshl_add_u64 v[224:225], s[44:45], 0, v[128:129]
	ds_read_b128 v[184:187], v155 offset:32768
	ds_read_b128 v[188:191], v155 offset:33792
	ds_read_b128 v[192:195], v155 offset:34816
	ds_read_b128 v[196:199], v155 offset:35840
	ds_read_b128 v[200:203], v155 offset:36864
	ds_read_b128 v[204:207], v155 offset:37888
	ds_read_b128 v[208:211], v155 offset:38912
	ds_read_b128 v[212:215], v155 offset:39936
	global_load_lds_dwordx4 v[224:225], off
	v_lshl_add_u64 v[224:225], s[44:45], 0, v[132:133]
	s_mov_b32 m0, s35
	s_nop 0
	global_load_lds_dwordx4 v[224:225], off
	s_waitcnt vmcnt(8)
	s_waitcnt lgkmcnt(0)
	s_barrier
	s_setprio 1
	s_waitcnt lgkmcnt(0)
	v_mfma_f32_16x16x32_bf16 v[124:127], v[146:149], v[184:187], v[124:127]
	v_mfma_f32_16x16x32_bf16 v[120:123], v[160:163], v[184:187], v[120:123]
	v_mfma_f32_16x16x32_bf16 v[116:119], v[146:149], v[192:195], v[116:119]
	v_mfma_f32_16x16x32_bf16 v[112:115], v[160:163], v[192:195], v[112:115]
	v_mfma_f32_16x16x32_bf16 v[108:111], v[146:149], v[200:203], v[108:111]
	v_mfma_f32_16x16x32_bf16 v[104:107], v[160:163], v[200:203], v[104:107]
	v_mfma_f32_16x16x32_bf16 v[100:103], v[146:149], v[208:211], v[100:103]
	v_mfma_f32_16x16x32_bf16 v[96:99], v[160:163], v[208:211], v[96:99]
	v_mfma_f32_16x16x32_bf16 v[124:127], v[156:159], v[188:191], v[124:127]
	v_mfma_f32_16x16x32_bf16 v[120:123], v[164:167], v[188:191], v[120:123]
	v_mfma_f32_16x16x32_bf16 v[116:119], v[156:159], v[196:199], v[116:119]
	v_mfma_f32_16x16x32_bf16 v[112:115], v[164:167], v[196:199], v[112:115]
	v_mfma_f32_16x16x32_bf16 v[108:111], v[156:159], v[204:207], v[108:111]
	v_mfma_f32_16x16x32_bf16 v[104:107], v[164:167], v[204:207], v[104:107]
	v_mfma_f32_16x16x32_bf16 v[100:103], v[156:159], v[212:215], v[100:103]
	v_mfma_f32_16x16x32_bf16 v[96:99], v[164:167], v[212:215], v[96:99]
	s_setprio 0
	s_setprio 1
	v_mfma_f32_16x16x32_bf16 v[60:63], v[168:171], v[184:187], v[60:63]
	v_mfma_f32_16x16x32_bf16 v[56:59], v[176:179], v[184:187], v[56:59]
	v_mfma_f32_16x16x32_bf16 v[52:55], v[168:171], v[192:195], v[52:55]
	v_mfma_f32_16x16x32_bf16 v[48:51], v[176:179], v[192:195], v[48:51]
	v_mfma_f32_16x16x32_bf16 v[44:47], v[168:171], v[200:203], v[44:47]
	v_mfma_f32_16x16x32_bf16 v[40:43], v[176:179], v[200:203], v[40:43]
	v_mfma_f32_16x16x32_bf16 v[36:39], v[168:171], v[208:211], v[36:39]
	v_mfma_f32_16x16x32_bf16 v[32:35], v[176:179], v[208:211], v[32:35]
	v_mfma_f32_16x16x32_bf16 v[60:63], v[172:175], v[188:191], v[60:63]
	v_mfma_f32_16x16x32_bf16 v[56:59], v[180:183], v[188:191], v[56:59]
	v_mfma_f32_16x16x32_bf16 v[52:55], v[172:175], v[196:199], v[52:55]
	v_mfma_f32_16x16x32_bf16 v[48:51], v[180:183], v[196:199], v[48:51]
	v_mfma_f32_16x16x32_bf16 v[44:47], v[172:175], v[204:207], v[44:47]
	v_mfma_f32_16x16x32_bf16 v[40:43], v[180:183], v[204:207], v[40:43]
	v_mfma_f32_16x16x32_bf16 v[36:39], v[172:175], v[212:215], v[36:39]
	v_mfma_f32_16x16x32_bf16 v[32:35], v[180:183], v[212:215], v[32:35]
	s_setprio 0
	s_barrier
	s_add_i32 s44, s57, s5
	v_lshl_add_u64 v[216:217], v[216:217], 0, s[16:17]
	s_mov_b32 m0, s44
	ds_read_b128 v[184:187], v155 offset:49152
	ds_read_b128 v[188:191], v155 offset:50176
	ds_read_b128 v[192:195], v155 offset:51200
	ds_read_b128 v[196:199], v155 offset:52224
	ds_read_b128 v[200:203], v155 offset:53248
	ds_read_b128 v[204:207], v155 offset:54272
	ds_read_b128 v[208:211], v155 offset:55296
	ds_read_b128 v[212:215], v155 offset:56320
	global_load_lds_dwordx4 v[216:217], off
	s_add_i32 m0, s44, 0x2000
	s_add_u32 s42, s42, 0x40080
	v_lshl_add_u64 v[216:217], v[218:219], 0, s[16:17]
	s_addc_u32 s43, s43, 0
	s_add_i32 s44, s58, s5
	global_load_lds_dwordx4 v[216:217], off
	v_lshl_add_u64 v[216:217], s[42:43], 0, v[130:131]
	s_mov_b32 m0, s44
	s_nop 0
	global_load_lds_dwordx4 v[216:217], off
	v_lshl_add_u64 v[216:217], s[42:43], 0, v[134:135]
	s_add_i32 m0, s44, 0x2000
	s_nop 0
	global_load_lds_dwordx4 v[216:217], off
	v_lshl_add_u64 v[216:217], v[220:221], 0, s[16:17]
	s_mov_b32 m0, s37
	s_nop 0
	global_load_lds_dwordx4 v[216:217], off
	v_lshl_add_u64 v[216:217], v[222:223], 0, s[16:17]
	s_mov_b32 m0, s38
	s_nop 0
	global_load_lds_dwordx4 v[216:217], off
	s_waitcnt vmcnt(8)
	s_waitcnt lgkmcnt(0)
	s_barrier
	s_setprio 1
	s_waitcnt lgkmcnt(0)
	v_mfma_f32_16x16x32_bf16 v[92:95], v[146:149], v[184:187], v[92:95]
	v_mfma_f32_16x16x32_bf16 v[88:91], v[160:163], v[184:187], v[88:91]
	v_mfma_f32_16x16x32_bf16 v[84:87], v[146:149], v[192:195], v[84:87]
	v_mfma_f32_16x16x32_bf16 v[80:83], v[160:163], v[192:195], v[80:83]
	v_mfma_f32_16x16x32_bf16 v[76:79], v[146:149], v[200:203], v[76:79]
	v_mfma_f32_16x16x32_bf16 v[72:75], v[160:163], v[200:203], v[72:75]
	v_mfma_f32_16x16x32_bf16 v[68:71], v[146:149], v[208:211], v[68:71]
	v_mfma_f32_16x16x32_bf16 v[64:67], v[160:163], v[208:211], v[64:67]
	v_mfma_f32_16x16x32_bf16 v[92:95], v[156:159], v[188:191], v[92:95]
	v_mfma_f32_16x16x32_bf16 v[88:91], v[164:167], v[188:191], v[88:91]
	v_mfma_f32_16x16x32_bf16 v[84:87], v[156:159], v[196:199], v[84:87]
	v_mfma_f32_16x16x32_bf16 v[80:83], v[164:167], v[196:199], v[80:83]
	v_mfma_f32_16x16x32_bf16 v[76:79], v[156:159], v[204:207], v[76:79]
	v_mfma_f32_16x16x32_bf16 v[72:75], v[164:167], v[204:207], v[72:75]
	v_mfma_f32_16x16x32_bf16 v[68:71], v[156:159], v[212:215], v[68:71]
	v_mfma_f32_16x16x32_bf16 v[64:67], v[164:167], v[212:215], v[64:67]
	s_setprio 0
	s_setprio 1
	v_mfma_f32_16x16x32_bf16 v[28:31], v[168:171], v[184:187], v[28:31]
	v_mfma_f32_16x16x32_bf16 v[24:27], v[176:179], v[184:187], v[24:27]
	v_mfma_f32_16x16x32_bf16 v[20:23], v[168:171], v[192:195], v[20:23]
	v_mfma_f32_16x16x32_bf16 v[16:19], v[176:179], v[192:195], v[16:19]
	v_mfma_f32_16x16x32_bf16 v[12:15], v[168:171], v[200:203], v[12:15]
	v_mfma_f32_16x16x32_bf16 v[8:11], v[176:179], v[200:203], v[8:11]
	v_mfma_f32_16x16x32_bf16 v[4:7], v[168:171], v[208:211], v[4:7]
	v_mfma_f32_16x16x32_bf16 v[0:3], v[176:179], v[208:211], v[0:3]
	v_mfma_f32_16x16x32_bf16 v[28:31], v[172:175], v[188:191], v[28:31]
	v_mfma_f32_16x16x32_bf16 v[24:27], v[180:183], v[188:191], v[24:27]
	v_mfma_f32_16x16x32_bf16 v[20:23], v[172:175], v[196:199], v[20:23]
	v_mfma_f32_16x16x32_bf16 v[16:19], v[180:183], v[196:199], v[16:19]
	v_mfma_f32_16x16x32_bf16 v[12:15], v[172:175], v[204:207], v[12:15]
	v_mfma_f32_16x16x32_bf16 v[8:11], v[180:183], v[204:207], v[8:11]
	v_mfma_f32_16x16x32_bf16 v[4:7], v[172:175], v[212:215], v[4:7]
	v_mfma_f32_16x16x32_bf16 v[0:3], v[180:183], v[212:215], v[0:3]
	s_setprio 0
	s_add_i32 s56, s56, 2
	s_add_u32 s54, s54, 0x100
	s_addc_u32 s55, s55, 0
	s_add_u32 s40, s40, 0x100
	s_addc_u32 s41, s41, 0
	s_cmp_gt_u32 s56, 13
	s_barrier
	s_cbranch_scc0 .LBB0_3685
	s_and_b64 vcc, exec, s[18:19]
	s_cbranch_vccz .LBB0_3688
	s_barrier

.LBB0_3906:
	ds_read_b128 v[144:147], v157
	ds_read_b128 v[148:151], v157 offset:1024
	ds_read_b128 v[160:163], v157 offset:2048
	ds_read_b128 v[164:167], v157 offset:3072
	ds_read_b128 v[168:171], v158
	ds_read_b128 v[172:175], v158 offset:1024
	ds_read_b128 v[176:179], v158 offset:2048
	ds_read_b128 v[180:183], v158 offset:3072
	s_add_u32 s30, s28, 0xfffc0080
	s_addc_u32 s31, s29, -1
	s_cmp_eq_u32 s54, 12
	s_cselect_b32 s39, s21, s31
	s_cselect_b32 s38, s50, s30
	s_cselect_b32 s31, s19, s53
	s_cselect_b32 s30, s51, s52
	v_lshl_add_u64 v[152:153], s[28:29], 0, v[138:139]
	s_add_i32 m0, s7, 0xc000
	ds_read_b128 v[184:187], v159
	ds_read_b128 v[188:191], v159 offset:1024
	ds_read_b128 v[192:195], v159 offset:2048
	ds_read_b128 v[196:199], v159 offset:3072
	ds_read_b128 v[200:203], v159 offset:4096
	ds_read_b128 v[204:207], v159 offset:5120
	ds_read_b128 v[208:211], v159 offset:6144
	ds_read_b128 v[212:215], v159 offset:7168
	global_load_lds_dwordx4 v[152:153], off
	v_lshl_add_u64 v[152:153], s[28:29], 0, v[136:137]
	s_add_i32 m0, s7, 0xe000
	s_nop 0
	global_load_lds_dwordx4 v[152:153], off
	s_waitcnt vmcnt(8)
	s_waitcnt lgkmcnt(0)
	s_barrier
	s_setprio 1
	s_waitcnt lgkmcnt(0)
	v_mfma_f32_16x16x32_bf16 v[124:127], v[144:147], v[184:187], v[124:127]
	v_mfma_f32_16x16x32_bf16 v[120:123], v[160:163], v[184:187], v[120:123]
	v_mfma_f32_16x16x32_bf16 v[116:119], v[144:147], v[192:195], v[116:119]
	v_mfma_f32_16x16x32_bf16 v[112:115], v[160:163], v[192:195], v[112:115]
	v_mfma_f32_16x16x32_bf16 v[108:111], v[144:147], v[200:203], v[108:111]
	v_mfma_f32_16x16x32_bf16 v[104:107], v[160:163], v[200:203], v[104:107]
	v_mfma_f32_16x16x32_bf16 v[100:103], v[144:147], v[208:211], v[100:103]
	v_mfma_f32_16x16x32_bf16 v[96:99], v[160:163], v[208:211], v[96:99]
	v_mfma_f32_16x16x32_bf16 v[124:127], v[148:151], v[188:191], v[124:127]
	v_mfma_f32_16x16x32_bf16 v[120:123], v[164:167], v[188:191], v[120:123]
	v_mfma_f32_16x16x32_bf16 v[116:119], v[148:151], v[196:199], v[116:119]
	v_mfma_f32_16x16x32_bf16 v[112:115], v[164:167], v[196:199], v[112:115]
	v_mfma_f32_16x16x32_bf16 v[108:111], v[148:151], v[204:207], v[108:111]
	v_mfma_f32_16x16x32_bf16 v[104:107], v[164:167], v[204:207], v[104:107]
	v_mfma_f32_16x16x32_bf16 v[100:103], v[148:151], v[212:215], v[100:103]
	v_mfma_f32_16x16x32_bf16 v[96:99], v[164:167], v[212:215], v[96:99]
	s_setprio 0
	s_setprio 1
	v_mfma_f32_16x16x32_bf16 v[76:79], v[168:171], v[184:187], v[76:79]
	v_mfma_f32_16x16x32_bf16 v[72:75], v[176:179], v[184:187], v[72:75]
	v_mfma_f32_16x16x32_bf16 v[60:63], v[168:171], v[192:195], v[60:63]
	v_mfma_f32_16x16x32_bf16 v[52:55], v[176:179], v[192:195], v[52:55]
	v_mfma_f32_16x16x32_bf16 v[44:47], v[168:171], v[200:203], v[44:47]
	v_mfma_f32_16x16x32_bf16 v[40:43], v[176:179], v[200:203], v[40:43]
	v_mfma_f32_16x16x32_bf16 v[36:39], v[168:171], v[208:211], v[36:39]
	v_mfma_f32_16x16x32_bf16 v[32:35], v[176:179], v[208:211], v[32:35]
	v_mfma_f32_16x16x32_bf16 v[76:79], v[172:175], v[188:191], v[76:79]
	v_mfma_f32_16x16x32_bf16 v[72:75], v[180:183], v[188:191], v[72:75]
	v_mfma_f32_16x16x32_bf16 v[60:63], v[172:175], v[196:199], v[60:63]
	v_mfma_f32_16x16x32_bf16 v[52:55], v[180:183], v[196:199], v[52:55]
	v_mfma_f32_16x16x32_bf16 v[44:47], v[172:175], v[204:207], v[44:47]
	v_mfma_f32_16x16x32_bf16 v[40:43], v[180:183], v[204:207], v[40:43]
	v_mfma_f32_16x16x32_bf16 v[36:39], v[172:175], v[212:215], v[36:39]
	v_mfma_f32_16x16x32_bf16 v[32:35], v[180:183], v[212:215], v[32:35]
	s_setprio 0
	s_barrier
	s_add_i32 s55, s45, s6
	v_lshl_add_u64 v[152:153], s[30:31], 0, v[130:131]
	s_mov_b32 m0, s55
	ds_read_b128 v[184:187], v159 offset:16384
	ds_read_b128 v[188:191], v159 offset:17408
	ds_read_b128 v[192:195], v159 offset:18432
	ds_read_b128 v[196:199], v159 offset:19456
	ds_read_b128 v[200:203], v159 offset:20480
	ds_read_b128 v[204:207], v159 offset:21504
	ds_read_b128 v[208:211], v159 offset:22528
	ds_read_b128 v[212:215], v159 offset:23552
	global_load_lds_dwordx4 v[152:153], off
	s_add_i32 m0, s55, 0x2000
	s_add_u32 s56, s30, 0x40000
	v_lshl_add_u64 v[216:217], s[30:31], 0, v[134:135]
	s_addc_u32 s57, s31, 0
	s_add_i32 s55, s46, s6
	global_load_lds_dwordx4 v[216:217], off
	v_lshl_add_u64 v[218:219], s[56:57], 0, v[130:131]
	s_mov_b32 m0, s55
	v_lshl_add_u64 v[220:221], s[38:39], 0, v[132:133]
	global_load_lds_dwordx4 v[218:219], off
	v_lshl_add_u64 v[218:219], s[56:57], 0, v[134:135]
	s_add_i32 m0, s55, 0x2000
	s_nop 0
	global_load_lds_dwordx4 v[218:219], off
	v_lshl_add_u64 v[218:219], s[38:39], 0, v[128:129]
	s_mov_b32 m0, s7
	s_nop 0
	global_load_lds_dwordx4 v[218:219], off
	s_mov_b32 m0, s33
	s_nop 0
	global_load_lds_dwordx4 v[220:221], off
	s_waitcnt vmcnt(8)
	s_waitcnt lgkmcnt(0)
	s_barrier
	s_setprio 1
	s_waitcnt lgkmcnt(0)
	v_mfma_f32_16x16x32_bf16 v[92:95], v[144:147], v[184:187], v[92:95]
	v_mfma_f32_16x16x32_bf16 v[88:91], v[160:163], v[184:187], v[88:91]
	v_mfma_f32_16x16x32_bf16 v[84:87], v[144:147], v[192:195], v[84:87]
	v_mfma_f32_16x16x32_bf16 v[80:83], v[160:163], v[192:195], v[80:83]
	v_mfma_f32_16x16x32_bf16 v[68:71], v[144:147], v[200:203], v[68:71]
	v_mfma_f32_16x16x32_bf16 v[64:67], v[160:163], v[200:203], v[64:67]
	v_mfma_f32_16x16x32_bf16 v[56:59], v[144:147], v[208:211], v[56:59]
	v_mfma_f32_16x16x32_bf16 v[48:51], v[160:163], v[208:211], v[48:51]
	v_mfma_f32_16x16x32_bf16 v[92:95], v[148:151], v[188:191], v[92:95]
	v_mfma_f32_16x16x32_bf16 v[88:91], v[164:167], v[188:191], v[88:91]
	v_mfma_f32_16x16x32_bf16 v[84:87], v[148:151], v[196:199], v[84:87]
	v_mfma_f32_16x16x32_bf16 v[80:83], v[164:167], v[196:199], v[80:83]
	v_mfma_f32_16x16x32_bf16 v[68:71], v[148:151], v[204:207], v[68:71]
	v_mfma_f32_16x16x32_bf16 v[64:67], v[164:167], v[204:207], v[64:67]
	v_mfma_f32_16x16x32_bf16 v[56:59], v[148:151], v[212:215], v[56:59]
	v_mfma_f32_16x16x32_bf16 v[48:51], v[164:167], v[212:215], v[48:51]
	s_setprio 0
	s_setprio 1
	v_mfma_f32_16x16x32_bf16 v[28:31], v[168:171], v[184:187], v[28:31]
	v_mfma_f32_16x16x32_bf16 v[24:27], v[176:179], v[184:187], v[24:27]
	v_mfma_f32_16x16x32_bf16 v[20:23], v[168:171], v[192:195], v[20:23]
	v_mfma_f32_16x16x32_bf16 v[16:19], v[176:179], v[192:195], v[16:19]
	v_mfma_f32_16x16x32_bf16 v[12:15], v[168:171], v[200:203], v[12:15]
	v_mfma_f32_16x16x32_bf16 v[8:11], v[176:179], v[200:203], v[8:11]
	v_mfma_f32_16x16x32_bf16 v[4:7], v[168:171], v[208:211], v[4:7]
	v_mfma_f32_16x16x32_bf16 v[0:3], v[176:179], v[208:211], v[0:3]
	v_mfma_f32_16x16x32_bf16 v[28:31], v[172:175], v[188:191], v[28:31]
	v_mfma_f32_16x16x32_bf16 v[24:27], v[180:183], v[188:191], v[24:27]
	v_mfma_f32_16x16x32_bf16 v[20:23], v[172:175], v[196:199], v[20:23]
	v_mfma_f32_16x16x32_bf16 v[16:19], v[180:183], v[196:199], v[16:19]
	v_mfma_f32_16x16x32_bf16 v[12:15], v[172:175], v[204:207], v[12:15]
	v_mfma_f32_16x16x32_bf16 v[8:11], v[180:183], v[204:207], v[8:11]
	v_mfma_f32_16x16x32_bf16 v[4:7], v[172:175], v[212:215], v[4:7]
	v_mfma_f32_16x16x32_bf16 v[0:3], v[180:183], v[212:215], v[0:3]
	s_setprio 0
	s_barrier
	s_add_i32 s55, 0, 0x18000
	s_add_i32 s56, 0, 0x1c000
	v_add_u32_e32 v164, s55, v155
	v_add_u32_e32 v180, s56, v155
	ds_read_b128 v[144:147], v164
	ds_read_b128 v[148:151], v164 offset:1024
	ds_read_b128 v[160:163], v164 offset:2048
	ds_read_b128 v[164:167], v164 offset:3072
	ds_read_b128 v[168:171], v180
	ds_read_b128 v[172:175], v180 offset:1024
	ds_read_b128 v[176:179], v180 offset:2048
	ds_read_b128 v[180:183], v180 offset:3072
	s_add_u32 s38, s38, 0x40000
	s_addc_u32 s39, s39, 0
	s_mov_b32 m0, s35
	v_lshl_add_u64 v[222:223], s[38:39], 0, v[128:129]
	ds_read_b128 v[184:187], v159 offset:32768
	ds_read_b128 v[188:191], v159 offset:33792
	ds_read_b128 v[192:195], v159 offset:34816
	ds_read_b128 v[196:199], v159 offset:35840
	ds_read_b128 v[200:203], v159 offset:36864
	ds_read_b128 v[204:207], v159 offset:37888
	ds_read_b128 v[208:211], v159 offset:38912
	ds_read_b128 v[212:215], v159 offset:39936
	global_load_lds_dwordx4 v[222:223], off
	v_lshl_add_u64 v[222:223], s[38:39], 0, v[132:133]
	s_mov_b32 m0, s36
	s_nop 0
	global_load_lds_dwordx4 v[222:223], off
	s_waitcnt vmcnt(8)
	s_waitcnt lgkmcnt(0)
	s_barrier
	s_setprio 1
	s_waitcnt lgkmcnt(0)
	v_mfma_f32_16x16x32_bf16 v[124:127], v[144:147], v[184:187], v[124:127]
	v_mfma_f32_16x16x32_bf16 v[120:123], v[160:163], v[184:187], v[120:123]
	v_mfma_f32_16x16x32_bf16 v[116:119], v[144:147], v[192:195], v[116:119]
	v_mfma_f32_16x16x32_bf16 v[112:115], v[160:163], v[192:195], v[112:115]
	v_mfma_f32_16x16x32_bf16 v[108:111], v[144:147], v[200:203], v[108:111]
	v_mfma_f32_16x16x32_bf16 v[104:107], v[160:163], v[200:203], v[104:107]
	v_mfma_f32_16x16x32_bf16 v[100:103], v[144:147], v[208:211], v[100:103]
	v_mfma_f32_16x16x32_bf16 v[96:99], v[160:163], v[208:211], v[96:99]
	v_mfma_f32_16x16x32_bf16 v[124:127], v[148:151], v[188:191], v[124:127]
	v_mfma_f32_16x16x32_bf16 v[120:123], v[164:167], v[188:191], v[120:123]
	v_mfma_f32_16x16x32_bf16 v[116:119], v[148:151], v[196:199], v[116:119]
	v_mfma_f32_16x16x32_bf16 v[112:115], v[164:167], v[196:199], v[112:115]
	v_mfma_f32_16x16x32_bf16 v[108:111], v[148:151], v[204:207], v[108:111]
	v_mfma_f32_16x16x32_bf16 v[104:107], v[164:167], v[204:207], v[104:107]
	v_mfma_f32_16x16x32_bf16 v[100:103], v[148:151], v[212:215], v[100:103]
	v_mfma_f32_16x16x32_bf16 v[96:99], v[164:167], v[212:215], v[96:99]
	s_setprio 0
	s_setprio 1
	v_mfma_f32_16x16x32_bf16 v[76:79], v[168:171], v[184:187], v[76:79]
	v_mfma_f32_16x16x32_bf16 v[72:75], v[176:179], v[184:187], v[72:75]
	v_mfma_f32_16x16x32_bf16 v[60:63], v[168:171], v[192:195], v[60:63]
	v_mfma_f32_16x16x32_bf16 v[52:55], v[176:179], v[192:195], v[52:55]
	v_mfma_f32_16x16x32_bf16 v[44:47], v[168:171], v[200:203], v[44:47]
	v_mfma_f32_16x16x32_bf16 v[40:43], v[176:179], v[200:203], v[40:43]
	v_mfma_f32_16x16x32_bf16 v[36:39], v[168:171], v[208:211], v[36:39]
	v_mfma_f32_16x16x32_bf16 v[32:35], v[176:179], v[208:211], v[32:35]
	v_mfma_f32_16x16x32_bf16 v[76:79], v[172:175], v[188:191], v[76:79]
	v_mfma_f32_16x16x32_bf16 v[72:75], v[180:183], v[188:191], v[72:75]
	v_mfma_f32_16x16x32_bf16 v[60:63], v[172:175], v[196:199], v[60:63]
	v_mfma_f32_16x16x32_bf16 v[52:55], v[180:183], v[196:199], v[52:55]
	v_mfma_f32_16x16x32_bf16 v[44:47], v[172:175], v[204:207], v[44:47]
	v_mfma_f32_16x16x32_bf16 v[40:43], v[180:183], v[204:207], v[40:43]
	v_mfma_f32_16x16x32_bf16 v[36:39], v[172:175], v[212:215], v[36:39]
	v_mfma_f32_16x16x32_bf16 v[32:35], v[180:183], v[212:215], v[32:35]
	s_setprio 0
	s_barrier
	s_add_i32 s38, s55, s6
	v_lshl_add_u64 v[152:153], v[152:153], 0, s[14:15]
	s_mov_b32 m0, s38
	ds_read_b128 v[184:187], v159 offset:49152
	ds_read_b128 v[188:191], v159 offset:50176
	ds_read_b128 v[192:195], v159 offset:51200
	ds_read_b128 v[196:199], v159 offset:52224
	ds_read_b128 v[200:203], v159 offset:53248
	ds_read_b128 v[204:207], v159 offset:54272
	ds_read_b128 v[208:211], v159 offset:55296
	ds_read_b128 v[212:215], v159 offset:56320
	global_load_lds_dwordx4 v[152:153], off
	s_add_i32 m0, s38, 0x2000
	s_add_u32 s30, s30, 0x40080
	v_lshl_add_u64 v[152:153], v[216:217], 0, s[14:15]
	s_addc_u32 s31, s31, 0
	s_add_i32 s38, s56, s6
	global_load_lds_dwordx4 v[152:153], off
	v_lshl_add_u64 v[152:153], s[30:31], 0, v[130:131]
	s_mov_b32 m0, s38
	s_nop 0
	global_load_lds_dwordx4 v[152:153], off
	v_lshl_add_u64 v[152:153], s[30:31], 0, v[134:135]
	s_add_i32 m0, s38, 0x2000
	s_nop 0
	global_load_lds_dwordx4 v[152:153], off
	v_lshl_add_u64 v[152:153], v[218:219], 0, s[14:15]
	s_mov_b32 m0, s41
	s_nop 0
	global_load_lds_dwordx4 v[152:153], off
	v_lshl_add_u64 v[152:153], v[220:221], 0, s[14:15]
	s_mov_b32 m0, s42
	s_nop 0
	global_load_lds_dwordx4 v[152:153], off
	s_waitcnt vmcnt(8)
	s_waitcnt lgkmcnt(0)
	s_barrier
	s_setprio 1
	s_waitcnt lgkmcnt(0)
	v_mfma_f32_16x16x32_bf16 v[92:95], v[144:147], v[184:187], v[92:95]
	v_mfma_f32_16x16x32_bf16 v[88:91], v[160:163], v[184:187], v[88:91]
	v_mfma_f32_16x16x32_bf16 v[84:87], v[144:147], v[192:195], v[84:87]
	v_mfma_f32_16x16x32_bf16 v[80:83], v[160:163], v[192:195], v[80:83]
	v_mfma_f32_16x16x32_bf16 v[68:71], v[144:147], v[200:203], v[68:71]
	v_mfma_f32_16x16x32_bf16 v[64:67], v[160:163], v[200:203], v[64:67]
	v_mfma_f32_16x16x32_bf16 v[56:59], v[144:147], v[208:211], v[56:59]
	v_mfma_f32_16x16x32_bf16 v[48:51], v[160:163], v[208:211], v[48:51]
	v_mfma_f32_16x16x32_bf16 v[92:95], v[148:151], v[188:191], v[92:95]
	v_mfma_f32_16x16x32_bf16 v[88:91], v[164:167], v[188:191], v[88:91]
	v_mfma_f32_16x16x32_bf16 v[84:87], v[148:151], v[196:199], v[84:87]
	v_mfma_f32_16x16x32_bf16 v[80:83], v[164:167], v[196:199], v[80:83]
	v_mfma_f32_16x16x32_bf16 v[68:71], v[148:151], v[204:207], v[68:71]
	v_mfma_f32_16x16x32_bf16 v[64:67], v[164:167], v[204:207], v[64:67]
	v_mfma_f32_16x16x32_bf16 v[56:59], v[148:151], v[212:215], v[56:59]
	v_mfma_f32_16x16x32_bf16 v[48:51], v[164:167], v[212:215], v[48:51]
	s_setprio 0
	s_setprio 1
	v_mfma_f32_16x16x32_bf16 v[28:31], v[168:171], v[184:187], v[28:31]
	v_mfma_f32_16x16x32_bf16 v[24:27], v[176:179], v[184:187], v[24:27]
	v_mfma_f32_16x16x32_bf16 v[20:23], v[168:171], v[192:195], v[20:23]
	v_mfma_f32_16x16x32_bf16 v[16:19], v[176:179], v[192:195], v[16:19]
	v_mfma_f32_16x16x32_bf16 v[12:15], v[168:171], v[200:203], v[12:15]
	v_mfma_f32_16x16x32_bf16 v[8:11], v[176:179], v[200:203], v[8:11]
	v_mfma_f32_16x16x32_bf16 v[4:7], v[168:171], v[208:211], v[4:7]
	v_mfma_f32_16x16x32_bf16 v[0:3], v[176:179], v[208:211], v[0:3]
	v_mfma_f32_16x16x32_bf16 v[28:31], v[172:175], v[188:191], v[28:31]
	v_mfma_f32_16x16x32_bf16 v[24:27], v[180:183], v[188:191], v[24:27]
	v_mfma_f32_16x16x32_bf16 v[20:23], v[172:175], v[196:199], v[20:23]
	v_mfma_f32_16x16x32_bf16 v[16:19], v[180:183], v[196:199], v[16:19]
	v_mfma_f32_16x16x32_bf16 v[12:15], v[172:175], v[204:207], v[12:15]
	v_mfma_f32_16x16x32_bf16 v[8:11], v[180:183], v[204:207], v[8:11]
	v_mfma_f32_16x16x32_bf16 v[4:7], v[172:175], v[212:215], v[4:7]
	v_mfma_f32_16x16x32_bf16 v[0:3], v[180:183], v[212:215], v[0:3]
	s_setprio 0
	s_add_i32 s54, s54, 2
	s_add_u32 s52, s52, 0x100
	s_addc_u32 s53, s53, 0
	s_add_u32 s28, s28, 0x100
	s_addc_u32 s29, s29, 0
	s_cmp_gt_u32 s54, 13
	s_barrier
	s_cbranch_scc0 .LBB0_3906
	s_and_b64 vcc, exec, s[16:17]
	s_cbranch_vccz .LBB0_3909
	s_barrier

.LBB0_4039:
	ds_read_b128 v[104:107], v233
	ds_read_b128 v[108:111], v233 offset:1024
	ds_read_b128 v[112:115], v233 offset:2048
	ds_read_b128 v[116:119], v233 offset:3072
	ds_read_b128 v[120:123], v234
	ds_read_b128 v[124:127], v234 offset:1024
	ds_read_b128 v[128:131], v234 offset:2048
	ds_read_b128 v[132:135], v234 offset:3072
	s_add_u32 s68, s24, 0xfffc0080
	s_addc_u32 s69, s25, -1
	s_cmp_eq_u32 s74, 12
	s_cselect_b32 s71, s63, s69
	s_cselect_b32 s70, s62, s68
	s_cselect_b32 s69, s61, s73
	s_cselect_b32 s68, s67, s72
	v_lshl_add_u64 v[208:209], s[24:25], 0, v[186:187]
	s_add_i32 m0, s92, 0xc000
	ds_read_b128 v[160:163], v235
	ds_read_b128 v[164:167], v235 offset:1024
	ds_read_b128 v[168:171], v235 offset:2048
	ds_read_b128 v[172:175], v235 offset:3072
	ds_read_b128 v[192:195], v235 offset:4096
	ds_read_b128 v[196:199], v235 offset:5120
	ds_read_b128 v[200:203], v235 offset:6144
	ds_read_b128 v[204:207], v235 offset:7168
	global_load_lds_dwordx4 v[208:209], off
	v_lshl_add_u64 v[208:209], s[24:25], 0, v[184:185]
	s_add_i32 m0, s92, 0xe000
	s_nop 0
	global_load_lds_dwordx4 v[208:209], off
	s_waitcnt vmcnt(8)
	s_waitcnt lgkmcnt(0)
	s_barrier
	s_setprio 1
	s_waitcnt lgkmcnt(0)
	v_mfma_f32_16x16x32_bf16 v[156:159], v[104:107], v[160:163], v[156:159]
	v_mfma_f32_16x16x32_bf16 v[60:63], v[112:115], v[160:163], v[60:63]
	v_mfma_f32_16x16x32_bf16 v[148:151], v[104:107], v[168:171], v[148:151]
	v_mfma_f32_16x16x32_bf16 v[52:55], v[112:115], v[168:171], v[52:55]
	v_mfma_f32_16x16x32_bf16 v[140:143], v[104:107], v[192:195], v[140:143]
	v_mfma_f32_16x16x32_bf16 v[44:47], v[112:115], v[192:195], v[44:47]
	v_mfma_f32_16x16x32_bf16 v[100:103], v[104:107], v[200:203], v[100:103]
	v_mfma_f32_16x16x32_bf16 v[36:39], v[112:115], v[200:203], v[36:39]
	v_mfma_f32_16x16x32_bf16 v[156:159], v[108:111], v[164:167], v[156:159]
	v_mfma_f32_16x16x32_bf16 v[60:63], v[116:119], v[164:167], v[60:63]
	v_mfma_f32_16x16x32_bf16 v[148:151], v[108:111], v[172:175], v[148:151]
	v_mfma_f32_16x16x32_bf16 v[52:55], v[116:119], v[172:175], v[52:55]
	v_mfma_f32_16x16x32_bf16 v[140:143], v[108:111], v[196:199], v[140:143]
	v_mfma_f32_16x16x32_bf16 v[44:47], v[116:119], v[196:199], v[44:47]
	v_mfma_f32_16x16x32_bf16 v[100:103], v[108:111], v[204:207], v[100:103]
	v_mfma_f32_16x16x32_bf16 v[36:39], v[116:119], v[204:207], v[36:39]
	s_setprio 0
	s_setprio 1
	v_mfma_f32_16x16x32_bf16 v[152:155], v[120:123], v[160:163], v[152:155]
	v_mfma_f32_16x16x32_bf16 v[56:59], v[128:131], v[160:163], v[56:59]
	v_mfma_f32_16x16x32_bf16 v[144:147], v[120:123], v[168:171], v[144:147]
	v_mfma_f32_16x16x32_bf16 v[48:51], v[128:131], v[168:171], v[48:51]
	v_mfma_f32_16x16x32_bf16 v[136:139], v[120:123], v[192:195], v[136:139]
	v_mfma_f32_16x16x32_bf16 v[40:43], v[128:131], v[192:195], v[40:43]
	v_mfma_f32_16x16x32_bf16 v[96:99], v[120:123], v[200:203], v[96:99]
	v_mfma_f32_16x16x32_bf16 v[32:35], v[128:131], v[200:203], v[32:35]
	v_mfma_f32_16x16x32_bf16 v[152:155], v[124:127], v[164:167], v[152:155]
	v_mfma_f32_16x16x32_bf16 v[56:59], v[132:135], v[164:167], v[56:59]
	v_mfma_f32_16x16x32_bf16 v[144:147], v[124:127], v[172:175], v[144:147]
	v_mfma_f32_16x16x32_bf16 v[48:51], v[132:135], v[172:175], v[48:51]
	v_mfma_f32_16x16x32_bf16 v[136:139], v[124:127], v[196:199], v[136:139]
	v_mfma_f32_16x16x32_bf16 v[40:43], v[132:135], v[196:199], v[40:43]
	v_mfma_f32_16x16x32_bf16 v[96:99], v[124:127], v[204:207], v[96:99]
	v_mfma_f32_16x16x32_bf16 v[32:35], v[132:135], v[204:207], v[32:35]
	s_setprio 0
	s_barrier
	s_add_i32 s75, s33, s91
	v_lshl_add_u64 v[208:209], s[68:69], 0, v[178:179]
	s_mov_b32 m0, s75
	ds_read_b128 v[160:163], v235 offset:16384
	ds_read_b128 v[164:167], v235 offset:17408
	ds_read_b128 v[168:171], v235 offset:18432
	ds_read_b128 v[172:175], v235 offset:19456
	ds_read_b128 v[192:195], v235 offset:20480
	ds_read_b128 v[196:199], v235 offset:21504
	ds_read_b128 v[200:203], v235 offset:22528
	ds_read_b128 v[204:207], v235 offset:23552
	global_load_lds_dwordx4 v[208:209], off
	s_add_i32 m0, s75, 0x2000
	s_add_u32 s76, s68, 0x40000
	v_lshl_add_u64 v[210:211], s[68:69], 0, v[182:183]
	s_addc_u32 s77, s69, 0
	s_add_i32 s75, s0, s91
	global_load_lds_dwordx4 v[210:211], off
	v_lshl_add_u64 v[212:213], s[76:77], 0, v[178:179]
	s_mov_b32 m0, s75
	v_lshl_add_u64 v[214:215], s[70:71], 0, v[180:181]
	global_load_lds_dwordx4 v[212:213], off
	v_lshl_add_u64 v[212:213], s[76:77], 0, v[182:183]
	s_add_i32 m0, s75, 0x2000
	s_nop 0
	global_load_lds_dwordx4 v[212:213], off
	v_lshl_add_u64 v[212:213], s[70:71], 0, v[176:177]
	s_mov_b32 m0, s92
	s_nop 0
	global_load_lds_dwordx4 v[212:213], off
	s_mov_b32 m0, s93
	s_nop 0
	global_load_lds_dwordx4 v[214:215], off
	s_waitcnt vmcnt(8)
	s_waitcnt lgkmcnt(0)
	s_barrier
	s_setprio 1
	s_waitcnt lgkmcnt(0)
	v_mfma_f32_16x16x32_bf16 v[92:95], v[104:107], v[160:163], v[92:95]
	v_mfma_f32_16x16x32_bf16 v[28:31], v[112:115], v[160:163], v[28:31]
	v_mfma_f32_16x16x32_bf16 v[84:87], v[104:107], v[168:171], v[84:87]
	v_mfma_f32_16x16x32_bf16 v[20:23], v[112:115], v[168:171], v[20:23]
	v_mfma_f32_16x16x32_bf16 v[76:79], v[104:107], v[192:195], v[76:79]
	v_mfma_f32_16x16x32_bf16 v[12:15], v[112:115], v[192:195], v[12:15]
	v_mfma_f32_16x16x32_bf16 v[68:71], v[104:107], v[200:203], v[68:71]
	v_mfma_f32_16x16x32_bf16 v[4:7], v[112:115], v[200:203], v[4:7]
	v_mfma_f32_16x16x32_bf16 v[92:95], v[108:111], v[164:167], v[92:95]
	v_mfma_f32_16x16x32_bf16 v[28:31], v[116:119], v[164:167], v[28:31]
	v_mfma_f32_16x16x32_bf16 v[84:87], v[108:111], v[172:175], v[84:87]
	v_mfma_f32_16x16x32_bf16 v[20:23], v[116:119], v[172:175], v[20:23]
	v_mfma_f32_16x16x32_bf16 v[76:79], v[108:111], v[196:199], v[76:79]
	v_mfma_f32_16x16x32_bf16 v[12:15], v[116:119], v[196:199], v[12:15]
	v_mfma_f32_16x16x32_bf16 v[68:71], v[108:111], v[204:207], v[68:71]
	v_mfma_f32_16x16x32_bf16 v[4:7], v[116:119], v[204:207], v[4:7]
	s_setprio 0
	s_setprio 1
	v_mfma_f32_16x16x32_bf16 v[88:91], v[120:123], v[160:163], v[88:91]
	v_mfma_f32_16x16x32_bf16 v[24:27], v[128:131], v[160:163], v[24:27]
	v_mfma_f32_16x16x32_bf16 v[80:83], v[120:123], v[168:171], v[80:83]
	v_mfma_f32_16x16x32_bf16 v[16:19], v[128:131], v[168:171], v[16:19]
	v_mfma_f32_16x16x32_bf16 v[72:75], v[120:123], v[192:195], v[72:75]
	v_mfma_f32_16x16x32_bf16 v[8:11], v[128:131], v[192:195], v[8:11]
	v_mfma_f32_16x16x32_bf16 v[64:67], v[120:123], v[200:203], v[64:67]
	v_mfma_f32_16x16x32_bf16 v[0:3], v[128:131], v[200:203], v[0:3]
	v_mfma_f32_16x16x32_bf16 v[88:91], v[124:127], v[164:167], v[88:91]
	v_mfma_f32_16x16x32_bf16 v[24:27], v[132:135], v[164:167], v[24:27]
	v_mfma_f32_16x16x32_bf16 v[80:83], v[124:127], v[172:175], v[80:83]
	v_mfma_f32_16x16x32_bf16 v[16:19], v[132:135], v[172:175], v[16:19]
	v_mfma_f32_16x16x32_bf16 v[72:75], v[124:127], v[196:199], v[72:75]
	v_mfma_f32_16x16x32_bf16 v[8:11], v[132:135], v[196:199], v[8:11]
	v_mfma_f32_16x16x32_bf16 v[64:67], v[124:127], v[204:207], v[64:67]
	v_mfma_f32_16x16x32_bf16 v[0:3], v[132:135], v[204:207], v[0:3]
	s_setprio 0
	s_barrier
	s_add_i32 s75, 0, 0x18000
	s_add_i32 s76, 0, 0x1c000
	v_add_u32_e32 v116, s75, v221
	v_add_u32_e32 v132, s76, v221
	ds_read_b128 v[104:107], v116
	ds_read_b128 v[108:111], v116 offset:1024
	ds_read_b128 v[112:115], v116 offset:2048
	ds_read_b128 v[116:119], v116 offset:3072
	ds_read_b128 v[120:123], v132
	ds_read_b128 v[124:127], v132 offset:1024
	ds_read_b128 v[128:131], v132 offset:2048
	ds_read_b128 v[132:135], v132 offset:3072
	s_add_u32 s70, s70, 0x40000
	s_addc_u32 s71, s71, 0
	s_mov_b32 m0, s94
	v_lshl_add_u64 v[216:217], s[70:71], 0, v[176:177]
	ds_read_b128 v[160:163], v235 offset:32768
	ds_read_b128 v[164:167], v235 offset:33792
	ds_read_b128 v[168:171], v235 offset:34816
	ds_read_b128 v[172:175], v235 offset:35840
	ds_read_b128 v[192:195], v235 offset:36864
	ds_read_b128 v[196:199], v235 offset:37888
	ds_read_b128 v[200:203], v235 offset:38912
	ds_read_b128 v[204:207], v235 offset:39936
	global_load_lds_dwordx4 v[216:217], off
	v_lshl_add_u64 v[216:217], s[70:71], 0, v[180:181]
	s_mov_b32 m0, s95
	s_nop 0
	global_load_lds_dwordx4 v[216:217], off
	s_waitcnt vmcnt(8)
	s_waitcnt lgkmcnt(0)
	s_barrier
	s_setprio 1
	s_waitcnt lgkmcnt(0)
	v_mfma_f32_16x16x32_bf16 v[156:159], v[104:107], v[160:163], v[156:159]
	v_mfma_f32_16x16x32_bf16 v[60:63], v[112:115], v[160:163], v[60:63]
	v_mfma_f32_16x16x32_bf16 v[148:151], v[104:107], v[168:171], v[148:151]
	v_mfma_f32_16x16x32_bf16 v[52:55], v[112:115], v[168:171], v[52:55]
	v_mfma_f32_16x16x32_bf16 v[140:143], v[104:107], v[192:195], v[140:143]
	v_mfma_f32_16x16x32_bf16 v[44:47], v[112:115], v[192:195], v[44:47]
	v_mfma_f32_16x16x32_bf16 v[100:103], v[104:107], v[200:203], v[100:103]
	v_mfma_f32_16x16x32_bf16 v[36:39], v[112:115], v[200:203], v[36:39]
	v_mfma_f32_16x16x32_bf16 v[156:159], v[108:111], v[164:167], v[156:159]
	v_mfma_f32_16x16x32_bf16 v[60:63], v[116:119], v[164:167], v[60:63]
	v_mfma_f32_16x16x32_bf16 v[148:151], v[108:111], v[172:175], v[148:151]
	v_mfma_f32_16x16x32_bf16 v[52:55], v[116:119], v[172:175], v[52:55]
	v_mfma_f32_16x16x32_bf16 v[140:143], v[108:111], v[196:199], v[140:143]
	v_mfma_f32_16x16x32_bf16 v[44:47], v[116:119], v[196:199], v[44:47]
	v_mfma_f32_16x16x32_bf16 v[100:103], v[108:111], v[204:207], v[100:103]
	v_mfma_f32_16x16x32_bf16 v[36:39], v[116:119], v[204:207], v[36:39]
	s_setprio 0
	s_setprio 1
	v_mfma_f32_16x16x32_bf16 v[152:155], v[120:123], v[160:163], v[152:155]
	v_mfma_f32_16x16x32_bf16 v[56:59], v[128:131], v[160:163], v[56:59]
	v_mfma_f32_16x16x32_bf16 v[144:147], v[120:123], v[168:171], v[144:147]
	v_mfma_f32_16x16x32_bf16 v[48:51], v[128:131], v[168:171], v[48:51]
	v_mfma_f32_16x16x32_bf16 v[136:139], v[120:123], v[192:195], v[136:139]
	v_mfma_f32_16x16x32_bf16 v[40:43], v[128:131], v[192:195], v[40:43]
	v_mfma_f32_16x16x32_bf16 v[96:99], v[120:123], v[200:203], v[96:99]
	v_mfma_f32_16x16x32_bf16 v[32:35], v[128:131], v[200:203], v[32:35]
	v_mfma_f32_16x16x32_bf16 v[152:155], v[124:127], v[164:167], v[152:155]
	v_mfma_f32_16x16x32_bf16 v[56:59], v[132:135], v[164:167], v[56:59]
	v_mfma_f32_16x16x32_bf16 v[144:147], v[124:127], v[172:175], v[144:147]
	v_mfma_f32_16x16x32_bf16 v[48:51], v[132:135], v[172:175], v[48:51]
	v_mfma_f32_16x16x32_bf16 v[136:139], v[124:127], v[196:199], v[136:139]
	v_mfma_f32_16x16x32_bf16 v[40:43], v[132:135], v[196:199], v[40:43]
	v_mfma_f32_16x16x32_bf16 v[96:99], v[124:127], v[204:207], v[96:99]
	v_mfma_f32_16x16x32_bf16 v[32:35], v[132:135], v[204:207], v[32:35]
	s_setprio 0
	s_barrier
	s_add_i32 s70, s75, s91
	v_lshl_add_u64 v[208:209], v[208:209], 0, s[42:43]
	s_mov_b32 m0, s70
	ds_read_b128 v[160:163], v235 offset:49152
	ds_read_b128 v[164:167], v235 offset:50176
	ds_read_b128 v[168:171], v235 offset:51200
	ds_read_b128 v[172:175], v235 offset:52224
	ds_read_b128 v[192:195], v235 offset:53248
	ds_read_b128 v[196:199], v235 offset:54272
	ds_read_b128 v[200:203], v235 offset:55296
	ds_read_b128 v[204:207], v235 offset:56320
	global_load_lds_dwordx4 v[208:209], off
	s_add_i32 m0, s70, 0x2000
	s_add_u32 s68, s68, 0x40080
	v_lshl_add_u64 v[208:209], v[210:211], 0, s[42:43]
	s_addc_u32 s69, s69, 0
	s_add_i32 s70, s76, s91
	global_load_lds_dwordx4 v[208:209], off
	v_lshl_add_u64 v[208:209], s[68:69], 0, v[178:179]
	s_mov_b32 m0, s70
	s_nop 0
	global_load_lds_dwordx4 v[208:209], off
	v_lshl_add_u64 v[208:209], s[68:69], 0, v[182:183]
	s_add_i32 m0, s70, 0x2000
	s_nop 0
	global_load_lds_dwordx4 v[208:209], off
	v_lshl_add_u64 v[208:209], v[212:213], 0, s[42:43]
	s_mov_b32 m0, s5
	s_nop 0
	global_load_lds_dwordx4 v[208:209], off
	v_lshl_add_u64 v[208:209], v[214:215], 0, s[42:43]
	s_mov_b32 m0, s96
	s_nop 0
	global_load_lds_dwordx4 v[208:209], off
	s_waitcnt vmcnt(8)
	s_waitcnt lgkmcnt(0)
	s_barrier
	s_setprio 1
	s_waitcnt lgkmcnt(0)
	v_mfma_f32_16x16x32_bf16 v[92:95], v[104:107], v[160:163], v[92:95]
	v_mfma_f32_16x16x32_bf16 v[28:31], v[112:115], v[160:163], v[28:31]
	v_mfma_f32_16x16x32_bf16 v[84:87], v[104:107], v[168:171], v[84:87]
	v_mfma_f32_16x16x32_bf16 v[20:23], v[112:115], v[168:171], v[20:23]
	v_mfma_f32_16x16x32_bf16 v[76:79], v[104:107], v[192:195], v[76:79]
	v_mfma_f32_16x16x32_bf16 v[12:15], v[112:115], v[192:195], v[12:15]
	v_mfma_f32_16x16x32_bf16 v[68:71], v[104:107], v[200:203], v[68:71]
	v_mfma_f32_16x16x32_bf16 v[4:7], v[112:115], v[200:203], v[4:7]
	v_mfma_f32_16x16x32_bf16 v[92:95], v[108:111], v[164:167], v[92:95]
	v_mfma_f32_16x16x32_bf16 v[28:31], v[116:119], v[164:167], v[28:31]
	v_mfma_f32_16x16x32_bf16 v[84:87], v[108:111], v[172:175], v[84:87]
	v_mfma_f32_16x16x32_bf16 v[20:23], v[116:119], v[172:175], v[20:23]
	v_mfma_f32_16x16x32_bf16 v[76:79], v[108:111], v[196:199], v[76:79]
	v_mfma_f32_16x16x32_bf16 v[12:15], v[116:119], v[196:199], v[12:15]
	v_mfma_f32_16x16x32_bf16 v[68:71], v[108:111], v[204:207], v[68:71]
	v_mfma_f32_16x16x32_bf16 v[4:7], v[116:119], v[204:207], v[4:7]
	s_setprio 0
	s_setprio 1
	v_mfma_f32_16x16x32_bf16 v[88:91], v[120:123], v[160:163], v[88:91]
	v_mfma_f32_16x16x32_bf16 v[24:27], v[128:131], v[160:163], v[24:27]
	v_mfma_f32_16x16x32_bf16 v[80:83], v[120:123], v[168:171], v[80:83]
	v_mfma_f32_16x16x32_bf16 v[16:19], v[128:131], v[168:171], v[16:19]
	v_mfma_f32_16x16x32_bf16 v[72:75], v[120:123], v[192:195], v[72:75]
	v_mfma_f32_16x16x32_bf16 v[8:11], v[128:131], v[192:195], v[8:11]
	v_mfma_f32_16x16x32_bf16 v[64:67], v[120:123], v[200:203], v[64:67]
	v_mfma_f32_16x16x32_bf16 v[0:3], v[128:131], v[200:203], v[0:3]
	v_mfma_f32_16x16x32_bf16 v[88:91], v[124:127], v[164:167], v[88:91]
	v_mfma_f32_16x16x32_bf16 v[24:27], v[132:135], v[164:167], v[24:27]
	v_mfma_f32_16x16x32_bf16 v[80:83], v[124:127], v[172:175], v[80:83]
	v_mfma_f32_16x16x32_bf16 v[16:19], v[132:135], v[172:175], v[16:19]
	v_mfma_f32_16x16x32_bf16 v[72:75], v[124:127], v[196:199], v[72:75]
	v_mfma_f32_16x16x32_bf16 v[8:11], v[132:135], v[196:199], v[8:11]
	v_mfma_f32_16x16x32_bf16 v[64:67], v[124:127], v[204:207], v[64:67]
	v_mfma_f32_16x16x32_bf16 v[0:3], v[132:135], v[204:207], v[0:3]
	s_setprio 0
	s_add_i32 s74, s74, 2
	s_add_u32 s72, s72, 0x100
	s_addc_u32 s73, s73, 0
	s_add_u32 s24, s24, 0x100
	s_addc_u32 s25, s25, 0
	s_cmp_gt_u32 s74, 13
	s_barrier
	s_cbranch_scc0 .LBB0_4039
	s_and_b64 vcc, exec, s[44:45]
	s_cbranch_vccz .LBB0_4042
	s_barrier
